# merged K-loops: first 4 MFMAs of each block issued before the block's barrier at low priority
# speedup vs baseline: 1.0129x; 1.0129x over previous
.Lrs_i1_pre:
	s_add_u32 s1, s28, 0xfffc0080
	s_addc_u32 s22, s29, -1
	s_add_i32 s23, 0, 0x10000
	v_add_u32_e32 v142, s23, v195
	ds_read_b128 v[130:133], v142
	ds_read_b128 v[134:137], v142 offset:1024
	ds_read_b128 v[138:141], v142 offset:2048
	ds_read_b128 v[142:145], v142 offset:3072
	s_cmp_eq_u32 s69, 12
	s_cselect_b32 s57, s21, s22
	s_cselect_b32 s56, s34, s1
	s_cselect_b32 s31, s47, s68
	s_cselect_b32 s30, s49, s67
	v_lshl_add_u64 v[176:177], s[28:29], 0, v[178:179]
	s_add_i32 m0, s59, 0xc000
	ds_read_b128 v[146:149], v197
	ds_read_b128 v[150:153], v197 offset:1024
	ds_read_b128 v[182:185], v197 offset:2048
	ds_read_b128 v[186:189], v197 offset:3072
	ds_read_b128 v[190:193], v197 offset:4096
	ds_read_b128 v[198:201], v197 offset:5120
	ds_read_b128 v[202:205], v197 offset:6144
	ds_read_b128 v[206:209], v197 offset:7168
	global_load_lds_dwordx4 v[176:177], off
	v_lshl_add_u64 v[176:177], s[28:29], 0, v[180:181]
	s_add_i32 m0, s59, 0xe000
	s_nop 0
	global_load_lds_dwordx4 v[176:177], off
	s_add_i32 s1, 0, 0x14000
	v_add_u32_e32 v168, s1, v195
	ds_read_b128 v[216:219], v168
	ds_read_b128 v[230:233], v168 offset:1024
	ds_read_b128 v[234:237], v168 offset:2048
	ds_read_b128 v[238:241], v168 offset:3072
	s_waitcnt vmcnt(8)
	s_waitcnt lgkmcnt(0)
	v_mfma_f32_16x16x32_bf16 v[126:129], v[130:133], v[146:149], 0
	v_mfma_f32_16x16x32_bf16 v[122:125], v[138:141], v[146:149], 0
	v_mfma_f32_16x16x32_bf16 v[110:113], v[130:133], v[182:185], 0
	v_mfma_f32_16x16x32_bf16 v[106:109], v[138:141], v[182:185], 0
	s_barrier
	s_setprio 1
	v_mfma_f32_16x16x32_bf16 v[94:97], v[130:133], v[190:193], 0
	v_mfma_f32_16x16x32_bf16 v[90:93], v[138:141], v[190:193], 0
	v_mfma_f32_16x16x32_bf16 v[78:81], v[130:133], v[202:205], 0
	v_mfma_f32_16x16x32_bf16 v[74:77], v[138:141], v[202:205], 0
	v_mfma_f32_16x16x32_bf16 v[126:129], v[134:137], v[150:153], v[126:129]
	v_mfma_f32_16x16x32_bf16 v[122:125], v[142:145], v[150:153], v[122:125]
	v_mfma_f32_16x16x32_bf16 v[110:113], v[134:137], v[186:189], v[110:113]
	v_mfma_f32_16x16x32_bf16 v[106:109], v[142:145], v[186:189], v[106:109]
	v_mfma_f32_16x16x32_bf16 v[94:97], v[134:137], v[198:201], v[94:97]
	v_mfma_f32_16x16x32_bf16 v[90:93], v[142:145], v[198:201], v[90:93]
	v_mfma_f32_16x16x32_bf16 v[78:81], v[134:137], v[206:209], v[78:81]
	v_mfma_f32_16x16x32_bf16 v[74:77], v[142:145], v[206:209], v[74:77]
	v_mfma_f32_16x16x32_bf16 v[118:121], v[216:219], v[146:149], 0
	v_mfma_f32_16x16x32_bf16 v[114:117], v[234:237], v[146:149], 0
	v_mfma_f32_16x16x32_bf16 v[102:105], v[216:219], v[182:185], 0
	v_mfma_f32_16x16x32_bf16 v[98:101], v[234:237], v[182:185], 0
	v_mfma_f32_16x16x32_bf16 v[86:89], v[216:219], v[190:193], 0
	v_mfma_f32_16x16x32_bf16 v[82:85], v[234:237], v[190:193], 0
	v_mfma_f32_16x16x32_bf16 v[70:73], v[216:219], v[202:205], 0
	v_mfma_f32_16x16x32_bf16 v[66:69], v[234:237], v[202:205], 0
	v_mfma_f32_16x16x32_bf16 v[118:121], v[230:233], v[150:153], v[118:121]
	v_mfma_f32_16x16x32_bf16 v[114:117], v[238:241], v[150:153], v[114:117]
	v_mfma_f32_16x16x32_bf16 v[102:105], v[230:233], v[186:189], v[102:105]
	v_mfma_f32_16x16x32_bf16 v[98:101], v[238:241], v[186:189], v[98:101]
	v_mfma_f32_16x16x32_bf16 v[86:89], v[230:233], v[198:201], v[86:89]
	v_mfma_f32_16x16x32_bf16 v[82:85], v[238:241], v[198:201], v[82:85]
	v_mfma_f32_16x16x32_bf16 v[70:73], v[230:233], v[206:209], v[70:73]
	v_mfma_f32_16x16x32_bf16 v[66:69], v[238:241], v[206:209], v[66:69]
	s_setprio 0
	s_barrier
	ds_read_b128 v[146:149], v197 offset:16384
	ds_read_b128 v[150:153], v197 offset:17408
	ds_read_b128 v[182:185], v197 offset:18432
	ds_read_b128 v[186:189], v197 offset:19456
	ds_read_b128 v[190:193], v197 offset:20480
	ds_read_b128 v[198:201], v197 offset:21504
	ds_read_b128 v[202:205], v197 offset:22528
	ds_read_b128 v[206:209], v197 offset:23552
	s_add_i32 s22, s23, s58
	v_lshl_add_u64 v[176:177], s[30:31], 0, v[0:1]
	s_mov_b32 m0, s22
	s_nop 0
	global_load_lds_dwordx4 v[176:177], off
	v_lshl_add_u64 v[220:221], s[30:31], 0, v[154:155]
	s_add_i32 m0, s22, 0x2000
	s_nop 0
	global_load_lds_dwordx4 v[220:221], off
	s_mov_b32 m0, s59
	v_lshl_add_u64 v[242:243], s[56:57], 0, v[158:159]
	global_load_lds_dwordx4 v[242:243], off
	v_lshl_add_u64 v[244:245], s[56:57], 0, v[156:157]
	s_mov_b32 m0, s60
	s_nop 0
	global_load_lds_dwordx4 v[244:245], off
	s_add_u32 s22, s30, 0x40000
	s_addc_u32 s23, s31, 0
	s_add_i32 s1, s1, s58
	s_mov_b32 m0, s1
	s_nop 0
	global_load_lds_dwordx4 v0, s[22:23]
	s_add_i32 m0, s1, 0x2000
	s_nop 0
	global_load_lds_dwordx4 v154, s[22:23]
	s_waitcnt vmcnt(8)
	s_waitcnt lgkmcnt(0)
	v_mfma_f32_16x16x32_bf16 v[62:65], v[130:133], v[146:149], 0
	v_mfma_f32_16x16x32_bf16 v[58:61], v[138:141], v[146:149], 0
	v_mfma_f32_16x16x32_bf16 v[46:49], v[130:133], v[182:185], 0
	v_mfma_f32_16x16x32_bf16 v[42:45], v[138:141], v[182:185], 0
	s_barrier
	s_setprio 1
	v_mfma_f32_16x16x32_bf16 v[30:33], v[130:133], v[190:193], 0
	v_mfma_f32_16x16x32_bf16 v[26:29], v[138:141], v[190:193], 0
	v_mfma_f32_16x16x32_bf16 v[14:17], v[130:133], v[202:205], 0
	v_mfma_f32_16x16x32_bf16 v[10:13], v[138:141], v[202:205], 0
	v_mfma_f32_16x16x32_bf16 v[62:65], v[134:137], v[150:153], v[62:65]
	v_mfma_f32_16x16x32_bf16 v[58:61], v[142:145], v[150:153], v[58:61]
	v_mfma_f32_16x16x32_bf16 v[46:49], v[134:137], v[186:189], v[46:49]
	v_mfma_f32_16x16x32_bf16 v[42:45], v[142:145], v[186:189], v[42:45]
	v_mfma_f32_16x16x32_bf16 v[30:33], v[134:137], v[198:201], v[30:33]
	v_mfma_f32_16x16x32_bf16 v[26:29], v[142:145], v[198:201], v[26:29]
	v_mfma_f32_16x16x32_bf16 v[14:17], v[134:137], v[206:209], v[14:17]
	v_mfma_f32_16x16x32_bf16 v[10:13], v[142:145], v[206:209], v[10:13]
	v_mfma_f32_16x16x32_bf16 v[54:57], v[216:219], v[146:149], 0
	v_mfma_f32_16x16x32_bf16 v[50:53], v[234:237], v[146:149], 0
	v_mfma_f32_16x16x32_bf16 v[38:41], v[216:219], v[182:185], 0
	v_mfma_f32_16x16x32_bf16 v[34:37], v[234:237], v[182:185], 0
	v_mfma_f32_16x16x32_bf16 v[22:25], v[216:219], v[190:193], 0
	v_mfma_f32_16x16x32_bf16 v[18:21], v[234:237], v[190:193], 0
	v_mfma_f32_16x16x32_bf16 v[6:9], v[216:219], v[202:205], 0
	v_mfma_f32_16x16x32_bf16 v[2:5], v[234:237], v[202:205], 0
	v_mfma_f32_16x16x32_bf16 v[54:57], v[230:233], v[150:153], v[54:57]
	v_mfma_f32_16x16x32_bf16 v[50:53], v[238:241], v[150:153], v[50:53]
	v_mfma_f32_16x16x32_bf16 v[38:41], v[230:233], v[186:189], v[38:41]
	v_mfma_f32_16x16x32_bf16 v[34:37], v[238:241], v[186:189], v[34:37]
	v_mfma_f32_16x16x32_bf16 v[22:25], v[230:233], v[198:201], v[22:25]
	v_mfma_f32_16x16x32_bf16 v[18:21], v[238:241], v[198:201], v[18:21]
	v_mfma_f32_16x16x32_bf16 v[6:9], v[230:233], v[206:209], v[6:9]
	v_mfma_f32_16x16x32_bf16 v[2:5], v[238:241], v[206:209], v[2:5]
	s_setprio 0
	s_barrier
	s_add_i32 s1, 0, 0x18000
	v_add_u32_e32 v142, s1, v195
	ds_read_b128 v[130:133], v142
	ds_read_b128 v[134:137], v142 offset:1024
	ds_read_b128 v[138:141], v142 offset:2048
	ds_read_b128 v[142:145], v142 offset:3072
	s_add_u32 s22, s56, 0x40000
	s_addc_u32 s23, s57, 0
	s_mov_b32 m0, s61
	v_lshl_add_u64 v[216:217], s[22:23], 0, v[158:159]
	ds_read_b128 v[146:149], v197 offset:32768
	ds_read_b128 v[150:153], v197 offset:33792
	ds_read_b128 v[182:185], v197 offset:34816
	ds_read_b128 v[186:189], v197 offset:35840
	ds_read_b128 v[190:193], v197 offset:36864
	ds_read_b128 v[198:201], v197 offset:37888
	ds_read_b128 v[202:205], v197 offset:38912
	ds_read_b128 v[206:209], v197 offset:39936
	global_load_lds_dwordx4 v[216:217], off
	v_lshl_add_u64 v[216:217], s[22:23], 0, v[156:157]
	s_mov_b32 m0, s62
	s_nop 0
	global_load_lds_dwordx4 v[216:217], off
	s_add_i32 s33, 0, 0x1c000
	v_add_u32_e32 v168, s33, v195
	ds_read_b128 v[216:219], v168
	ds_read_b128 v[230:233], v168 offset:1024
	ds_read_b128 v[234:237], v168 offset:2048
	ds_read_b128 v[238:241], v168 offset:3072
	s_waitcnt vmcnt(8)
	s_waitcnt lgkmcnt(0)
	v_mfma_f32_16x16x32_bf16 v[126:129], v[130:133], v[146:149], v[126:129]
	v_mfma_f32_16x16x32_bf16 v[122:125], v[138:141], v[146:149], v[122:125]
	v_mfma_f32_16x16x32_bf16 v[110:113], v[130:133], v[182:185], v[110:113]
	v_mfma_f32_16x16x32_bf16 v[106:109], v[138:141], v[182:185], v[106:109]
	s_barrier
	s_setprio 1
	v_mfma_f32_16x16x32_bf16 v[94:97], v[130:133], v[190:193], v[94:97]
	v_mfma_f32_16x16x32_bf16 v[90:93], v[138:141], v[190:193], v[90:93]
	v_mfma_f32_16x16x32_bf16 v[78:81], v[130:133], v[202:205], v[78:81]
	v_mfma_f32_16x16x32_bf16 v[74:77], v[138:141], v[202:205], v[74:77]
	v_mfma_f32_16x16x32_bf16 v[126:129], v[134:137], v[150:153], v[126:129]
	v_mfma_f32_16x16x32_bf16 v[122:125], v[142:145], v[150:153], v[122:125]
	v_mfma_f32_16x16x32_bf16 v[110:113], v[134:137], v[186:189], v[110:113]
	v_mfma_f32_16x16x32_bf16 v[106:109], v[142:145], v[186:189], v[106:109]
	v_mfma_f32_16x16x32_bf16 v[94:97], v[134:137], v[198:201], v[94:97]
	v_mfma_f32_16x16x32_bf16 v[90:93], v[142:145], v[198:201], v[90:93]
	v_mfma_f32_16x16x32_bf16 v[78:81], v[134:137], v[206:209], v[78:81]
	v_mfma_f32_16x16x32_bf16 v[74:77], v[142:145], v[206:209], v[74:77]
	v_mfma_f32_16x16x32_bf16 v[118:121], v[216:219], v[146:149], v[118:121]
	v_mfma_f32_16x16x32_bf16 v[114:117], v[234:237], v[146:149], v[114:117]
	v_mfma_f32_16x16x32_bf16 v[102:105], v[216:219], v[182:185], v[102:105]
	v_mfma_f32_16x16x32_bf16 v[98:101], v[234:237], v[182:185], v[98:101]
	v_mfma_f32_16x16x32_bf16 v[86:89], v[216:219], v[190:193], v[86:89]
	v_mfma_f32_16x16x32_bf16 v[82:85], v[234:237], v[190:193], v[82:85]
	v_mfma_f32_16x16x32_bf16 v[70:73], v[216:219], v[202:205], v[70:73]
	v_mfma_f32_16x16x32_bf16 v[66:69], v[234:237], v[202:205], v[66:69]
	v_mfma_f32_16x16x32_bf16 v[118:121], v[230:233], v[150:153], v[118:121]
	v_mfma_f32_16x16x32_bf16 v[114:117], v[238:241], v[150:153], v[114:117]
	v_mfma_f32_16x16x32_bf16 v[102:105], v[230:233], v[186:189], v[102:105]
	v_mfma_f32_16x16x32_bf16 v[98:101], v[238:241], v[186:189], v[98:101]
	v_mfma_f32_16x16x32_bf16 v[86:89], v[230:233], v[198:201], v[86:89]
	v_mfma_f32_16x16x32_bf16 v[82:85], v[238:241], v[198:201], v[82:85]
	v_mfma_f32_16x16x32_bf16 v[70:73], v[230:233], v[206:209], v[70:73]
	v_mfma_f32_16x16x32_bf16 v[66:69], v[238:241], v[206:209], v[66:69]
	s_setprio 0
	s_barrier
	ds_read_b128 v[146:149], v197 offset:49152
	ds_read_b128 v[150:153], v197 offset:50176
	ds_read_b128 v[182:185], v197 offset:51200
	ds_read_b128 v[186:189], v197 offset:52224
	ds_read_b128 v[190:193], v197 offset:53248
	ds_read_b128 v[198:201], v197 offset:54272
	ds_read_b128 v[202:205], v197 offset:55296
	ds_read_b128 v[206:209], v197 offset:56320
	s_add_i32 s1, s1, s58
	v_lshl_add_u64 v[176:177], v[176:177], 0, s[12:13]
	s_mov_b32 m0, s1
	s_nop 0
	global_load_lds_dwordx4 v[176:177], off
	v_lshl_add_u64 v[176:177], v[220:221], 0, s[12:13]
	s_add_i32 m0, s1, 0x2000
	s_nop 0
	global_load_lds_dwordx4 v[176:177], off
	s_mov_b32 m0, s64
	v_lshl_add_u64 v[176:177], v[242:243], 0, s[12:13]
	global_load_lds_dwordx4 v[176:177], off
	v_lshl_add_u64 v[176:177], v[244:245], 0, s[12:13]
	s_mov_b32 m0, s65
	s_nop 0
	global_load_lds_dwordx4 v[176:177], off
	s_add_u32 s22, s30, 0x40080
	s_addc_u32 s23, s31, 0
	s_add_i32 s1, s33, s58
	s_mov_b32 m0, s1
	s_nop 0
	global_load_lds_dwordx4 v0, s[22:23]
	s_add_i32 m0, s1, 0x2000
	s_nop 0
	global_load_lds_dwordx4 v154, s[22:23]
	s_waitcnt vmcnt(8)
	s_waitcnt lgkmcnt(0)
	v_mfma_f32_16x16x32_bf16 v[62:65], v[130:133], v[146:149], v[62:65]
	v_mfma_f32_16x16x32_bf16 v[58:61], v[138:141], v[146:149], v[58:61]
	v_mfma_f32_16x16x32_bf16 v[46:49], v[130:133], v[182:185], v[46:49]
	v_mfma_f32_16x16x32_bf16 v[42:45], v[138:141], v[182:185], v[42:45]
	s_barrier
	s_setprio 1
	v_mfma_f32_16x16x32_bf16 v[30:33], v[130:133], v[190:193], v[30:33]
	v_mfma_f32_16x16x32_bf16 v[26:29], v[138:141], v[190:193], v[26:29]
	v_mfma_f32_16x16x32_bf16 v[14:17], v[130:133], v[202:205], v[14:17]
	v_mfma_f32_16x16x32_bf16 v[10:13], v[138:141], v[202:205], v[10:13]
	v_mfma_f32_16x16x32_bf16 v[62:65], v[134:137], v[150:153], v[62:65]
	v_mfma_f32_16x16x32_bf16 v[58:61], v[142:145], v[150:153], v[58:61]
	v_mfma_f32_16x16x32_bf16 v[46:49], v[134:137], v[186:189], v[46:49]
	v_mfma_f32_16x16x32_bf16 v[42:45], v[142:145], v[186:189], v[42:45]
	v_mfma_f32_16x16x32_bf16 v[30:33], v[134:137], v[198:201], v[30:33]
	v_mfma_f32_16x16x32_bf16 v[26:29], v[142:145], v[198:201], v[26:29]
	v_mfma_f32_16x16x32_bf16 v[14:17], v[134:137], v[206:209], v[14:17]
	v_mfma_f32_16x16x32_bf16 v[10:13], v[142:145], v[206:209], v[10:13]
	v_mfma_f32_16x16x32_bf16 v[54:57], v[216:219], v[146:149], v[54:57]
	v_mfma_f32_16x16x32_bf16 v[50:53], v[234:237], v[146:149], v[50:53]
	v_mfma_f32_16x16x32_bf16 v[38:41], v[216:219], v[182:185], v[38:41]
	v_mfma_f32_16x16x32_bf16 v[34:37], v[234:237], v[182:185], v[34:37]
	v_mfma_f32_16x16x32_bf16 v[22:25], v[216:219], v[190:193], v[22:25]
	v_mfma_f32_16x16x32_bf16 v[18:21], v[234:237], v[190:193], v[18:21]
	v_mfma_f32_16x16x32_bf16 v[6:9], v[216:219], v[202:205], v[6:9]
	v_mfma_f32_16x16x32_bf16 v[2:5], v[234:237], v[202:205], v[2:5]
	v_mfma_f32_16x16x32_bf16 v[54:57], v[230:233], v[150:153], v[54:57]
	v_mfma_f32_16x16x32_bf16 v[50:53], v[238:241], v[150:153], v[50:53]
	v_mfma_f32_16x16x32_bf16 v[38:41], v[230:233], v[186:189], v[38:41]
	v_mfma_f32_16x16x32_bf16 v[34:37], v[238:241], v[186:189], v[34:37]
	v_mfma_f32_16x16x32_bf16 v[22:25], v[230:233], v[198:201], v[22:25]
	v_mfma_f32_16x16x32_bf16 v[18:21], v[238:241], v[198:201], v[18:21]
	v_mfma_f32_16x16x32_bf16 v[6:9], v[230:233], v[206:209], v[6:9]
	v_mfma_f32_16x16x32_bf16 v[2:5], v[238:241], v[206:209], v[2:5]
	s_setprio 0
	s_add_i32 s69, s69, 2
	s_add_u32 s28, s28, 0x100
	s_addc_u32 s29, s29, 0
	s_add_u32 s67, s67, 0x100
	s_addc_u32 s68, s68, 0
	s_cmp_gt_u32 s69, 13
	s_barrier
.LBB0_47:
	s_add_u32 s1, s28, 0xfffc0080
	s_addc_u32 s22, s29, -1
	s_add_i32 s23, 0, 0x10000
	v_add_u32_e32 v142, s23, v195
	ds_read_b128 v[130:133], v142
	ds_read_b128 v[134:137], v142 offset:1024
	ds_read_b128 v[138:141], v142 offset:2048
	ds_read_b128 v[142:145], v142 offset:3072
	s_cmp_eq_u32 s69, 12
	s_cselect_b32 s57, s21, s22
	s_cselect_b32 s56, s34, s1
	s_cselect_b32 s31, s47, s68
	s_cselect_b32 s30, s49, s67
	v_lshl_add_u64 v[176:177], s[28:29], 0, v[178:179]
	s_add_i32 m0, s59, 0xc000
	ds_read_b128 v[146:149], v197
	ds_read_b128 v[150:153], v197 offset:1024
	ds_read_b128 v[182:185], v197 offset:2048
	ds_read_b128 v[186:189], v197 offset:3072
	ds_read_b128 v[190:193], v197 offset:4096
	ds_read_b128 v[198:201], v197 offset:5120
	ds_read_b128 v[202:205], v197 offset:6144
	ds_read_b128 v[206:209], v197 offset:7168
	global_load_lds_dwordx4 v[176:177], off
	v_lshl_add_u64 v[176:177], s[28:29], 0, v[180:181]
	s_add_i32 m0, s59, 0xe000
	s_nop 0
	global_load_lds_dwordx4 v[176:177], off
	s_add_i32 s1, 0, 0x14000
	v_add_u32_e32 v168, s1, v195
	ds_read_b128 v[216:219], v168
	ds_read_b128 v[230:233], v168 offset:1024
	ds_read_b128 v[234:237], v168 offset:2048
	ds_read_b128 v[238:241], v168 offset:3072
	s_waitcnt vmcnt(8)
	s_waitcnt lgkmcnt(0)
	v_mfma_f32_16x16x32_bf16 v[126:129], v[130:133], v[146:149], v[126:129]
	v_mfma_f32_16x16x32_bf16 v[122:125], v[138:141], v[146:149], v[122:125]
	v_mfma_f32_16x16x32_bf16 v[110:113], v[130:133], v[182:185], v[110:113]
	v_mfma_f32_16x16x32_bf16 v[106:109], v[138:141], v[182:185], v[106:109]
	s_barrier
	s_setprio 1
	v_mfma_f32_16x16x32_bf16 v[94:97], v[130:133], v[190:193], v[94:97]
	v_mfma_f32_16x16x32_bf16 v[90:93], v[138:141], v[190:193], v[90:93]
	v_mfma_f32_16x16x32_bf16 v[78:81], v[130:133], v[202:205], v[78:81]
	v_mfma_f32_16x16x32_bf16 v[74:77], v[138:141], v[202:205], v[74:77]
	v_mfma_f32_16x16x32_bf16 v[126:129], v[134:137], v[150:153], v[126:129]
	v_mfma_f32_16x16x32_bf16 v[122:125], v[142:145], v[150:153], v[122:125]
	v_mfma_f32_16x16x32_bf16 v[110:113], v[134:137], v[186:189], v[110:113]
	v_mfma_f32_16x16x32_bf16 v[106:109], v[142:145], v[186:189], v[106:109]
	v_mfma_f32_16x16x32_bf16 v[94:97], v[134:137], v[198:201], v[94:97]
	v_mfma_f32_16x16x32_bf16 v[90:93], v[142:145], v[198:201], v[90:93]
	v_mfma_f32_16x16x32_bf16 v[78:81], v[134:137], v[206:209], v[78:81]
	v_mfma_f32_16x16x32_bf16 v[74:77], v[142:145], v[206:209], v[74:77]
	v_mfma_f32_16x16x32_bf16 v[118:121], v[216:219], v[146:149], v[118:121]
	v_mfma_f32_16x16x32_bf16 v[114:117], v[234:237], v[146:149], v[114:117]
	v_mfma_f32_16x16x32_bf16 v[102:105], v[216:219], v[182:185], v[102:105]
	v_mfma_f32_16x16x32_bf16 v[98:101], v[234:237], v[182:185], v[98:101]
	v_mfma_f32_16x16x32_bf16 v[86:89], v[216:219], v[190:193], v[86:89]
	v_mfma_f32_16x16x32_bf16 v[82:85], v[234:237], v[190:193], v[82:85]
	v_mfma_f32_16x16x32_bf16 v[70:73], v[216:219], v[202:205], v[70:73]
	v_mfma_f32_16x16x32_bf16 v[66:69], v[234:237], v[202:205], v[66:69]
	v_mfma_f32_16x16x32_bf16 v[118:121], v[230:233], v[150:153], v[118:121]
	v_mfma_f32_16x16x32_bf16 v[114:117], v[238:241], v[150:153], v[114:117]
	v_mfma_f32_16x16x32_bf16 v[102:105], v[230:233], v[186:189], v[102:105]
	v_mfma_f32_16x16x32_bf16 v[98:101], v[238:241], v[186:189], v[98:101]
	v_mfma_f32_16x16x32_bf16 v[86:89], v[230:233], v[198:201], v[86:89]
	v_mfma_f32_16x16x32_bf16 v[82:85], v[238:241], v[198:201], v[82:85]
	v_mfma_f32_16x16x32_bf16 v[70:73], v[230:233], v[206:209], v[70:73]
	v_mfma_f32_16x16x32_bf16 v[66:69], v[238:241], v[206:209], v[66:69]
	s_setprio 0
	s_barrier
	ds_read_b128 v[146:149], v197 offset:16384
	ds_read_b128 v[150:153], v197 offset:17408
	ds_read_b128 v[182:185], v197 offset:18432
	ds_read_b128 v[186:189], v197 offset:19456
	ds_read_b128 v[190:193], v197 offset:20480
	ds_read_b128 v[198:201], v197 offset:21504
	ds_read_b128 v[202:205], v197 offset:22528
	ds_read_b128 v[206:209], v197 offset:23552
	s_add_i32 s22, s23, s58
	v_lshl_add_u64 v[176:177], s[30:31], 0, v[0:1]
	s_mov_b32 m0, s22
	s_nop 0
	global_load_lds_dwordx4 v[176:177], off
	v_lshl_add_u64 v[220:221], s[30:31], 0, v[154:155]
	s_add_i32 m0, s22, 0x2000
	s_nop 0
	global_load_lds_dwordx4 v[220:221], off
	s_mov_b32 m0, s59
	v_lshl_add_u64 v[242:243], s[56:57], 0, v[158:159]
	global_load_lds_dwordx4 v[242:243], off
	v_lshl_add_u64 v[244:245], s[56:57], 0, v[156:157]
	s_mov_b32 m0, s60
	s_nop 0
	global_load_lds_dwordx4 v[244:245], off
	s_add_u32 s22, s30, 0x40000
	s_addc_u32 s23, s31, 0
	s_add_i32 s1, s1, s58
	s_mov_b32 m0, s1
	s_nop 0
	global_load_lds_dwordx4 v0, s[22:23]
	s_add_i32 m0, s1, 0x2000
	s_nop 0
	global_load_lds_dwordx4 v154, s[22:23]
	s_waitcnt vmcnt(8)
	s_waitcnt lgkmcnt(0)
	v_mfma_f32_16x16x32_bf16 v[62:65], v[130:133], v[146:149], v[62:65]
	v_mfma_f32_16x16x32_bf16 v[58:61], v[138:141], v[146:149], v[58:61]
	v_mfma_f32_16x16x32_bf16 v[46:49], v[130:133], v[182:185], v[46:49]
	v_mfma_f32_16x16x32_bf16 v[42:45], v[138:141], v[182:185], v[42:45]
	s_barrier
	s_setprio 1
	v_mfma_f32_16x16x32_bf16 v[30:33], v[130:133], v[190:193], v[30:33]
	v_mfma_f32_16x16x32_bf16 v[26:29], v[138:141], v[190:193], v[26:29]
	v_mfma_f32_16x16x32_bf16 v[14:17], v[130:133], v[202:205], v[14:17]
	v_mfma_f32_16x16x32_bf16 v[10:13], v[138:141], v[202:205], v[10:13]
	v_mfma_f32_16x16x32_bf16 v[62:65], v[134:137], v[150:153], v[62:65]
	v_mfma_f32_16x16x32_bf16 v[58:61], v[142:145], v[150:153], v[58:61]
	v_mfma_f32_16x16x32_bf16 v[46:49], v[134:137], v[186:189], v[46:49]
	v_mfma_f32_16x16x32_bf16 v[42:45], v[142:145], v[186:189], v[42:45]
	v_mfma_f32_16x16x32_bf16 v[30:33], v[134:137], v[198:201], v[30:33]
	v_mfma_f32_16x16x32_bf16 v[26:29], v[142:145], v[198:201], v[26:29]
	v_mfma_f32_16x16x32_bf16 v[14:17], v[134:137], v[206:209], v[14:17]
	v_mfma_f32_16x16x32_bf16 v[10:13], v[142:145], v[206:209], v[10:13]
	v_mfma_f32_16x16x32_bf16 v[54:57], v[216:219], v[146:149], v[54:57]
	v_mfma_f32_16x16x32_bf16 v[50:53], v[234:237], v[146:149], v[50:53]
	v_mfma_f32_16x16x32_bf16 v[38:41], v[216:219], v[182:185], v[38:41]
	v_mfma_f32_16x16x32_bf16 v[34:37], v[234:237], v[182:185], v[34:37]
	v_mfma_f32_16x16x32_bf16 v[22:25], v[216:219], v[190:193], v[22:25]
	v_mfma_f32_16x16x32_bf16 v[18:21], v[234:237], v[190:193], v[18:21]
	v_mfma_f32_16x16x32_bf16 v[6:9], v[216:219], v[202:205], v[6:9]
	v_mfma_f32_16x16x32_bf16 v[2:5], v[234:237], v[202:205], v[2:5]
	v_mfma_f32_16x16x32_bf16 v[54:57], v[230:233], v[150:153], v[54:57]
	v_mfma_f32_16x16x32_bf16 v[50:53], v[238:241], v[150:153], v[50:53]
	v_mfma_f32_16x16x32_bf16 v[38:41], v[230:233], v[186:189], v[38:41]
	v_mfma_f32_16x16x32_bf16 v[34:37], v[238:241], v[186:189], v[34:37]
	v_mfma_f32_16x16x32_bf16 v[22:25], v[230:233], v[198:201], v[22:25]
	v_mfma_f32_16x16x32_bf16 v[18:21], v[238:241], v[198:201], v[18:21]
	v_mfma_f32_16x16x32_bf16 v[6:9], v[230:233], v[206:209], v[6:9]
	v_mfma_f32_16x16x32_bf16 v[2:5], v[238:241], v[206:209], v[2:5]
	s_setprio 0
	s_barrier
	s_add_i32 s1, 0, 0x18000
	v_add_u32_e32 v142, s1, v195
	ds_read_b128 v[130:133], v142
	ds_read_b128 v[134:137], v142 offset:1024
	ds_read_b128 v[138:141], v142 offset:2048
	ds_read_b128 v[142:145], v142 offset:3072
	s_add_u32 s22, s56, 0x40000
	s_addc_u32 s23, s57, 0
	s_mov_b32 m0, s61
	v_lshl_add_u64 v[216:217], s[22:23], 0, v[158:159]
	ds_read_b128 v[146:149], v197 offset:32768
	ds_read_b128 v[150:153], v197 offset:33792
	ds_read_b128 v[182:185], v197 offset:34816
	ds_read_b128 v[186:189], v197 offset:35840
	ds_read_b128 v[190:193], v197 offset:36864
	ds_read_b128 v[198:201], v197 offset:37888
	ds_read_b128 v[202:205], v197 offset:38912
	ds_read_b128 v[206:209], v197 offset:39936
	global_load_lds_dwordx4 v[216:217], off
	v_lshl_add_u64 v[216:217], s[22:23], 0, v[156:157]
	s_mov_b32 m0, s62
	s_nop 0
	global_load_lds_dwordx4 v[216:217], off
	s_add_i32 s33, 0, 0x1c000
	v_add_u32_e32 v168, s33, v195
	ds_read_b128 v[216:219], v168
	ds_read_b128 v[230:233], v168 offset:1024
	ds_read_b128 v[234:237], v168 offset:2048
	ds_read_b128 v[238:241], v168 offset:3072
	s_waitcnt vmcnt(8)
	s_waitcnt lgkmcnt(0)
	v_mfma_f32_16x16x32_bf16 v[126:129], v[130:133], v[146:149], v[126:129]
	v_mfma_f32_16x16x32_bf16 v[122:125], v[138:141], v[146:149], v[122:125]
	v_mfma_f32_16x16x32_bf16 v[110:113], v[130:133], v[182:185], v[110:113]
	v_mfma_f32_16x16x32_bf16 v[106:109], v[138:141], v[182:185], v[106:109]
	s_barrier
	s_setprio 1
	v_mfma_f32_16x16x32_bf16 v[94:97], v[130:133], v[190:193], v[94:97]
	v_mfma_f32_16x16x32_bf16 v[90:93], v[138:141], v[190:193], v[90:93]
	v_mfma_f32_16x16x32_bf16 v[78:81], v[130:133], v[202:205], v[78:81]
	v_mfma_f32_16x16x32_bf16 v[74:77], v[138:141], v[202:205], v[74:77]
	v_mfma_f32_16x16x32_bf16 v[126:129], v[134:137], v[150:153], v[126:129]
	v_mfma_f32_16x16x32_bf16 v[122:125], v[142:145], v[150:153], v[122:125]
	v_mfma_f32_16x16x32_bf16 v[110:113], v[134:137], v[186:189], v[110:113]
	v_mfma_f32_16x16x32_bf16 v[106:109], v[142:145], v[186:189], v[106:109]
	v_mfma_f32_16x16x32_bf16 v[94:97], v[134:137], v[198:201], v[94:97]
	v_mfma_f32_16x16x32_bf16 v[90:93], v[142:145], v[198:201], v[90:93]
	v_mfma_f32_16x16x32_bf16 v[78:81], v[134:137], v[206:209], v[78:81]
	v_mfma_f32_16x16x32_bf16 v[74:77], v[142:145], v[206:209], v[74:77]
	v_mfma_f32_16x16x32_bf16 v[118:121], v[216:219], v[146:149], v[118:121]
	v_mfma_f32_16x16x32_bf16 v[114:117], v[234:237], v[146:149], v[114:117]
	v_mfma_f32_16x16x32_bf16 v[102:105], v[216:219], v[182:185], v[102:105]
	v_mfma_f32_16x16x32_bf16 v[98:101], v[234:237], v[182:185], v[98:101]
	v_mfma_f32_16x16x32_bf16 v[86:89], v[216:219], v[190:193], v[86:89]
	v_mfma_f32_16x16x32_bf16 v[82:85], v[234:237], v[190:193], v[82:85]
	v_mfma_f32_16x16x32_bf16 v[70:73], v[216:219], v[202:205], v[70:73]
	v_mfma_f32_16x16x32_bf16 v[66:69], v[234:237], v[202:205], v[66:69]
	v_mfma_f32_16x16x32_bf16 v[118:121], v[230:233], v[150:153], v[118:121]
	v_mfma_f32_16x16x32_bf16 v[114:117], v[238:241], v[150:153], v[114:117]
	v_mfma_f32_16x16x32_bf16 v[102:105], v[230:233], v[186:189], v[102:105]
	v_mfma_f32_16x16x32_bf16 v[98:101], v[238:241], v[186:189], v[98:101]
	v_mfma_f32_16x16x32_bf16 v[86:89], v[230:233], v[198:201], v[86:89]
	v_mfma_f32_16x16x32_bf16 v[82:85], v[238:241], v[198:201], v[82:85]
	v_mfma_f32_16x16x32_bf16 v[70:73], v[230:233], v[206:209], v[70:73]
	v_mfma_f32_16x16x32_bf16 v[66:69], v[238:241], v[206:209], v[66:69]
	s_setprio 0
	s_barrier
	ds_read_b128 v[146:149], v197 offset:49152
	ds_read_b128 v[150:153], v197 offset:50176
	ds_read_b128 v[182:185], v197 offset:51200
	ds_read_b128 v[186:189], v197 offset:52224
	ds_read_b128 v[190:193], v197 offset:53248
	ds_read_b128 v[198:201], v197 offset:54272
	ds_read_b128 v[202:205], v197 offset:55296
	ds_read_b128 v[206:209], v197 offset:56320
	s_add_i32 s1, s1, s58
	v_lshl_add_u64 v[176:177], v[176:177], 0, s[12:13]
	s_mov_b32 m0, s1
	s_nop 0
	global_load_lds_dwordx4 v[176:177], off
	v_lshl_add_u64 v[176:177], v[220:221], 0, s[12:13]
	s_add_i32 m0, s1, 0x2000
	s_nop 0
	global_load_lds_dwordx4 v[176:177], off
	s_mov_b32 m0, s64
	v_lshl_add_u64 v[176:177], v[242:243], 0, s[12:13]
	global_load_lds_dwordx4 v[176:177], off
	v_lshl_add_u64 v[176:177], v[244:245], 0, s[12:13]
	s_mov_b32 m0, s65
	s_nop 0
	global_load_lds_dwordx4 v[176:177], off
	s_add_u32 s22, s30, 0x40080
	s_addc_u32 s23, s31, 0
	s_add_i32 s1, s33, s58
	s_mov_b32 m0, s1
	s_nop 0
	global_load_lds_dwordx4 v0, s[22:23]
	s_add_i32 m0, s1, 0x2000
	s_nop 0
	global_load_lds_dwordx4 v154, s[22:23]
	s_waitcnt vmcnt(8)
	s_waitcnt lgkmcnt(0)
	v_mfma_f32_16x16x32_bf16 v[62:65], v[130:133], v[146:149], v[62:65]
	v_mfma_f32_16x16x32_bf16 v[58:61], v[138:141], v[146:149], v[58:61]
	v_mfma_f32_16x16x32_bf16 v[46:49], v[130:133], v[182:185], v[46:49]
	v_mfma_f32_16x16x32_bf16 v[42:45], v[138:141], v[182:185], v[42:45]
	s_barrier
	s_setprio 1
	v_mfma_f32_16x16x32_bf16 v[30:33], v[130:133], v[190:193], v[30:33]
	v_mfma_f32_16x16x32_bf16 v[26:29], v[138:141], v[190:193], v[26:29]
	v_mfma_f32_16x16x32_bf16 v[14:17], v[130:133], v[202:205], v[14:17]
	v_mfma_f32_16x16x32_bf16 v[10:13], v[138:141], v[202:205], v[10:13]
	v_mfma_f32_16x16x32_bf16 v[62:65], v[134:137], v[150:153], v[62:65]
	v_mfma_f32_16x16x32_bf16 v[58:61], v[142:145], v[150:153], v[58:61]
	v_mfma_f32_16x16x32_bf16 v[46:49], v[134:137], v[186:189], v[46:49]
	v_mfma_f32_16x16x32_bf16 v[42:45], v[142:145], v[186:189], v[42:45]
	v_mfma_f32_16x16x32_bf16 v[30:33], v[134:137], v[198:201], v[30:33]
	v_mfma_f32_16x16x32_bf16 v[26:29], v[142:145], v[198:201], v[26:29]
	v_mfma_f32_16x16x32_bf16 v[14:17], v[134:137], v[206:209], v[14:17]
	v_mfma_f32_16x16x32_bf16 v[10:13], v[142:145], v[206:209], v[10:13]
	v_mfma_f32_16x16x32_bf16 v[54:57], v[216:219], v[146:149], v[54:57]
	v_mfma_f32_16x16x32_bf16 v[50:53], v[234:237], v[146:149], v[50:53]
	v_mfma_f32_16x16x32_bf16 v[38:41], v[216:219], v[182:185], v[38:41]
	v_mfma_f32_16x16x32_bf16 v[34:37], v[234:237], v[182:185], v[34:37]
	v_mfma_f32_16x16x32_bf16 v[22:25], v[216:219], v[190:193], v[22:25]
	v_mfma_f32_16x16x32_bf16 v[18:21], v[234:237], v[190:193], v[18:21]
	v_mfma_f32_16x16x32_bf16 v[6:9], v[216:219], v[202:205], v[6:9]
	v_mfma_f32_16x16x32_bf16 v[2:5], v[234:237], v[202:205], v[2:5]
	v_mfma_f32_16x16x32_bf16 v[54:57], v[230:233], v[150:153], v[54:57]
	v_mfma_f32_16x16x32_bf16 v[50:53], v[238:241], v[150:153], v[50:53]
	v_mfma_f32_16x16x32_bf16 v[38:41], v[230:233], v[186:189], v[38:41]
	v_mfma_f32_16x16x32_bf16 v[34:37], v[238:241], v[186:189], v[34:37]
	v_mfma_f32_16x16x32_bf16 v[22:25], v[230:233], v[198:201], v[22:25]
	v_mfma_f32_16x16x32_bf16 v[18:21], v[238:241], v[198:201], v[18:21]
	v_mfma_f32_16x16x32_bf16 v[6:9], v[230:233], v[206:209], v[6:9]
	v_mfma_f32_16x16x32_bf16 v[2:5], v[238:241], v[206:209], v[2:5]
	s_setprio 0
	s_add_i32 s69, s69, 2
	s_add_u32 s28, s28, 0x100
	s_addc_u32 s29, s29, 0
	s_add_u32 s67, s67, 0x100
	s_addc_u32 s68, s68, 0
	s_cmp_gt_u32 s69, 13
	s_barrier
	s_cbranch_scc0 .LBB0_47
	s_cmpk_gt_u32 s0, 0xff
	s_cbranch_scc1 .Lrs_i1_post
	s_barrier

.Lrs_i2_pre:
	s_add_u32 s1, s28, 0xfffc0080
	s_addc_u32 s22, s29, -1
	s_add_i32 s23, 0, 0x10000
	v_add_u32_e32 v142, s23, v201
	ds_read_b128 v[130:133], v142
	ds_read_b128 v[134:137], v142 offset:1024
	ds_read_b128 v[138:141], v142 offset:2048
	ds_read_b128 v[142:145], v142 offset:3072
	s_cmp_eq_u32 s60, 12
	s_cselect_b32 s43, s27, s22
	s_cselect_b32 s42, s56, s1
	s_cselect_b32 s31, s7, s59
	s_cselect_b32 s30, s57, s58
	v_lshl_add_u64 v[176:177], s[28:29], 0, v[178:179]
	s_add_i32 m0, s46, 0xc000
	ds_read_b128 v[146:149], v205
	ds_read_b128 v[150:153], v205 offset:1024
	ds_read_b128 v[182:185], v205 offset:2048
	ds_read_b128 v[186:189], v205 offset:3072
	ds_read_b128 v[190:193], v205 offset:4096
	ds_read_b128 v[194:197], v205 offset:5120
	ds_read_b128 v[206:209], v205 offset:6144
	ds_read_b128 v[216:219], v205 offset:7168
	global_load_lds_dwordx4 v[176:177], off
	v_lshl_add_u64 v[176:177], s[28:29], 0, v[180:181]
	s_add_i32 m0, s46, 0xe000
	s_nop 0
	global_load_lds_dwordx4 v[176:177], off
	s_add_i32 s1, 0, 0x14000
	v_add_u32_e32 v168, s1, v201
	ds_read_b128 v[230:233], v168
	ds_read_b128 v[234:237], v168 offset:1024
	ds_read_b128 v[238:241], v168 offset:2048
	ds_read_b128 v[242:245], v168 offset:3072
	s_waitcnt vmcnt(8)
	s_waitcnt lgkmcnt(0)
	v_mfma_f32_16x16x32_bf16 v[126:129], v[130:133], v[146:149], 0
	v_mfma_f32_16x16x32_bf16 v[118:121], v[138:141], v[146:149], 0
	v_mfma_f32_16x16x32_bf16 v[110:113], v[130:133], v[182:185], 0
	v_mfma_f32_16x16x32_bf16 v[102:105], v[138:141], v[182:185], 0
	s_barrier
	s_setprio 1
	v_mfma_f32_16x16x32_bf16 v[94:97], v[130:133], v[190:193], 0
	v_mfma_f32_16x16x32_bf16 v[86:89], v[138:141], v[190:193], 0
	v_mfma_f32_16x16x32_bf16 v[78:81], v[130:133], v[206:209], 0
	v_mfma_f32_16x16x32_bf16 v[70:73], v[138:141], v[206:209], 0
	v_mfma_f32_16x16x32_bf16 v[126:129], v[134:137], v[150:153], v[126:129]
	v_mfma_f32_16x16x32_bf16 v[118:121], v[142:145], v[150:153], v[118:121]
	v_mfma_f32_16x16x32_bf16 v[110:113], v[134:137], v[186:189], v[110:113]
	v_mfma_f32_16x16x32_bf16 v[102:105], v[142:145], v[186:189], v[102:105]
	v_mfma_f32_16x16x32_bf16 v[94:97], v[134:137], v[194:197], v[94:97]
	v_mfma_f32_16x16x32_bf16 v[86:89], v[142:145], v[194:197], v[86:89]
	v_mfma_f32_16x16x32_bf16 v[78:81], v[134:137], v[216:219], v[78:81]
	v_mfma_f32_16x16x32_bf16 v[70:73], v[142:145], v[216:219], v[70:73]
	v_mfma_f32_16x16x32_bf16 v[122:125], v[230:233], v[146:149], 0
	v_mfma_f32_16x16x32_bf16 v[114:117], v[238:241], v[146:149], 0
	v_mfma_f32_16x16x32_bf16 v[106:109], v[230:233], v[182:185], 0
	v_mfma_f32_16x16x32_bf16 v[98:101], v[238:241], v[182:185], 0
	v_mfma_f32_16x16x32_bf16 v[90:93], v[230:233], v[190:193], 0
	v_mfma_f32_16x16x32_bf16 v[82:85], v[238:241], v[190:193], 0
	v_mfma_f32_16x16x32_bf16 v[74:77], v[230:233], v[206:209], 0
	v_mfma_f32_16x16x32_bf16 v[66:69], v[238:241], v[206:209], 0
	v_mfma_f32_16x16x32_bf16 v[122:125], v[234:237], v[150:153], v[122:125]
	v_mfma_f32_16x16x32_bf16 v[114:117], v[242:245], v[150:153], v[114:117]
	v_mfma_f32_16x16x32_bf16 v[106:109], v[234:237], v[186:189], v[106:109]
	v_mfma_f32_16x16x32_bf16 v[98:101], v[242:245], v[186:189], v[98:101]
	v_mfma_f32_16x16x32_bf16 v[90:93], v[234:237], v[194:197], v[90:93]
	v_mfma_f32_16x16x32_bf16 v[82:85], v[242:245], v[194:197], v[82:85]
	v_mfma_f32_16x16x32_bf16 v[74:77], v[234:237], v[216:219], v[74:77]
	v_mfma_f32_16x16x32_bf16 v[66:69], v[242:245], v[216:219], v[66:69]
	s_setprio 0
	s_barrier
	ds_read_b128 v[146:149], v205 offset:16384
	ds_read_b128 v[150:153], v205 offset:17408
	ds_read_b128 v[182:185], v205 offset:18432
	ds_read_b128 v[186:189], v205 offset:19456
	ds_read_b128 v[190:193], v205 offset:20480
	ds_read_b128 v[194:197], v205 offset:21504
	ds_read_b128 v[206:209], v205 offset:22528
	ds_read_b128 v[216:219], v205 offset:23552
	s_add_i32 s22, s23, s17
	v_lshl_add_u64 v[176:177], s[30:31], 0, v[0:1]
	s_mov_b32 m0, s22
	s_nop 0
	global_load_lds_dwordx4 v[176:177], off
	v_lshl_add_u64 v[202:203], s[30:31], 0, v[154:155]
	s_add_i32 m0, s22, 0x2000
	s_nop 0
	global_load_lds_dwordx4 v[202:203], off
	s_mov_b32 m0, s46
	v_lshl_add_u64 v[220:221], s[42:43], 0, v[158:159]
	global_load_lds_dwordx4 v[220:221], off
	v_lshl_add_u64 v[246:247], s[42:43], 0, v[156:157]
	s_mov_b32 m0, s47
	s_nop 0
	global_load_lds_dwordx4 v[246:247], off
	s_add_u32 s22, s30, 0x40000
	s_addc_u32 s23, s31, 0
	s_add_i32 s1, s1, s17
	s_mov_b32 m0, s1
	s_nop 0
	global_load_lds_dwordx4 v0, s[22:23]
	s_add_i32 m0, s1, 0x2000
	s_nop 0
	global_load_lds_dwordx4 v154, s[22:23]
	s_waitcnt vmcnt(8)
	s_waitcnt lgkmcnt(0)
	v_mfma_f32_16x16x32_bf16 v[62:65], v[130:133], v[146:149], 0
	v_mfma_f32_16x16x32_bf16 v[54:57], v[138:141], v[146:149], 0
	v_mfma_f32_16x16x32_bf16 v[46:49], v[130:133], v[182:185], 0
	v_mfma_f32_16x16x32_bf16 v[38:41], v[138:141], v[182:185], 0
	s_barrier
	s_setprio 1
	v_mfma_f32_16x16x32_bf16 v[30:33], v[130:133], v[190:193], 0
	v_mfma_f32_16x16x32_bf16 v[22:25], v[138:141], v[190:193], 0
	v_mfma_f32_16x16x32_bf16 v[14:17], v[130:133], v[206:209], 0
	v_mfma_f32_16x16x32_bf16 v[6:9], v[138:141], v[206:209], 0
	v_mfma_f32_16x16x32_bf16 v[62:65], v[134:137], v[150:153], v[62:65]
	v_mfma_f32_16x16x32_bf16 v[54:57], v[142:145], v[150:153], v[54:57]
	v_mfma_f32_16x16x32_bf16 v[46:49], v[134:137], v[186:189], v[46:49]
	v_mfma_f32_16x16x32_bf16 v[38:41], v[142:145], v[186:189], v[38:41]
	v_mfma_f32_16x16x32_bf16 v[30:33], v[134:137], v[194:197], v[30:33]
	v_mfma_f32_16x16x32_bf16 v[22:25], v[142:145], v[194:197], v[22:25]
	v_mfma_f32_16x16x32_bf16 v[14:17], v[134:137], v[216:219], v[14:17]
	v_mfma_f32_16x16x32_bf16 v[6:9], v[142:145], v[216:219], v[6:9]
	v_mfma_f32_16x16x32_bf16 v[58:61], v[230:233], v[146:149], 0
	v_mfma_f32_16x16x32_bf16 v[50:53], v[238:241], v[146:149], 0
	v_mfma_f32_16x16x32_bf16 v[42:45], v[230:233], v[182:185], 0
	v_mfma_f32_16x16x32_bf16 v[34:37], v[238:241], v[182:185], 0
	v_mfma_f32_16x16x32_bf16 v[26:29], v[230:233], v[190:193], 0
	v_mfma_f32_16x16x32_bf16 v[18:21], v[238:241], v[190:193], 0
	v_mfma_f32_16x16x32_bf16 v[10:13], v[230:233], v[206:209], 0
	v_mfma_f32_16x16x32_bf16 v[2:5], v[238:241], v[206:209], 0
	v_mfma_f32_16x16x32_bf16 v[58:61], v[234:237], v[150:153], v[58:61]
	v_mfma_f32_16x16x32_bf16 v[50:53], v[242:245], v[150:153], v[50:53]
	v_mfma_f32_16x16x32_bf16 v[42:45], v[234:237], v[186:189], v[42:45]
	v_mfma_f32_16x16x32_bf16 v[34:37], v[242:245], v[186:189], v[34:37]
	v_mfma_f32_16x16x32_bf16 v[26:29], v[234:237], v[194:197], v[26:29]
	v_mfma_f32_16x16x32_bf16 v[18:21], v[242:245], v[194:197], v[18:21]
	v_mfma_f32_16x16x32_bf16 v[10:13], v[234:237], v[216:219], v[10:13]
	v_mfma_f32_16x16x32_bf16 v[2:5], v[242:245], v[216:219], v[2:5]
	s_setprio 0
	s_barrier
	s_add_i32 s1, 0, 0x18000
	v_add_u32_e32 v142, s1, v201
	ds_read_b128 v[130:133], v142
	ds_read_b128 v[134:137], v142 offset:1024
	ds_read_b128 v[138:141], v142 offset:2048
	ds_read_b128 v[142:145], v142 offset:3072
	s_add_u32 s22, s42, 0x40000
	s_addc_u32 s23, s43, 0
	s_mov_b32 m0, s48
	v_lshl_add_u64 v[230:231], s[22:23], 0, v[158:159]
	ds_read_b128 v[146:149], v205 offset:32768
	ds_read_b128 v[150:153], v205 offset:33792
	ds_read_b128 v[182:185], v205 offset:34816
	ds_read_b128 v[186:189], v205 offset:35840
	ds_read_b128 v[190:193], v205 offset:36864
	ds_read_b128 v[194:197], v205 offset:37888
	ds_read_b128 v[206:209], v205 offset:38912
	ds_read_b128 v[216:219], v205 offset:39936
	global_load_lds_dwordx4 v[230:231], off
	v_lshl_add_u64 v[230:231], s[22:23], 0, v[156:157]
	s_mov_b32 m0, s49
	s_nop 0
	global_load_lds_dwordx4 v[230:231], off
	s_add_i32 s33, 0, 0x1c000
	v_add_u32_e32 v168, s33, v201
	ds_read_b128 v[230:233], v168
	ds_read_b128 v[234:237], v168 offset:1024
	ds_read_b128 v[238:241], v168 offset:2048
	ds_read_b128 v[242:245], v168 offset:3072
	s_waitcnt vmcnt(8)
	s_waitcnt lgkmcnt(0)
	v_mfma_f32_16x16x32_bf16 v[126:129], v[130:133], v[146:149], v[126:129]
	v_mfma_f32_16x16x32_bf16 v[118:121], v[138:141], v[146:149], v[118:121]
	v_mfma_f32_16x16x32_bf16 v[110:113], v[130:133], v[182:185], v[110:113]
	v_mfma_f32_16x16x32_bf16 v[102:105], v[138:141], v[182:185], v[102:105]
	s_barrier
	s_setprio 1
	v_mfma_f32_16x16x32_bf16 v[94:97], v[130:133], v[190:193], v[94:97]
	v_mfma_f32_16x16x32_bf16 v[86:89], v[138:141], v[190:193], v[86:89]
	v_mfma_f32_16x16x32_bf16 v[78:81], v[130:133], v[206:209], v[78:81]
	v_mfma_f32_16x16x32_bf16 v[70:73], v[138:141], v[206:209], v[70:73]
	v_mfma_f32_16x16x32_bf16 v[126:129], v[134:137], v[150:153], v[126:129]
	v_mfma_f32_16x16x32_bf16 v[118:121], v[142:145], v[150:153], v[118:121]
	v_mfma_f32_16x16x32_bf16 v[110:113], v[134:137], v[186:189], v[110:113]
	v_mfma_f32_16x16x32_bf16 v[102:105], v[142:145], v[186:189], v[102:105]
	v_mfma_f32_16x16x32_bf16 v[94:97], v[134:137], v[194:197], v[94:97]
	v_mfma_f32_16x16x32_bf16 v[86:89], v[142:145], v[194:197], v[86:89]
	v_mfma_f32_16x16x32_bf16 v[78:81], v[134:137], v[216:219], v[78:81]
	v_mfma_f32_16x16x32_bf16 v[70:73], v[142:145], v[216:219], v[70:73]
	v_mfma_f32_16x16x32_bf16 v[122:125], v[230:233], v[146:149], v[122:125]
	v_mfma_f32_16x16x32_bf16 v[114:117], v[238:241], v[146:149], v[114:117]
	v_mfma_f32_16x16x32_bf16 v[106:109], v[230:233], v[182:185], v[106:109]
	v_mfma_f32_16x16x32_bf16 v[98:101], v[238:241], v[182:185], v[98:101]
	v_mfma_f32_16x16x32_bf16 v[90:93], v[230:233], v[190:193], v[90:93]
	v_mfma_f32_16x16x32_bf16 v[82:85], v[238:241], v[190:193], v[82:85]
	v_mfma_f32_16x16x32_bf16 v[74:77], v[230:233], v[206:209], v[74:77]
	v_mfma_f32_16x16x32_bf16 v[66:69], v[238:241], v[206:209], v[66:69]
	v_mfma_f32_16x16x32_bf16 v[122:125], v[234:237], v[150:153], v[122:125]
	v_mfma_f32_16x16x32_bf16 v[114:117], v[242:245], v[150:153], v[114:117]
	v_mfma_f32_16x16x32_bf16 v[106:109], v[234:237], v[186:189], v[106:109]
	v_mfma_f32_16x16x32_bf16 v[98:101], v[242:245], v[186:189], v[98:101]
	v_mfma_f32_16x16x32_bf16 v[90:93], v[234:237], v[194:197], v[90:93]
	v_mfma_f32_16x16x32_bf16 v[82:85], v[242:245], v[194:197], v[82:85]
	v_mfma_f32_16x16x32_bf16 v[74:77], v[234:237], v[216:219], v[74:77]
	v_mfma_f32_16x16x32_bf16 v[66:69], v[242:245], v[216:219], v[66:69]
	s_setprio 0
	s_barrier
	ds_read_b128 v[146:149], v205 offset:49152
	ds_read_b128 v[150:153], v205 offset:50176
	ds_read_b128 v[182:185], v205 offset:51200
	ds_read_b128 v[186:189], v205 offset:52224
	ds_read_b128 v[190:193], v205 offset:53248
	ds_read_b128 v[194:197], v205 offset:54272
	ds_read_b128 v[206:209], v205 offset:55296
	ds_read_b128 v[216:219], v205 offset:56320
	s_add_i32 s1, s1, s17
	v_lshl_add_u64 v[176:177], v[176:177], 0, s[12:13]
	s_mov_b32 m0, s1
	s_nop 0
	global_load_lds_dwordx4 v[176:177], off
	v_lshl_add_u64 v[176:177], v[202:203], 0, s[12:13]
	s_add_i32 m0, s1, 0x2000
	s_nop 0
	global_load_lds_dwordx4 v[176:177], off
	s_mov_b32 m0, s20
	v_lshl_add_u64 v[176:177], v[220:221], 0, s[12:13]
	global_load_lds_dwordx4 v[176:177], off
	v_lshl_add_u64 v[176:177], v[246:247], 0, s[12:13]
	s_mov_b32 m0, s21
	s_nop 0
	global_load_lds_dwordx4 v[176:177], off
	s_add_u32 s22, s30, 0x40080
	s_addc_u32 s23, s31, 0
	s_add_i32 s1, s33, s17
	s_mov_b32 m0, s1
	s_nop 0
	global_load_lds_dwordx4 v0, s[22:23]
	s_add_i32 m0, s1, 0x2000
	s_nop 0
	global_load_lds_dwordx4 v154, s[22:23]
	s_waitcnt vmcnt(8)
	s_waitcnt lgkmcnt(0)
	v_mfma_f32_16x16x32_bf16 v[62:65], v[130:133], v[146:149], v[62:65]
	v_mfma_f32_16x16x32_bf16 v[54:57], v[138:141], v[146:149], v[54:57]
	v_mfma_f32_16x16x32_bf16 v[46:49], v[130:133], v[182:185], v[46:49]
	v_mfma_f32_16x16x32_bf16 v[38:41], v[138:141], v[182:185], v[38:41]
	s_barrier
	s_setprio 1
	v_mfma_f32_16x16x32_bf16 v[30:33], v[130:133], v[190:193], v[30:33]
	v_mfma_f32_16x16x32_bf16 v[22:25], v[138:141], v[190:193], v[22:25]
	v_mfma_f32_16x16x32_bf16 v[14:17], v[130:133], v[206:209], v[14:17]
	v_mfma_f32_16x16x32_bf16 v[6:9], v[138:141], v[206:209], v[6:9]
	v_mfma_f32_16x16x32_bf16 v[62:65], v[134:137], v[150:153], v[62:65]
	v_mfma_f32_16x16x32_bf16 v[54:57], v[142:145], v[150:153], v[54:57]
	v_mfma_f32_16x16x32_bf16 v[46:49], v[134:137], v[186:189], v[46:49]
	v_mfma_f32_16x16x32_bf16 v[38:41], v[142:145], v[186:189], v[38:41]
	v_mfma_f32_16x16x32_bf16 v[30:33], v[134:137], v[194:197], v[30:33]
	v_mfma_f32_16x16x32_bf16 v[22:25], v[142:145], v[194:197], v[22:25]
	v_mfma_f32_16x16x32_bf16 v[14:17], v[134:137], v[216:219], v[14:17]
	v_mfma_f32_16x16x32_bf16 v[6:9], v[142:145], v[216:219], v[6:9]
	v_mfma_f32_16x16x32_bf16 v[58:61], v[230:233], v[146:149], v[58:61]
	v_mfma_f32_16x16x32_bf16 v[50:53], v[238:241], v[146:149], v[50:53]
	v_mfma_f32_16x16x32_bf16 v[42:45], v[230:233], v[182:185], v[42:45]
	v_mfma_f32_16x16x32_bf16 v[34:37], v[238:241], v[182:185], v[34:37]
	v_mfma_f32_16x16x32_bf16 v[26:29], v[230:233], v[190:193], v[26:29]
	v_mfma_f32_16x16x32_bf16 v[18:21], v[238:241], v[190:193], v[18:21]
	v_mfma_f32_16x16x32_bf16 v[10:13], v[230:233], v[206:209], v[10:13]
	v_mfma_f32_16x16x32_bf16 v[2:5], v[238:241], v[206:209], v[2:5]
	v_mfma_f32_16x16x32_bf16 v[58:61], v[234:237], v[150:153], v[58:61]
	v_mfma_f32_16x16x32_bf16 v[50:53], v[242:245], v[150:153], v[50:53]
	v_mfma_f32_16x16x32_bf16 v[42:45], v[234:237], v[186:189], v[42:45]
	v_mfma_f32_16x16x32_bf16 v[34:37], v[242:245], v[186:189], v[34:37]
	v_mfma_f32_16x16x32_bf16 v[26:29], v[234:237], v[194:197], v[26:29]
	v_mfma_f32_16x16x32_bf16 v[18:21], v[242:245], v[194:197], v[18:21]
	v_mfma_f32_16x16x32_bf16 v[10:13], v[234:237], v[216:219], v[10:13]
	v_mfma_f32_16x16x32_bf16 v[2:5], v[242:245], v[216:219], v[2:5]
	s_setprio 0
	s_add_i32 s60, s60, 2
	s_add_u32 s28, s28, 0x100
	s_addc_u32 s29, s29, 0
	s_add_u32 s58, s58, 0x100
	s_addc_u32 s59, s59, 0
	s_cmp_gt_u32 s60, 13
	s_barrier
.LBB0_83:
	s_add_u32 s1, s28, 0xfffc0080
	s_addc_u32 s22, s29, -1
	s_add_i32 s23, 0, 0x10000
	v_add_u32_e32 v142, s23, v201
	ds_read_b128 v[130:133], v142
	ds_read_b128 v[134:137], v142 offset:1024
	ds_read_b128 v[138:141], v142 offset:2048
	ds_read_b128 v[142:145], v142 offset:3072
	s_cmp_eq_u32 s60, 12
	s_cselect_b32 s43, s27, s22
	s_cselect_b32 s42, s56, s1
	s_cselect_b32 s31, s7, s59
	s_cselect_b32 s30, s57, s58
	v_lshl_add_u64 v[176:177], s[28:29], 0, v[178:179]
	s_add_i32 m0, s46, 0xc000
	ds_read_b128 v[146:149], v205
	ds_read_b128 v[150:153], v205 offset:1024
	ds_read_b128 v[182:185], v205 offset:2048
	ds_read_b128 v[186:189], v205 offset:3072
	ds_read_b128 v[190:193], v205 offset:4096
	ds_read_b128 v[194:197], v205 offset:5120
	ds_read_b128 v[206:209], v205 offset:6144
	ds_read_b128 v[216:219], v205 offset:7168
	global_load_lds_dwordx4 v[176:177], off
	v_lshl_add_u64 v[176:177], s[28:29], 0, v[180:181]
	s_add_i32 m0, s46, 0xe000
	s_nop 0
	global_load_lds_dwordx4 v[176:177], off
	s_add_i32 s1, 0, 0x14000
	v_add_u32_e32 v168, s1, v201
	ds_read_b128 v[230:233], v168
	ds_read_b128 v[234:237], v168 offset:1024
	ds_read_b128 v[238:241], v168 offset:2048
	ds_read_b128 v[242:245], v168 offset:3072
	s_waitcnt vmcnt(8)
	s_waitcnt lgkmcnt(0)
	v_mfma_f32_16x16x32_bf16 v[126:129], v[130:133], v[146:149], v[126:129]
	v_mfma_f32_16x16x32_bf16 v[118:121], v[138:141], v[146:149], v[118:121]
	v_mfma_f32_16x16x32_bf16 v[110:113], v[130:133], v[182:185], v[110:113]
	v_mfma_f32_16x16x32_bf16 v[102:105], v[138:141], v[182:185], v[102:105]
	s_barrier
	s_setprio 1
	v_mfma_f32_16x16x32_bf16 v[94:97], v[130:133], v[190:193], v[94:97]
	v_mfma_f32_16x16x32_bf16 v[86:89], v[138:141], v[190:193], v[86:89]
	v_mfma_f32_16x16x32_bf16 v[78:81], v[130:133], v[206:209], v[78:81]
	v_mfma_f32_16x16x32_bf16 v[70:73], v[138:141], v[206:209], v[70:73]
	v_mfma_f32_16x16x32_bf16 v[126:129], v[134:137], v[150:153], v[126:129]
	v_mfma_f32_16x16x32_bf16 v[118:121], v[142:145], v[150:153], v[118:121]
	v_mfma_f32_16x16x32_bf16 v[110:113], v[134:137], v[186:189], v[110:113]
	v_mfma_f32_16x16x32_bf16 v[102:105], v[142:145], v[186:189], v[102:105]
	v_mfma_f32_16x16x32_bf16 v[94:97], v[134:137], v[194:197], v[94:97]
	v_mfma_f32_16x16x32_bf16 v[86:89], v[142:145], v[194:197], v[86:89]
	v_mfma_f32_16x16x32_bf16 v[78:81], v[134:137], v[216:219], v[78:81]
	v_mfma_f32_16x16x32_bf16 v[70:73], v[142:145], v[216:219], v[70:73]
	v_mfma_f32_16x16x32_bf16 v[122:125], v[230:233], v[146:149], v[122:125]
	v_mfma_f32_16x16x32_bf16 v[114:117], v[238:241], v[146:149], v[114:117]
	v_mfma_f32_16x16x32_bf16 v[106:109], v[230:233], v[182:185], v[106:109]
	v_mfma_f32_16x16x32_bf16 v[98:101], v[238:241], v[182:185], v[98:101]
	v_mfma_f32_16x16x32_bf16 v[90:93], v[230:233], v[190:193], v[90:93]
	v_mfma_f32_16x16x32_bf16 v[82:85], v[238:241], v[190:193], v[82:85]
	v_mfma_f32_16x16x32_bf16 v[74:77], v[230:233], v[206:209], v[74:77]
	v_mfma_f32_16x16x32_bf16 v[66:69], v[238:241], v[206:209], v[66:69]
	v_mfma_f32_16x16x32_bf16 v[122:125], v[234:237], v[150:153], v[122:125]
	v_mfma_f32_16x16x32_bf16 v[114:117], v[242:245], v[150:153], v[114:117]
	v_mfma_f32_16x16x32_bf16 v[106:109], v[234:237], v[186:189], v[106:109]
	v_mfma_f32_16x16x32_bf16 v[98:101], v[242:245], v[186:189], v[98:101]
	v_mfma_f32_16x16x32_bf16 v[90:93], v[234:237], v[194:197], v[90:93]
	v_mfma_f32_16x16x32_bf16 v[82:85], v[242:245], v[194:197], v[82:85]
	v_mfma_f32_16x16x32_bf16 v[74:77], v[234:237], v[216:219], v[74:77]
	v_mfma_f32_16x16x32_bf16 v[66:69], v[242:245], v[216:219], v[66:69]
	s_setprio 0
	s_barrier
	ds_read_b128 v[146:149], v205 offset:16384
	ds_read_b128 v[150:153], v205 offset:17408
	ds_read_b128 v[182:185], v205 offset:18432
	ds_read_b128 v[186:189], v205 offset:19456
	ds_read_b128 v[190:193], v205 offset:20480
	ds_read_b128 v[194:197], v205 offset:21504
	ds_read_b128 v[206:209], v205 offset:22528
	ds_read_b128 v[216:219], v205 offset:23552
	s_add_i32 s22, s23, s17
	v_lshl_add_u64 v[176:177], s[30:31], 0, v[0:1]
	s_mov_b32 m0, s22
	s_nop 0
	global_load_lds_dwordx4 v[176:177], off
	v_lshl_add_u64 v[202:203], s[30:31], 0, v[154:155]
	s_add_i32 m0, s22, 0x2000
	s_nop 0
	global_load_lds_dwordx4 v[202:203], off
	s_mov_b32 m0, s46
	v_lshl_add_u64 v[220:221], s[42:43], 0, v[158:159]
	global_load_lds_dwordx4 v[220:221], off
	v_lshl_add_u64 v[246:247], s[42:43], 0, v[156:157]
	s_mov_b32 m0, s47
	s_nop 0
	global_load_lds_dwordx4 v[246:247], off
	s_add_u32 s22, s30, 0x40000
	s_addc_u32 s23, s31, 0
	s_add_i32 s1, s1, s17
	s_mov_b32 m0, s1
	s_nop 0
	global_load_lds_dwordx4 v0, s[22:23]
	s_add_i32 m0, s1, 0x2000
	s_nop 0
	global_load_lds_dwordx4 v154, s[22:23]
	s_waitcnt vmcnt(8)
	s_waitcnt lgkmcnt(0)
	v_mfma_f32_16x16x32_bf16 v[62:65], v[130:133], v[146:149], v[62:65]
	v_mfma_f32_16x16x32_bf16 v[54:57], v[138:141], v[146:149], v[54:57]
	v_mfma_f32_16x16x32_bf16 v[46:49], v[130:133], v[182:185], v[46:49]
	v_mfma_f32_16x16x32_bf16 v[38:41], v[138:141], v[182:185], v[38:41]
	s_barrier
	s_setprio 1
	v_mfma_f32_16x16x32_bf16 v[30:33], v[130:133], v[190:193], v[30:33]
	v_mfma_f32_16x16x32_bf16 v[22:25], v[138:141], v[190:193], v[22:25]
	v_mfma_f32_16x16x32_bf16 v[14:17], v[130:133], v[206:209], v[14:17]
	v_mfma_f32_16x16x32_bf16 v[6:9], v[138:141], v[206:209], v[6:9]
	v_mfma_f32_16x16x32_bf16 v[62:65], v[134:137], v[150:153], v[62:65]
	v_mfma_f32_16x16x32_bf16 v[54:57], v[142:145], v[150:153], v[54:57]
	v_mfma_f32_16x16x32_bf16 v[46:49], v[134:137], v[186:189], v[46:49]
	v_mfma_f32_16x16x32_bf16 v[38:41], v[142:145], v[186:189], v[38:41]
	v_mfma_f32_16x16x32_bf16 v[30:33], v[134:137], v[194:197], v[30:33]
	v_mfma_f32_16x16x32_bf16 v[22:25], v[142:145], v[194:197], v[22:25]
	v_mfma_f32_16x16x32_bf16 v[14:17], v[134:137], v[216:219], v[14:17]
	v_mfma_f32_16x16x32_bf16 v[6:9], v[142:145], v[216:219], v[6:9]
	v_mfma_f32_16x16x32_bf16 v[58:61], v[230:233], v[146:149], v[58:61]
	v_mfma_f32_16x16x32_bf16 v[50:53], v[238:241], v[146:149], v[50:53]
	v_mfma_f32_16x16x32_bf16 v[42:45], v[230:233], v[182:185], v[42:45]
	v_mfma_f32_16x16x32_bf16 v[34:37], v[238:241], v[182:185], v[34:37]
	v_mfma_f32_16x16x32_bf16 v[26:29], v[230:233], v[190:193], v[26:29]
	v_mfma_f32_16x16x32_bf16 v[18:21], v[238:241], v[190:193], v[18:21]
	v_mfma_f32_16x16x32_bf16 v[10:13], v[230:233], v[206:209], v[10:13]
	v_mfma_f32_16x16x32_bf16 v[2:5], v[238:241], v[206:209], v[2:5]
	v_mfma_f32_16x16x32_bf16 v[58:61], v[234:237], v[150:153], v[58:61]
	v_mfma_f32_16x16x32_bf16 v[50:53], v[242:245], v[150:153], v[50:53]
	v_mfma_f32_16x16x32_bf16 v[42:45], v[234:237], v[186:189], v[42:45]
	v_mfma_f32_16x16x32_bf16 v[34:37], v[242:245], v[186:189], v[34:37]
	v_mfma_f32_16x16x32_bf16 v[26:29], v[234:237], v[194:197], v[26:29]
	v_mfma_f32_16x16x32_bf16 v[18:21], v[242:245], v[194:197], v[18:21]
	v_mfma_f32_16x16x32_bf16 v[10:13], v[234:237], v[216:219], v[10:13]
	v_mfma_f32_16x16x32_bf16 v[2:5], v[242:245], v[216:219], v[2:5]
	s_setprio 0
	s_barrier
	s_add_i32 s1, 0, 0x18000
	v_add_u32_e32 v142, s1, v201
	ds_read_b128 v[130:133], v142
	ds_read_b128 v[134:137], v142 offset:1024
	ds_read_b128 v[138:141], v142 offset:2048
	ds_read_b128 v[142:145], v142 offset:3072
	s_add_u32 s22, s42, 0x40000
	s_addc_u32 s23, s43, 0
	s_mov_b32 m0, s48
	v_lshl_add_u64 v[230:231], s[22:23], 0, v[158:159]
	ds_read_b128 v[146:149], v205 offset:32768
	ds_read_b128 v[150:153], v205 offset:33792
	ds_read_b128 v[182:185], v205 offset:34816
	ds_read_b128 v[186:189], v205 offset:35840
	ds_read_b128 v[190:193], v205 offset:36864
	ds_read_b128 v[194:197], v205 offset:37888
	ds_read_b128 v[206:209], v205 offset:38912
	ds_read_b128 v[216:219], v205 offset:39936
	global_load_lds_dwordx4 v[230:231], off
	v_lshl_add_u64 v[230:231], s[22:23], 0, v[156:157]
	s_mov_b32 m0, s49
	s_nop 0
	global_load_lds_dwordx4 v[230:231], off
	s_add_i32 s33, 0, 0x1c000
	v_add_u32_e32 v168, s33, v201
	ds_read_b128 v[230:233], v168
	ds_read_b128 v[234:237], v168 offset:1024
	ds_read_b128 v[238:241], v168 offset:2048
	ds_read_b128 v[242:245], v168 offset:3072
	s_waitcnt vmcnt(8)
	s_waitcnt lgkmcnt(0)
	v_mfma_f32_16x16x32_bf16 v[126:129], v[130:133], v[146:149], v[126:129]
	v_mfma_f32_16x16x32_bf16 v[118:121], v[138:141], v[146:149], v[118:121]
	v_mfma_f32_16x16x32_bf16 v[110:113], v[130:133], v[182:185], v[110:113]
	v_mfma_f32_16x16x32_bf16 v[102:105], v[138:141], v[182:185], v[102:105]
	s_barrier
	s_setprio 1
	v_mfma_f32_16x16x32_bf16 v[94:97], v[130:133], v[190:193], v[94:97]
	v_mfma_f32_16x16x32_bf16 v[86:89], v[138:141], v[190:193], v[86:89]
	v_mfma_f32_16x16x32_bf16 v[78:81], v[130:133], v[206:209], v[78:81]
	v_mfma_f32_16x16x32_bf16 v[70:73], v[138:141], v[206:209], v[70:73]
	v_mfma_f32_16x16x32_bf16 v[126:129], v[134:137], v[150:153], v[126:129]
	v_mfma_f32_16x16x32_bf16 v[118:121], v[142:145], v[150:153], v[118:121]
	v_mfma_f32_16x16x32_bf16 v[110:113], v[134:137], v[186:189], v[110:113]
	v_mfma_f32_16x16x32_bf16 v[102:105], v[142:145], v[186:189], v[102:105]
	v_mfma_f32_16x16x32_bf16 v[94:97], v[134:137], v[194:197], v[94:97]
	v_mfma_f32_16x16x32_bf16 v[86:89], v[142:145], v[194:197], v[86:89]
	v_mfma_f32_16x16x32_bf16 v[78:81], v[134:137], v[216:219], v[78:81]
	v_mfma_f32_16x16x32_bf16 v[70:73], v[142:145], v[216:219], v[70:73]
	v_mfma_f32_16x16x32_bf16 v[122:125], v[230:233], v[146:149], v[122:125]
	v_mfma_f32_16x16x32_bf16 v[114:117], v[238:241], v[146:149], v[114:117]
	v_mfma_f32_16x16x32_bf16 v[106:109], v[230:233], v[182:185], v[106:109]
	v_mfma_f32_16x16x32_bf16 v[98:101], v[238:241], v[182:185], v[98:101]
	v_mfma_f32_16x16x32_bf16 v[90:93], v[230:233], v[190:193], v[90:93]
	v_mfma_f32_16x16x32_bf16 v[82:85], v[238:241], v[190:193], v[82:85]
	v_mfma_f32_16x16x32_bf16 v[74:77], v[230:233], v[206:209], v[74:77]
	v_mfma_f32_16x16x32_bf16 v[66:69], v[238:241], v[206:209], v[66:69]
	v_mfma_f32_16x16x32_bf16 v[122:125], v[234:237], v[150:153], v[122:125]
	v_mfma_f32_16x16x32_bf16 v[114:117], v[242:245], v[150:153], v[114:117]
	v_mfma_f32_16x16x32_bf16 v[106:109], v[234:237], v[186:189], v[106:109]
	v_mfma_f32_16x16x32_bf16 v[98:101], v[242:245], v[186:189], v[98:101]
	v_mfma_f32_16x16x32_bf16 v[90:93], v[234:237], v[194:197], v[90:93]
	v_mfma_f32_16x16x32_bf16 v[82:85], v[242:245], v[194:197], v[82:85]
	v_mfma_f32_16x16x32_bf16 v[74:77], v[234:237], v[216:219], v[74:77]
	v_mfma_f32_16x16x32_bf16 v[66:69], v[242:245], v[216:219], v[66:69]
	s_setprio 0
	s_barrier
	ds_read_b128 v[146:149], v205 offset:49152
	ds_read_b128 v[150:153], v205 offset:50176
	ds_read_b128 v[182:185], v205 offset:51200
	ds_read_b128 v[186:189], v205 offset:52224
	ds_read_b128 v[190:193], v205 offset:53248
	ds_read_b128 v[194:197], v205 offset:54272
	ds_read_b128 v[206:209], v205 offset:55296
	ds_read_b128 v[216:219], v205 offset:56320
	s_add_i32 s1, s1, s17
	v_lshl_add_u64 v[176:177], v[176:177], 0, s[12:13]
	s_mov_b32 m0, s1
	s_nop 0
	global_load_lds_dwordx4 v[176:177], off
	v_lshl_add_u64 v[176:177], v[202:203], 0, s[12:13]
	s_add_i32 m0, s1, 0x2000
	s_nop 0
	global_load_lds_dwordx4 v[176:177], off
	s_mov_b32 m0, s20
	v_lshl_add_u64 v[176:177], v[220:221], 0, s[12:13]
	global_load_lds_dwordx4 v[176:177], off
	v_lshl_add_u64 v[176:177], v[246:247], 0, s[12:13]
	s_mov_b32 m0, s21
	s_nop 0
	global_load_lds_dwordx4 v[176:177], off
	s_add_u32 s22, s30, 0x40080
	s_addc_u32 s23, s31, 0
	s_add_i32 s1, s33, s17
	s_mov_b32 m0, s1
	s_nop 0
	global_load_lds_dwordx4 v0, s[22:23]
	s_add_i32 m0, s1, 0x2000
	s_nop 0
	global_load_lds_dwordx4 v154, s[22:23]
	s_waitcnt vmcnt(8)
	s_waitcnt lgkmcnt(0)
	v_mfma_f32_16x16x32_bf16 v[62:65], v[130:133], v[146:149], v[62:65]
	v_mfma_f32_16x16x32_bf16 v[54:57], v[138:141], v[146:149], v[54:57]
	v_mfma_f32_16x16x32_bf16 v[46:49], v[130:133], v[182:185], v[46:49]
	v_mfma_f32_16x16x32_bf16 v[38:41], v[138:141], v[182:185], v[38:41]
	s_barrier
	s_setprio 1
	v_mfma_f32_16x16x32_bf16 v[30:33], v[130:133], v[190:193], v[30:33]
	v_mfma_f32_16x16x32_bf16 v[22:25], v[138:141], v[190:193], v[22:25]
	v_mfma_f32_16x16x32_bf16 v[14:17], v[130:133], v[206:209], v[14:17]
	v_mfma_f32_16x16x32_bf16 v[6:9], v[138:141], v[206:209], v[6:9]
	v_mfma_f32_16x16x32_bf16 v[62:65], v[134:137], v[150:153], v[62:65]
	v_mfma_f32_16x16x32_bf16 v[54:57], v[142:145], v[150:153], v[54:57]
	v_mfma_f32_16x16x32_bf16 v[46:49], v[134:137], v[186:189], v[46:49]
	v_mfma_f32_16x16x32_bf16 v[38:41], v[142:145], v[186:189], v[38:41]
	v_mfma_f32_16x16x32_bf16 v[30:33], v[134:137], v[194:197], v[30:33]
	v_mfma_f32_16x16x32_bf16 v[22:25], v[142:145], v[194:197], v[22:25]
	v_mfma_f32_16x16x32_bf16 v[14:17], v[134:137], v[216:219], v[14:17]
	v_mfma_f32_16x16x32_bf16 v[6:9], v[142:145], v[216:219], v[6:9]
	v_mfma_f32_16x16x32_bf16 v[58:61], v[230:233], v[146:149], v[58:61]
	v_mfma_f32_16x16x32_bf16 v[50:53], v[238:241], v[146:149], v[50:53]
	v_mfma_f32_16x16x32_bf16 v[42:45], v[230:233], v[182:185], v[42:45]
	v_mfma_f32_16x16x32_bf16 v[34:37], v[238:241], v[182:185], v[34:37]
	v_mfma_f32_16x16x32_bf16 v[26:29], v[230:233], v[190:193], v[26:29]
	v_mfma_f32_16x16x32_bf16 v[18:21], v[238:241], v[190:193], v[18:21]
	v_mfma_f32_16x16x32_bf16 v[10:13], v[230:233], v[206:209], v[10:13]
	v_mfma_f32_16x16x32_bf16 v[2:5], v[238:241], v[206:209], v[2:5]
	v_mfma_f32_16x16x32_bf16 v[58:61], v[234:237], v[150:153], v[58:61]
	v_mfma_f32_16x16x32_bf16 v[50:53], v[242:245], v[150:153], v[50:53]
	v_mfma_f32_16x16x32_bf16 v[42:45], v[234:237], v[186:189], v[42:45]
	v_mfma_f32_16x16x32_bf16 v[34:37], v[242:245], v[186:189], v[34:37]
	v_mfma_f32_16x16x32_bf16 v[26:29], v[234:237], v[194:197], v[26:29]
	v_mfma_f32_16x16x32_bf16 v[18:21], v[242:245], v[194:197], v[18:21]
	v_mfma_f32_16x16x32_bf16 v[10:13], v[234:237], v[216:219], v[10:13]
	v_mfma_f32_16x16x32_bf16 v[2:5], v[242:245], v[216:219], v[2:5]
	s_setprio 0
	s_add_i32 s60, s60, 2
	s_add_u32 s28, s28, 0x100
	s_addc_u32 s29, s29, 0
	s_add_u32 s58, s58, 0x100
	s_addc_u32 s59, s59, 0
	s_cmp_gt_u32 s60, 13
	s_barrier
	s_cbranch_scc0 .LBB0_83
	s_cmpk_gt_u32 s0, 0xff
	s_cbranch_scc1 .Lrs_i2_post
	s_barrier

.Lrs_i3_pre:
	s_add_i32 s23, s22, 2
	s_add_u32 s1, s36, 0x80
	s_addc_u32 s30, s37, 0
	s_add_i32 s33, 0, 0x10000
	v_add_u32_e32 v142, s33, v203
	ds_read_b128 v[130:133], v142
	ds_read_b128 v[134:137], v142 offset:1024
	ds_read_b128 v[138:141], v142 offset:2048
	ds_read_b128 v[142:145], v142 offset:3072
	s_cmp_eq_u32 s69, s22
	s_cselect_b32 s31, s27, s30
	s_cselect_b32 s30, s26, s1
	s_cselect_b32 s47, s29, s49
	s_cselect_b32 s46, s28, s48
	v_lshl_add_u64 v[176:177], s[36:37], 0, v[180:181]
	s_add_i32 m0, s21, 0xc000
	ds_read_b128 v[146:149], v205
	ds_read_b128 v[150:153], v205 offset:1024
	ds_read_b128 v[154:157], v205 offset:2048
	ds_read_b128 v[184:187], v205 offset:3072
	ds_read_b128 v[188:191], v205 offset:4096
	ds_read_b128 v[192:195], v205 offset:5120
	ds_read_b128 v[196:199], v205 offset:6144
	ds_read_b128 v[206:209], v205 offset:7168
	global_load_lds_dwordx4 v[176:177], off
	v_lshl_add_u64 v[176:177], s[36:37], 0, v[182:183]
	s_add_i32 m0, s21, 0xe000
	s_nop 0
	global_load_lds_dwordx4 v[176:177], off
	s_add_i32 s1, 0, 0x14000
	v_add_u32_e32 v168, s1, v203
	ds_read_b128 v[216:219], v168
	ds_read_b128 v[230:233], v168 offset:1024
	ds_read_b128 v[234:237], v168 offset:2048
	ds_read_b128 v[238:241], v168 offset:3072
	s_waitcnt vmcnt(8)
	s_waitcnt lgkmcnt(0)
	v_mfma_f32_16x16x32_bf16 v[126:129], v[130:133], v[146:149], 0
	v_mfma_f32_16x16x32_bf16 v[122:125], v[138:141], v[146:149], 0
	v_mfma_f32_16x16x32_bf16 v[110:113], v[130:133], v[154:157], 0
	v_mfma_f32_16x16x32_bf16 v[106:109], v[138:141], v[154:157], 0
	s_barrier
	s_setprio 1
	v_mfma_f32_16x16x32_bf16 v[94:97], v[130:133], v[188:191], 0
	v_mfma_f32_16x16x32_bf16 v[90:93], v[138:141], v[188:191], 0
	v_mfma_f32_16x16x32_bf16 v[78:81], v[130:133], v[196:199], 0
	v_mfma_f32_16x16x32_bf16 v[74:77], v[138:141], v[196:199], 0
	v_mfma_f32_16x16x32_bf16 v[126:129], v[134:137], v[150:153], v[126:129]
	v_mfma_f32_16x16x32_bf16 v[122:125], v[142:145], v[150:153], v[122:125]
	v_mfma_f32_16x16x32_bf16 v[110:113], v[134:137], v[184:187], v[110:113]
	v_mfma_f32_16x16x32_bf16 v[106:109], v[142:145], v[184:187], v[106:109]
	v_mfma_f32_16x16x32_bf16 v[94:97], v[134:137], v[192:195], v[94:97]
	v_mfma_f32_16x16x32_bf16 v[90:93], v[142:145], v[192:195], v[90:93]
	v_mfma_f32_16x16x32_bf16 v[78:81], v[134:137], v[206:209], v[78:81]
	v_mfma_f32_16x16x32_bf16 v[74:77], v[142:145], v[206:209], v[74:77]
	v_mfma_f32_16x16x32_bf16 v[118:121], v[216:219], v[146:149], 0
	v_mfma_f32_16x16x32_bf16 v[114:117], v[234:237], v[146:149], 0
	v_mfma_f32_16x16x32_bf16 v[102:105], v[216:219], v[154:157], 0
	v_mfma_f32_16x16x32_bf16 v[98:101], v[234:237], v[154:157], 0
	v_mfma_f32_16x16x32_bf16 v[86:89], v[216:219], v[188:191], 0
	v_mfma_f32_16x16x32_bf16 v[82:85], v[234:237], v[188:191], 0
	v_mfma_f32_16x16x32_bf16 v[70:73], v[216:219], v[196:199], 0
	v_mfma_f32_16x16x32_bf16 v[66:69], v[234:237], v[196:199], 0
	v_mfma_f32_16x16x32_bf16 v[118:121], v[230:233], v[150:153], v[118:121]
	v_mfma_f32_16x16x32_bf16 v[114:117], v[238:241], v[150:153], v[114:117]
	v_mfma_f32_16x16x32_bf16 v[102:105], v[230:233], v[184:187], v[102:105]
	v_mfma_f32_16x16x32_bf16 v[98:101], v[238:241], v[184:187], v[98:101]
	v_mfma_f32_16x16x32_bf16 v[86:89], v[230:233], v[192:195], v[86:89]
	v_mfma_f32_16x16x32_bf16 v[82:85], v[238:241], v[192:195], v[82:85]
	v_mfma_f32_16x16x32_bf16 v[70:73], v[230:233], v[206:209], v[70:73]
	v_mfma_f32_16x16x32_bf16 v[66:69], v[238:241], v[206:209], v[66:69]
	s_setprio 0
	s_barrier
	ds_read_b128 v[146:149], v205 offset:16384
	ds_read_b128 v[150:153], v205 offset:17408
	ds_read_b128 v[154:157], v205 offset:18432
	ds_read_b128 v[184:187], v205 offset:19456
	ds_read_b128 v[188:191], v205 offset:20480
	ds_read_b128 v[192:195], v205 offset:21504
	ds_read_b128 v[196:199], v205 offset:22528
	ds_read_b128 v[206:209], v205 offset:23552
	s_add_i32 s22, s33, s20
	v_lshl_add_u64 v[176:177], s[46:47], 0, v[0:1]
	s_mov_b32 m0, s22
	s_nop 0
	global_load_lds_dwordx4 v[176:177], off
	v_lshl_add_u64 v[200:201], s[46:47], 0, v[158:159]
	s_add_i32 m0, s22, 0x2000
	s_nop 0
	global_load_lds_dwordx4 v[200:201], off
	s_mov_b32 m0, s21
	v_lshl_add_u64 v[220:221], s[30:31], 0, v[178:179]
	global_load_lds_dwordx4 v[220:221], off
	v_lshl_add_u64 v[242:243], s[30:31], 0, v[160:161]
	s_mov_b32 m0, s34
	s_nop 0
	global_load_lds_dwordx4 v[242:243], off
	s_add_u32 s46, s46, s6
	s_addc_u32 s47, s47, 0
	s_add_i32 s1, s1, s20
	v_lshl_add_u64 v[244:245], s[46:47], 0, v[0:1]
	s_mov_b32 m0, s1
	v_lshl_add_u64 v[246:247], s[46:47], 0, v[158:159]
	global_load_lds_dwordx4 v[244:245], off
	s_add_i32 m0, s1, 0x2000
	s_nop 0
	global_load_lds_dwordx4 v[246:247], off
	s_waitcnt vmcnt(8)
	s_waitcnt lgkmcnt(0)
	v_mfma_f32_16x16x32_bf16 v[62:65], v[130:133], v[146:149], 0
	v_mfma_f32_16x16x32_bf16 v[58:61], v[138:141], v[146:149], 0
	v_mfma_f32_16x16x32_bf16 v[46:49], v[130:133], v[154:157], 0
	v_mfma_f32_16x16x32_bf16 v[42:45], v[138:141], v[154:157], 0
	s_barrier
	s_setprio 1
	v_mfma_f32_16x16x32_bf16 v[30:33], v[130:133], v[188:191], 0
	v_mfma_f32_16x16x32_bf16 v[26:29], v[138:141], v[188:191], 0
	v_mfma_f32_16x16x32_bf16 v[14:17], v[130:133], v[196:199], 0
	v_mfma_f32_16x16x32_bf16 v[10:13], v[138:141], v[196:199], 0
	v_mfma_f32_16x16x32_bf16 v[62:65], v[134:137], v[150:153], v[62:65]
	v_mfma_f32_16x16x32_bf16 v[58:61], v[142:145], v[150:153], v[58:61]
	v_mfma_f32_16x16x32_bf16 v[46:49], v[134:137], v[184:187], v[46:49]
	v_mfma_f32_16x16x32_bf16 v[42:45], v[142:145], v[184:187], v[42:45]
	v_mfma_f32_16x16x32_bf16 v[30:33], v[134:137], v[192:195], v[30:33]
	v_mfma_f32_16x16x32_bf16 v[26:29], v[142:145], v[192:195], v[26:29]
	v_mfma_f32_16x16x32_bf16 v[14:17], v[134:137], v[206:209], v[14:17]
	v_mfma_f32_16x16x32_bf16 v[10:13], v[142:145], v[206:209], v[10:13]
	v_mfma_f32_16x16x32_bf16 v[54:57], v[216:219], v[146:149], 0
	v_mfma_f32_16x16x32_bf16 v[50:53], v[234:237], v[146:149], 0
	v_mfma_f32_16x16x32_bf16 v[38:41], v[216:219], v[154:157], 0
	v_mfma_f32_16x16x32_bf16 v[34:37], v[234:237], v[154:157], 0
	v_mfma_f32_16x16x32_bf16 v[22:25], v[216:219], v[188:191], 0
	v_mfma_f32_16x16x32_bf16 v[18:21], v[234:237], v[188:191], 0
	v_mfma_f32_16x16x32_bf16 v[6:9], v[216:219], v[196:199], 0
	v_mfma_f32_16x16x32_bf16 v[2:5], v[234:237], v[196:199], 0
	v_mfma_f32_16x16x32_bf16 v[54:57], v[230:233], v[150:153], v[54:57]
	v_mfma_f32_16x16x32_bf16 v[50:53], v[238:241], v[150:153], v[50:53]
	v_mfma_f32_16x16x32_bf16 v[38:41], v[230:233], v[184:187], v[38:41]
	v_mfma_f32_16x16x32_bf16 v[34:37], v[238:241], v[184:187], v[34:37]
	v_mfma_f32_16x16x32_bf16 v[22:25], v[230:233], v[192:195], v[22:25]
	v_mfma_f32_16x16x32_bf16 v[18:21], v[238:241], v[192:195], v[18:21]
	v_mfma_f32_16x16x32_bf16 v[6:9], v[230:233], v[206:209], v[6:9]
	v_mfma_f32_16x16x32_bf16 v[2:5], v[238:241], v[206:209], v[2:5]
	s_setprio 0
	s_barrier
	s_add_i32 s1, 0, 0x18000
	v_add_u32_e32 v142, s1, v203
	ds_read_b128 v[130:133], v142
	ds_read_b128 v[134:137], v142 offset:1024
	ds_read_b128 v[138:141], v142 offset:2048
	ds_read_b128 v[142:145], v142 offset:3072
	s_add_u32 s30, s30, s6
	s_addc_u32 s31, s31, 0
	s_mov_b32 m0, s63
	v_lshl_add_u64 v[216:217], s[30:31], 0, v[178:179]
	ds_read_b128 v[146:149], v205 offset:32768
	ds_read_b128 v[150:153], v205 offset:33792
	ds_read_b128 v[154:157], v205 offset:34816
	ds_read_b128 v[184:187], v205 offset:35840
	ds_read_b128 v[188:191], v205 offset:36864
	ds_read_b128 v[192:195], v205 offset:37888
	ds_read_b128 v[196:199], v205 offset:38912
	ds_read_b128 v[206:209], v205 offset:39936
	global_load_lds_dwordx4 v[216:217], off
	v_lshl_add_u64 v[216:217], s[30:31], 0, v[160:161]
	s_mov_b32 m0, s64
	s_nop 0
	global_load_lds_dwordx4 v[216:217], off
	s_add_i32 s22, 0, 0x1c000
	v_add_u32_e32 v168, s22, v203
	ds_read_b128 v[216:219], v168
	ds_read_b128 v[230:233], v168 offset:1024
	ds_read_b128 v[234:237], v168 offset:2048
	ds_read_b128 v[238:241], v168 offset:3072
	s_waitcnt vmcnt(8)
	s_waitcnt lgkmcnt(0)
	v_mfma_f32_16x16x32_bf16 v[126:129], v[130:133], v[146:149], v[126:129]
	v_mfma_f32_16x16x32_bf16 v[122:125], v[138:141], v[146:149], v[122:125]
	v_mfma_f32_16x16x32_bf16 v[110:113], v[130:133], v[154:157], v[110:113]
	v_mfma_f32_16x16x32_bf16 v[106:109], v[138:141], v[154:157], v[106:109]
	s_barrier
	s_setprio 1
	v_mfma_f32_16x16x32_bf16 v[94:97], v[130:133], v[188:191], v[94:97]
	v_mfma_f32_16x16x32_bf16 v[90:93], v[138:141], v[188:191], v[90:93]
	v_mfma_f32_16x16x32_bf16 v[78:81], v[130:133], v[196:199], v[78:81]
	v_mfma_f32_16x16x32_bf16 v[74:77], v[138:141], v[196:199], v[74:77]
	v_mfma_f32_16x16x32_bf16 v[126:129], v[134:137], v[150:153], v[126:129]
	v_mfma_f32_16x16x32_bf16 v[122:125], v[142:145], v[150:153], v[122:125]
	v_mfma_f32_16x16x32_bf16 v[110:113], v[134:137], v[184:187], v[110:113]
	v_mfma_f32_16x16x32_bf16 v[106:109], v[142:145], v[184:187], v[106:109]
	v_mfma_f32_16x16x32_bf16 v[94:97], v[134:137], v[192:195], v[94:97]
	v_mfma_f32_16x16x32_bf16 v[90:93], v[142:145], v[192:195], v[90:93]
	v_mfma_f32_16x16x32_bf16 v[78:81], v[134:137], v[206:209], v[78:81]
	v_mfma_f32_16x16x32_bf16 v[74:77], v[142:145], v[206:209], v[74:77]
	v_mfma_f32_16x16x32_bf16 v[118:121], v[216:219], v[146:149], v[118:121]
	v_mfma_f32_16x16x32_bf16 v[114:117], v[234:237], v[146:149], v[114:117]
	v_mfma_f32_16x16x32_bf16 v[102:105], v[216:219], v[154:157], v[102:105]
	v_mfma_f32_16x16x32_bf16 v[98:101], v[234:237], v[154:157], v[98:101]
	v_mfma_f32_16x16x32_bf16 v[86:89], v[216:219], v[188:191], v[86:89]
	v_mfma_f32_16x16x32_bf16 v[82:85], v[234:237], v[188:191], v[82:85]
	v_mfma_f32_16x16x32_bf16 v[70:73], v[216:219], v[196:199], v[70:73]
	v_mfma_f32_16x16x32_bf16 v[66:69], v[234:237], v[196:199], v[66:69]
	v_mfma_f32_16x16x32_bf16 v[118:121], v[230:233], v[150:153], v[118:121]
	v_mfma_f32_16x16x32_bf16 v[114:117], v[238:241], v[150:153], v[114:117]
	v_mfma_f32_16x16x32_bf16 v[102:105], v[230:233], v[184:187], v[102:105]
	v_mfma_f32_16x16x32_bf16 v[98:101], v[238:241], v[184:187], v[98:101]
	v_mfma_f32_16x16x32_bf16 v[86:89], v[230:233], v[192:195], v[86:89]
	v_mfma_f32_16x16x32_bf16 v[82:85], v[238:241], v[192:195], v[82:85]
	v_mfma_f32_16x16x32_bf16 v[70:73], v[230:233], v[206:209], v[70:73]
	v_mfma_f32_16x16x32_bf16 v[66:69], v[238:241], v[206:209], v[66:69]
	s_setprio 0
	s_barrier
	ds_read_b128 v[146:149], v205 offset:49152
	ds_read_b128 v[150:153], v205 offset:50176
	ds_read_b128 v[154:157], v205 offset:51200
	ds_read_b128 v[184:187], v205 offset:52224
	ds_read_b128 v[188:191], v205 offset:53248
	ds_read_b128 v[192:195], v205 offset:54272
	ds_read_b128 v[196:199], v205 offset:55296
	ds_read_b128 v[206:209], v205 offset:56320
	s_add_i32 s1, s1, s20
	v_lshl_add_u64 v[176:177], v[176:177], 0, s[12:13]
	s_mov_b32 m0, s1
	s_nop 0
	global_load_lds_dwordx4 v[176:177], off
	v_lshl_add_u64 v[176:177], v[200:201], 0, s[12:13]
	s_add_i32 m0, s1, 0x2000
	s_nop 0
	global_load_lds_dwordx4 v[176:177], off
	s_mov_b32 m0, s65
	v_lshl_add_u64 v[176:177], v[220:221], 0, s[12:13]
	global_load_lds_dwordx4 v[176:177], off
	v_lshl_add_u64 v[176:177], v[242:243], 0, s[12:13]
	s_mov_b32 m0, s66
	s_nop 0
	global_load_lds_dwordx4 v[176:177], off
	s_add_i32 s1, s22, s20
	v_lshl_add_u64 v[176:177], v[244:245], 0, s[12:13]
	s_mov_b32 m0, s1
	s_nop 0
	global_load_lds_dwordx4 v[176:177], off
	v_lshl_add_u64 v[176:177], v[246:247], 0, s[12:13]
	s_add_i32 m0, s1, 0x2000
	s_nop 0
	global_load_lds_dwordx4 v[176:177], off
	s_waitcnt vmcnt(8)
	s_waitcnt lgkmcnt(0)
	v_mfma_f32_16x16x32_bf16 v[62:65], v[130:133], v[146:149], v[62:65]
	v_mfma_f32_16x16x32_bf16 v[58:61], v[138:141], v[146:149], v[58:61]
	v_mfma_f32_16x16x32_bf16 v[46:49], v[130:133], v[154:157], v[46:49]
	v_mfma_f32_16x16x32_bf16 v[42:45], v[138:141], v[154:157], v[42:45]
	s_barrier
	s_setprio 1
	v_mfma_f32_16x16x32_bf16 v[30:33], v[130:133], v[188:191], v[30:33]
	v_mfma_f32_16x16x32_bf16 v[26:29], v[138:141], v[188:191], v[26:29]
	v_mfma_f32_16x16x32_bf16 v[14:17], v[130:133], v[196:199], v[14:17]
	v_mfma_f32_16x16x32_bf16 v[10:13], v[138:141], v[196:199], v[10:13]
	v_mfma_f32_16x16x32_bf16 v[62:65], v[134:137], v[150:153], v[62:65]
	v_mfma_f32_16x16x32_bf16 v[58:61], v[142:145], v[150:153], v[58:61]
	v_mfma_f32_16x16x32_bf16 v[46:49], v[134:137], v[184:187], v[46:49]
	v_mfma_f32_16x16x32_bf16 v[42:45], v[142:145], v[184:187], v[42:45]
	v_mfma_f32_16x16x32_bf16 v[30:33], v[134:137], v[192:195], v[30:33]
	v_mfma_f32_16x16x32_bf16 v[26:29], v[142:145], v[192:195], v[26:29]
	v_mfma_f32_16x16x32_bf16 v[14:17], v[134:137], v[206:209], v[14:17]
	v_mfma_f32_16x16x32_bf16 v[10:13], v[142:145], v[206:209], v[10:13]
	v_mfma_f32_16x16x32_bf16 v[54:57], v[216:219], v[146:149], v[54:57]
	v_mfma_f32_16x16x32_bf16 v[50:53], v[234:237], v[146:149], v[50:53]
	v_mfma_f32_16x16x32_bf16 v[38:41], v[216:219], v[154:157], v[38:41]
	v_mfma_f32_16x16x32_bf16 v[34:37], v[234:237], v[154:157], v[34:37]
	v_mfma_f32_16x16x32_bf16 v[22:25], v[216:219], v[188:191], v[22:25]
	v_mfma_f32_16x16x32_bf16 v[18:21], v[234:237], v[188:191], v[18:21]
	v_mfma_f32_16x16x32_bf16 v[6:9], v[216:219], v[196:199], v[6:9]
	v_mfma_f32_16x16x32_bf16 v[2:5], v[234:237], v[196:199], v[2:5]
	v_mfma_f32_16x16x32_bf16 v[54:57], v[230:233], v[150:153], v[54:57]
	v_mfma_f32_16x16x32_bf16 v[50:53], v[238:241], v[150:153], v[50:53]
	v_mfma_f32_16x16x32_bf16 v[38:41], v[230:233], v[184:187], v[38:41]
	v_mfma_f32_16x16x32_bf16 v[34:37], v[238:241], v[184:187], v[34:37]
	v_mfma_f32_16x16x32_bf16 v[22:25], v[230:233], v[192:195], v[22:25]
	v_mfma_f32_16x16x32_bf16 v[18:21], v[238:241], v[192:195], v[18:21]
	v_mfma_f32_16x16x32_bf16 v[6:9], v[230:233], v[206:209], v[6:9]
	v_mfma_f32_16x16x32_bf16 v[2:5], v[238:241], v[206:209], v[2:5]
	s_setprio 0
	s_add_u32 s36, s36, 0x100
	s_addc_u32 s37, s37, 0
	s_add_u32 s48, s48, 0x100
	s_addc_u32 s49, s49, 0
	s_cmp_ge_u32 s23, s68
	s_mov_b32 s22, s23
	s_barrier
.LBB0_120:
	s_add_i32 s23, s22, 2
	s_add_u32 s1, s36, 0x80
	s_addc_u32 s30, s37, 0
	s_add_i32 s33, 0, 0x10000
	v_add_u32_e32 v142, s33, v203
	ds_read_b128 v[130:133], v142
	ds_read_b128 v[134:137], v142 offset:1024
	ds_read_b128 v[138:141], v142 offset:2048
	ds_read_b128 v[142:145], v142 offset:3072
	s_cmp_eq_u32 s69, s22
	s_cselect_b32 s31, s27, s30
	s_cselect_b32 s30, s26, s1
	s_cselect_b32 s47, s29, s49
	s_cselect_b32 s46, s28, s48
	v_lshl_add_u64 v[176:177], s[36:37], 0, v[180:181]
	s_add_i32 m0, s21, 0xc000
	ds_read_b128 v[146:149], v205
	ds_read_b128 v[150:153], v205 offset:1024
	ds_read_b128 v[154:157], v205 offset:2048
	ds_read_b128 v[184:187], v205 offset:3072
	ds_read_b128 v[188:191], v205 offset:4096
	ds_read_b128 v[192:195], v205 offset:5120
	ds_read_b128 v[196:199], v205 offset:6144
	ds_read_b128 v[206:209], v205 offset:7168
	global_load_lds_dwordx4 v[176:177], off
	v_lshl_add_u64 v[176:177], s[36:37], 0, v[182:183]
	s_add_i32 m0, s21, 0xe000
	s_nop 0
	global_load_lds_dwordx4 v[176:177], off
	s_add_i32 s1, 0, 0x14000
	v_add_u32_e32 v168, s1, v203
	ds_read_b128 v[216:219], v168
	ds_read_b128 v[230:233], v168 offset:1024
	ds_read_b128 v[234:237], v168 offset:2048
	ds_read_b128 v[238:241], v168 offset:3072
	s_waitcnt vmcnt(8)
	s_waitcnt lgkmcnt(0)
	v_mfma_f32_16x16x32_bf16 v[126:129], v[130:133], v[146:149], v[126:129]
	v_mfma_f32_16x16x32_bf16 v[122:125], v[138:141], v[146:149], v[122:125]
	v_mfma_f32_16x16x32_bf16 v[110:113], v[130:133], v[154:157], v[110:113]
	v_mfma_f32_16x16x32_bf16 v[106:109], v[138:141], v[154:157], v[106:109]
	s_barrier
	s_setprio 1
	v_mfma_f32_16x16x32_bf16 v[94:97], v[130:133], v[188:191], v[94:97]
	v_mfma_f32_16x16x32_bf16 v[90:93], v[138:141], v[188:191], v[90:93]
	v_mfma_f32_16x16x32_bf16 v[78:81], v[130:133], v[196:199], v[78:81]
	v_mfma_f32_16x16x32_bf16 v[74:77], v[138:141], v[196:199], v[74:77]
	v_mfma_f32_16x16x32_bf16 v[126:129], v[134:137], v[150:153], v[126:129]
	v_mfma_f32_16x16x32_bf16 v[122:125], v[142:145], v[150:153], v[122:125]
	v_mfma_f32_16x16x32_bf16 v[110:113], v[134:137], v[184:187], v[110:113]
	v_mfma_f32_16x16x32_bf16 v[106:109], v[142:145], v[184:187], v[106:109]
	v_mfma_f32_16x16x32_bf16 v[94:97], v[134:137], v[192:195], v[94:97]
	v_mfma_f32_16x16x32_bf16 v[90:93], v[142:145], v[192:195], v[90:93]
	v_mfma_f32_16x16x32_bf16 v[78:81], v[134:137], v[206:209], v[78:81]
	v_mfma_f32_16x16x32_bf16 v[74:77], v[142:145], v[206:209], v[74:77]
	v_mfma_f32_16x16x32_bf16 v[118:121], v[216:219], v[146:149], v[118:121]
	v_mfma_f32_16x16x32_bf16 v[114:117], v[234:237], v[146:149], v[114:117]
	v_mfma_f32_16x16x32_bf16 v[102:105], v[216:219], v[154:157], v[102:105]
	v_mfma_f32_16x16x32_bf16 v[98:101], v[234:237], v[154:157], v[98:101]
	v_mfma_f32_16x16x32_bf16 v[86:89], v[216:219], v[188:191], v[86:89]
	v_mfma_f32_16x16x32_bf16 v[82:85], v[234:237], v[188:191], v[82:85]
	v_mfma_f32_16x16x32_bf16 v[70:73], v[216:219], v[196:199], v[70:73]
	v_mfma_f32_16x16x32_bf16 v[66:69], v[234:237], v[196:199], v[66:69]
	v_mfma_f32_16x16x32_bf16 v[118:121], v[230:233], v[150:153], v[118:121]
	v_mfma_f32_16x16x32_bf16 v[114:117], v[238:241], v[150:153], v[114:117]
	v_mfma_f32_16x16x32_bf16 v[102:105], v[230:233], v[184:187], v[102:105]
	v_mfma_f32_16x16x32_bf16 v[98:101], v[238:241], v[184:187], v[98:101]
	v_mfma_f32_16x16x32_bf16 v[86:89], v[230:233], v[192:195], v[86:89]
	v_mfma_f32_16x16x32_bf16 v[82:85], v[238:241], v[192:195], v[82:85]
	v_mfma_f32_16x16x32_bf16 v[70:73], v[230:233], v[206:209], v[70:73]
	v_mfma_f32_16x16x32_bf16 v[66:69], v[238:241], v[206:209], v[66:69]
	s_setprio 0
	s_barrier
	ds_read_b128 v[146:149], v205 offset:16384
	ds_read_b128 v[150:153], v205 offset:17408
	ds_read_b128 v[154:157], v205 offset:18432
	ds_read_b128 v[184:187], v205 offset:19456
	ds_read_b128 v[188:191], v205 offset:20480
	ds_read_b128 v[192:195], v205 offset:21504
	ds_read_b128 v[196:199], v205 offset:22528
	ds_read_b128 v[206:209], v205 offset:23552
	s_add_i32 s22, s33, s20
	v_lshl_add_u64 v[176:177], s[46:47], 0, v[0:1]
	s_mov_b32 m0, s22
	s_nop 0
	global_load_lds_dwordx4 v[176:177], off
	v_lshl_add_u64 v[200:201], s[46:47], 0, v[158:159]
	s_add_i32 m0, s22, 0x2000
	s_nop 0
	global_load_lds_dwordx4 v[200:201], off
	s_mov_b32 m0, s21
	v_lshl_add_u64 v[220:221], s[30:31], 0, v[178:179]
	global_load_lds_dwordx4 v[220:221], off
	v_lshl_add_u64 v[242:243], s[30:31], 0, v[160:161]
	s_mov_b32 m0, s34
	s_nop 0
	global_load_lds_dwordx4 v[242:243], off
	s_add_u32 s46, s46, s6
	s_addc_u32 s47, s47, 0
	s_add_i32 s1, s1, s20
	v_lshl_add_u64 v[244:245], s[46:47], 0, v[0:1]
	s_mov_b32 m0, s1
	v_lshl_add_u64 v[246:247], s[46:47], 0, v[158:159]
	global_load_lds_dwordx4 v[244:245], off
	s_add_i32 m0, s1, 0x2000
	s_nop 0
	global_load_lds_dwordx4 v[246:247], off
	s_waitcnt vmcnt(8)
	s_waitcnt lgkmcnt(0)
	v_mfma_f32_16x16x32_bf16 v[62:65], v[130:133], v[146:149], v[62:65]
	v_mfma_f32_16x16x32_bf16 v[58:61], v[138:141], v[146:149], v[58:61]
	v_mfma_f32_16x16x32_bf16 v[46:49], v[130:133], v[154:157], v[46:49]
	v_mfma_f32_16x16x32_bf16 v[42:45], v[138:141], v[154:157], v[42:45]
	s_barrier
	s_setprio 1
	v_mfma_f32_16x16x32_bf16 v[30:33], v[130:133], v[188:191], v[30:33]
	v_mfma_f32_16x16x32_bf16 v[26:29], v[138:141], v[188:191], v[26:29]
	v_mfma_f32_16x16x32_bf16 v[14:17], v[130:133], v[196:199], v[14:17]
	v_mfma_f32_16x16x32_bf16 v[10:13], v[138:141], v[196:199], v[10:13]
	v_mfma_f32_16x16x32_bf16 v[62:65], v[134:137], v[150:153], v[62:65]
	v_mfma_f32_16x16x32_bf16 v[58:61], v[142:145], v[150:153], v[58:61]
	v_mfma_f32_16x16x32_bf16 v[46:49], v[134:137], v[184:187], v[46:49]
	v_mfma_f32_16x16x32_bf16 v[42:45], v[142:145], v[184:187], v[42:45]
	v_mfma_f32_16x16x32_bf16 v[30:33], v[134:137], v[192:195], v[30:33]
	v_mfma_f32_16x16x32_bf16 v[26:29], v[142:145], v[192:195], v[26:29]
	v_mfma_f32_16x16x32_bf16 v[14:17], v[134:137], v[206:209], v[14:17]
	v_mfma_f32_16x16x32_bf16 v[10:13], v[142:145], v[206:209], v[10:13]
	v_mfma_f32_16x16x32_bf16 v[54:57], v[216:219], v[146:149], v[54:57]
	v_mfma_f32_16x16x32_bf16 v[50:53], v[234:237], v[146:149], v[50:53]
	v_mfma_f32_16x16x32_bf16 v[38:41], v[216:219], v[154:157], v[38:41]
	v_mfma_f32_16x16x32_bf16 v[34:37], v[234:237], v[154:157], v[34:37]
	v_mfma_f32_16x16x32_bf16 v[22:25], v[216:219], v[188:191], v[22:25]
	v_mfma_f32_16x16x32_bf16 v[18:21], v[234:237], v[188:191], v[18:21]
	v_mfma_f32_16x16x32_bf16 v[6:9], v[216:219], v[196:199], v[6:9]
	v_mfma_f32_16x16x32_bf16 v[2:5], v[234:237], v[196:199], v[2:5]
	v_mfma_f32_16x16x32_bf16 v[54:57], v[230:233], v[150:153], v[54:57]
	v_mfma_f32_16x16x32_bf16 v[50:53], v[238:241], v[150:153], v[50:53]
	v_mfma_f32_16x16x32_bf16 v[38:41], v[230:233], v[184:187], v[38:41]
	v_mfma_f32_16x16x32_bf16 v[34:37], v[238:241], v[184:187], v[34:37]
	v_mfma_f32_16x16x32_bf16 v[22:25], v[230:233], v[192:195], v[22:25]
	v_mfma_f32_16x16x32_bf16 v[18:21], v[238:241], v[192:195], v[18:21]
	v_mfma_f32_16x16x32_bf16 v[6:9], v[230:233], v[206:209], v[6:9]
	v_mfma_f32_16x16x32_bf16 v[2:5], v[238:241], v[206:209], v[2:5]
	s_setprio 0
	s_barrier
	s_add_i32 s1, 0, 0x18000
	v_add_u32_e32 v142, s1, v203
	ds_read_b128 v[130:133], v142
	ds_read_b128 v[134:137], v142 offset:1024
	ds_read_b128 v[138:141], v142 offset:2048
	ds_read_b128 v[142:145], v142 offset:3072
	s_add_u32 s30, s30, s6
	s_addc_u32 s31, s31, 0
	s_mov_b32 m0, s63
	v_lshl_add_u64 v[216:217], s[30:31], 0, v[178:179]
	ds_read_b128 v[146:149], v205 offset:32768
	ds_read_b128 v[150:153], v205 offset:33792
	ds_read_b128 v[154:157], v205 offset:34816
	ds_read_b128 v[184:187], v205 offset:35840
	ds_read_b128 v[188:191], v205 offset:36864
	ds_read_b128 v[192:195], v205 offset:37888
	ds_read_b128 v[196:199], v205 offset:38912
	ds_read_b128 v[206:209], v205 offset:39936
	global_load_lds_dwordx4 v[216:217], off
	v_lshl_add_u64 v[216:217], s[30:31], 0, v[160:161]
	s_mov_b32 m0, s64
	s_nop 0
	global_load_lds_dwordx4 v[216:217], off
	s_add_i32 s22, 0, 0x1c000
	v_add_u32_e32 v168, s22, v203
	ds_read_b128 v[216:219], v168
	ds_read_b128 v[230:233], v168 offset:1024
	ds_read_b128 v[234:237], v168 offset:2048
	ds_read_b128 v[238:241], v168 offset:3072
	s_waitcnt vmcnt(8)
	s_waitcnt lgkmcnt(0)
	v_mfma_f32_16x16x32_bf16 v[126:129], v[130:133], v[146:149], v[126:129]
	v_mfma_f32_16x16x32_bf16 v[122:125], v[138:141], v[146:149], v[122:125]
	v_mfma_f32_16x16x32_bf16 v[110:113], v[130:133], v[154:157], v[110:113]
	v_mfma_f32_16x16x32_bf16 v[106:109], v[138:141], v[154:157], v[106:109]
	s_barrier
	s_setprio 1
	v_mfma_f32_16x16x32_bf16 v[94:97], v[130:133], v[188:191], v[94:97]
	v_mfma_f32_16x16x32_bf16 v[90:93], v[138:141], v[188:191], v[90:93]
	v_mfma_f32_16x16x32_bf16 v[78:81], v[130:133], v[196:199], v[78:81]
	v_mfma_f32_16x16x32_bf16 v[74:77], v[138:141], v[196:199], v[74:77]
	v_mfma_f32_16x16x32_bf16 v[126:129], v[134:137], v[150:153], v[126:129]
	v_mfma_f32_16x16x32_bf16 v[122:125], v[142:145], v[150:153], v[122:125]
	v_mfma_f32_16x16x32_bf16 v[110:113], v[134:137], v[184:187], v[110:113]
	v_mfma_f32_16x16x32_bf16 v[106:109], v[142:145], v[184:187], v[106:109]
	v_mfma_f32_16x16x32_bf16 v[94:97], v[134:137], v[192:195], v[94:97]
	v_mfma_f32_16x16x32_bf16 v[90:93], v[142:145], v[192:195], v[90:93]
	v_mfma_f32_16x16x32_bf16 v[78:81], v[134:137], v[206:209], v[78:81]
	v_mfma_f32_16x16x32_bf16 v[74:77], v[142:145], v[206:209], v[74:77]
	v_mfma_f32_16x16x32_bf16 v[118:121], v[216:219], v[146:149], v[118:121]
	v_mfma_f32_16x16x32_bf16 v[114:117], v[234:237], v[146:149], v[114:117]
	v_mfma_f32_16x16x32_bf16 v[102:105], v[216:219], v[154:157], v[102:105]
	v_mfma_f32_16x16x32_bf16 v[98:101], v[234:237], v[154:157], v[98:101]
	v_mfma_f32_16x16x32_bf16 v[86:89], v[216:219], v[188:191], v[86:89]
	v_mfma_f32_16x16x32_bf16 v[82:85], v[234:237], v[188:191], v[82:85]
	v_mfma_f32_16x16x32_bf16 v[70:73], v[216:219], v[196:199], v[70:73]
	v_mfma_f32_16x16x32_bf16 v[66:69], v[234:237], v[196:199], v[66:69]
	v_mfma_f32_16x16x32_bf16 v[118:121], v[230:233], v[150:153], v[118:121]
	v_mfma_f32_16x16x32_bf16 v[114:117], v[238:241], v[150:153], v[114:117]
	v_mfma_f32_16x16x32_bf16 v[102:105], v[230:233], v[184:187], v[102:105]
	v_mfma_f32_16x16x32_bf16 v[98:101], v[238:241], v[184:187], v[98:101]
	v_mfma_f32_16x16x32_bf16 v[86:89], v[230:233], v[192:195], v[86:89]
	v_mfma_f32_16x16x32_bf16 v[82:85], v[238:241], v[192:195], v[82:85]
	v_mfma_f32_16x16x32_bf16 v[70:73], v[230:233], v[206:209], v[70:73]
	v_mfma_f32_16x16x32_bf16 v[66:69], v[238:241], v[206:209], v[66:69]
	s_setprio 0
	s_barrier
	ds_read_b128 v[146:149], v205 offset:49152
	ds_read_b128 v[150:153], v205 offset:50176
	ds_read_b128 v[154:157], v205 offset:51200
	ds_read_b128 v[184:187], v205 offset:52224
	ds_read_b128 v[188:191], v205 offset:53248
	ds_read_b128 v[192:195], v205 offset:54272
	ds_read_b128 v[196:199], v205 offset:55296
	ds_read_b128 v[206:209], v205 offset:56320
	s_add_i32 s1, s1, s20
	v_lshl_add_u64 v[176:177], v[176:177], 0, s[12:13]
	s_mov_b32 m0, s1
	s_nop 0
	global_load_lds_dwordx4 v[176:177], off
	v_lshl_add_u64 v[176:177], v[200:201], 0, s[12:13]
	s_add_i32 m0, s1, 0x2000
	s_nop 0
	global_load_lds_dwordx4 v[176:177], off
	s_mov_b32 m0, s65
	v_lshl_add_u64 v[176:177], v[220:221], 0, s[12:13]
	global_load_lds_dwordx4 v[176:177], off
	v_lshl_add_u64 v[176:177], v[242:243], 0, s[12:13]
	s_mov_b32 m0, s66
	s_nop 0
	global_load_lds_dwordx4 v[176:177], off
	s_add_i32 s1, s22, s20
	v_lshl_add_u64 v[176:177], v[244:245], 0, s[12:13]
	s_mov_b32 m0, s1
	s_nop 0
	global_load_lds_dwordx4 v[176:177], off
	v_lshl_add_u64 v[176:177], v[246:247], 0, s[12:13]
	s_add_i32 m0, s1, 0x2000
	s_nop 0
	global_load_lds_dwordx4 v[176:177], off
	s_waitcnt vmcnt(8)
	s_waitcnt lgkmcnt(0)
	v_mfma_f32_16x16x32_bf16 v[62:65], v[130:133], v[146:149], v[62:65]
	v_mfma_f32_16x16x32_bf16 v[58:61], v[138:141], v[146:149], v[58:61]
	v_mfma_f32_16x16x32_bf16 v[46:49], v[130:133], v[154:157], v[46:49]
	v_mfma_f32_16x16x32_bf16 v[42:45], v[138:141], v[154:157], v[42:45]
	s_barrier
	s_setprio 1
	v_mfma_f32_16x16x32_bf16 v[30:33], v[130:133], v[188:191], v[30:33]
	v_mfma_f32_16x16x32_bf16 v[26:29], v[138:141], v[188:191], v[26:29]
	v_mfma_f32_16x16x32_bf16 v[14:17], v[130:133], v[196:199], v[14:17]
	v_mfma_f32_16x16x32_bf16 v[10:13], v[138:141], v[196:199], v[10:13]
	v_mfma_f32_16x16x32_bf16 v[62:65], v[134:137], v[150:153], v[62:65]
	v_mfma_f32_16x16x32_bf16 v[58:61], v[142:145], v[150:153], v[58:61]
	v_mfma_f32_16x16x32_bf16 v[46:49], v[134:137], v[184:187], v[46:49]
	v_mfma_f32_16x16x32_bf16 v[42:45], v[142:145], v[184:187], v[42:45]
	v_mfma_f32_16x16x32_bf16 v[30:33], v[134:137], v[192:195], v[30:33]
	v_mfma_f32_16x16x32_bf16 v[26:29], v[142:145], v[192:195], v[26:29]
	v_mfma_f32_16x16x32_bf16 v[14:17], v[134:137], v[206:209], v[14:17]
	v_mfma_f32_16x16x32_bf16 v[10:13], v[142:145], v[206:209], v[10:13]
	v_mfma_f32_16x16x32_bf16 v[54:57], v[216:219], v[146:149], v[54:57]
	v_mfma_f32_16x16x32_bf16 v[50:53], v[234:237], v[146:149], v[50:53]
	v_mfma_f32_16x16x32_bf16 v[38:41], v[216:219], v[154:157], v[38:41]
	v_mfma_f32_16x16x32_bf16 v[34:37], v[234:237], v[154:157], v[34:37]
	v_mfma_f32_16x16x32_bf16 v[22:25], v[216:219], v[188:191], v[22:25]
	v_mfma_f32_16x16x32_bf16 v[18:21], v[234:237], v[188:191], v[18:21]
	v_mfma_f32_16x16x32_bf16 v[6:9], v[216:219], v[196:199], v[6:9]
	v_mfma_f32_16x16x32_bf16 v[2:5], v[234:237], v[196:199], v[2:5]
	v_mfma_f32_16x16x32_bf16 v[54:57], v[230:233], v[150:153], v[54:57]
	v_mfma_f32_16x16x32_bf16 v[50:53], v[238:241], v[150:153], v[50:53]
	v_mfma_f32_16x16x32_bf16 v[38:41], v[230:233], v[184:187], v[38:41]
	v_mfma_f32_16x16x32_bf16 v[34:37], v[238:241], v[184:187], v[34:37]
	v_mfma_f32_16x16x32_bf16 v[22:25], v[230:233], v[192:195], v[22:25]
	v_mfma_f32_16x16x32_bf16 v[18:21], v[238:241], v[192:195], v[18:21]
	v_mfma_f32_16x16x32_bf16 v[6:9], v[230:233], v[206:209], v[6:9]
	v_mfma_f32_16x16x32_bf16 v[2:5], v[238:241], v[206:209], v[2:5]
	s_setprio 0
	s_add_u32 s36, s36, 0x100
	s_addc_u32 s37, s37, 0
	s_add_u32 s48, s48, 0x100
	s_addc_u32 s49, s49, 0
	s_cmp_ge_u32 s23, s68
	s_mov_b32 s22, s23
	s_barrier
	s_cbranch_scc0 .LBB0_120
	s_cmpk_gt_u32 s16, 0xff
	s_cbranch_scc1 .Lrs_i3_post
	s_barrier

.Lrs_i4_pre:
	s_add_i32 s23, s22, 2
	s_add_u32 s1, s36, 0x80
	s_addc_u32 s30, s37, 0
	s_add_i32 s33, 0, 0x10000
	v_add_u32_e32 v142, s33, v181
	ds_read_b128 v[130:133], v142
	ds_read_b128 v[134:137], v142 offset:1024
	ds_read_b128 v[138:141], v142 offset:2048
	ds_read_b128 v[142:145], v142 offset:3072
	s_cmp_eq_u32 s68, s22
	s_cselect_b32 s31, s27, s30
	s_cselect_b32 s30, s26, s1
	s_cselect_b32 s47, s29, s49
	s_cselect_b32 s46, s28, s48
	v_lshl_add_u64 v[160:161], s[36:37], 0, v[152:153]
	s_add_i32 m0, s21, 0xc000
	ds_read_b128 v[156:159], v183
	ds_read_b128 v[184:187], v183 offset:1024
	ds_read_b128 v[188:191], v183 offset:2048
	ds_read_b128 v[192:195], v183 offset:3072
	ds_read_b128 v[196:199], v183 offset:4096
	ds_read_b128 v[200:203], v183 offset:5120
	ds_read_b128 v[204:207], v183 offset:6144
	ds_read_b128 v[216:219], v183 offset:7168
	global_load_lds_dwordx4 v[160:161], off
	v_lshl_add_u64 v[160:161], s[36:37], 0, v[154:155]
	s_add_i32 m0, s21, 0xe000
	s_nop 0
	global_load_lds_dwordx4 v[160:161], off
	s_add_i32 s1, 0, 0x14000
	v_add_u32_e32 v160, s1, v181
	ds_read_b128 v[230:233], v160
	ds_read_b128 v[234:237], v160 offset:1024
	ds_read_b128 v[238:241], v160 offset:2048
	ds_read_b128 v[242:245], v160 offset:3072
	s_waitcnt vmcnt(8)
	s_waitcnt lgkmcnt(0)
	v_mfma_f32_16x16x32_bf16 v[126:129], v[130:133], v[156:159], 0
	v_mfma_f32_16x16x32_bf16 v[122:125], v[138:141], v[156:159], 0
	v_mfma_f32_16x16x32_bf16 v[110:113], v[130:133], v[188:191], 0
	v_mfma_f32_16x16x32_bf16 v[106:109], v[138:141], v[188:191], 0
	s_barrier
	s_setprio 1
	v_mfma_f32_16x16x32_bf16 v[94:97], v[130:133], v[196:199], 0
	v_mfma_f32_16x16x32_bf16 v[90:93], v[138:141], v[196:199], 0
	v_mfma_f32_16x16x32_bf16 v[78:81], v[130:133], v[204:207], 0
	v_mfma_f32_16x16x32_bf16 v[74:77], v[138:141], v[204:207], 0
	v_mfma_f32_16x16x32_bf16 v[126:129], v[134:137], v[184:187], v[126:129]
	v_mfma_f32_16x16x32_bf16 v[122:125], v[142:145], v[184:187], v[122:125]
	v_mfma_f32_16x16x32_bf16 v[110:113], v[134:137], v[192:195], v[110:113]
	v_mfma_f32_16x16x32_bf16 v[106:109], v[142:145], v[192:195], v[106:109]
	v_mfma_f32_16x16x32_bf16 v[94:97], v[134:137], v[200:203], v[94:97]
	v_mfma_f32_16x16x32_bf16 v[90:93], v[142:145], v[200:203], v[90:93]
	v_mfma_f32_16x16x32_bf16 v[78:81], v[134:137], v[216:219], v[78:81]
	v_mfma_f32_16x16x32_bf16 v[74:77], v[142:145], v[216:219], v[74:77]
	v_mfma_f32_16x16x32_bf16 v[118:121], v[230:233], v[156:159], 0
	v_mfma_f32_16x16x32_bf16 v[114:117], v[238:241], v[156:159], 0
	v_mfma_f32_16x16x32_bf16 v[102:105], v[230:233], v[188:191], 0
	v_mfma_f32_16x16x32_bf16 v[98:101], v[238:241], v[188:191], 0
	v_mfma_f32_16x16x32_bf16 v[86:89], v[230:233], v[196:199], 0
	v_mfma_f32_16x16x32_bf16 v[82:85], v[238:241], v[196:199], 0
	v_mfma_f32_16x16x32_bf16 v[70:73], v[230:233], v[204:207], 0
	v_mfma_f32_16x16x32_bf16 v[66:69], v[238:241], v[204:207], 0
	v_mfma_f32_16x16x32_bf16 v[118:121], v[234:237], v[184:187], v[118:121]
	v_mfma_f32_16x16x32_bf16 v[114:117], v[242:245], v[184:187], v[114:117]
	v_mfma_f32_16x16x32_bf16 v[102:105], v[234:237], v[192:195], v[102:105]
	v_mfma_f32_16x16x32_bf16 v[98:101], v[242:245], v[192:195], v[98:101]
	v_mfma_f32_16x16x32_bf16 v[86:89], v[234:237], v[200:203], v[86:89]
	v_mfma_f32_16x16x32_bf16 v[82:85], v[242:245], v[200:203], v[82:85]
	v_mfma_f32_16x16x32_bf16 v[70:73], v[234:237], v[216:219], v[70:73]
	v_mfma_f32_16x16x32_bf16 v[66:69], v[242:245], v[216:219], v[66:69]
	s_setprio 0
	s_barrier
	ds_read_b128 v[156:159], v183 offset:16384
	ds_read_b128 v[184:187], v183 offset:17408
	ds_read_b128 v[188:191], v183 offset:18432
	ds_read_b128 v[192:195], v183 offset:19456
	ds_read_b128 v[196:199], v183 offset:20480
	ds_read_b128 v[200:203], v183 offset:21504
	ds_read_b128 v[204:207], v183 offset:22528
	ds_read_b128 v[216:219], v183 offset:23552
	s_add_i32 s22, s33, s20
	v_lshl_add_u64 v[160:161], s[46:47], 0, v[0:1]
	s_mov_b32 m0, s22
	v_lshl_add_u64 v[176:177], s[46:47], 0, v[146:147]
	global_load_lds_dwordx4 v[160:161], off
	s_add_i32 m0, s22, 0x2000
	s_nop 0
	global_load_lds_dwordx4 v[176:177], off
	s_mov_b32 m0, s21
	v_lshl_add_u64 v[178:179], s[30:31], 0, v[150:151]
	global_load_lds_dwordx4 v[178:179], off
	v_lshl_add_u64 v[208:209], s[30:31], 0, v[148:149]
	s_mov_b32 m0, s34
	s_nop 0
	global_load_lds_dwordx4 v[208:209], off
	s_add_u32 s46, s46, s6
	s_addc_u32 s47, s47, 0
	s_add_i32 s1, s1, s20
	v_lshl_add_u64 v[220:221], s[46:47], 0, v[0:1]
	s_mov_b32 m0, s1
	v_lshl_add_u64 v[246:247], s[46:47], 0, v[146:147]
	global_load_lds_dwordx4 v[220:221], off
	s_add_i32 m0, s1, 0x2000
	s_nop 0
	global_load_lds_dwordx4 v[246:247], off
	s_waitcnt vmcnt(8)
	s_waitcnt lgkmcnt(0)
	v_mfma_f32_16x16x32_bf16 v[62:65], v[130:133], v[156:159], 0
	v_mfma_f32_16x16x32_bf16 v[58:61], v[138:141], v[156:159], 0
	v_mfma_f32_16x16x32_bf16 v[46:49], v[130:133], v[188:191], 0
	v_mfma_f32_16x16x32_bf16 v[42:45], v[138:141], v[188:191], 0
	s_barrier
	s_setprio 1
	v_mfma_f32_16x16x32_bf16 v[30:33], v[130:133], v[196:199], 0
	v_mfma_f32_16x16x32_bf16 v[26:29], v[138:141], v[196:199], 0
	v_mfma_f32_16x16x32_bf16 v[14:17], v[130:133], v[204:207], 0
	v_mfma_f32_16x16x32_bf16 v[10:13], v[138:141], v[204:207], 0
	v_mfma_f32_16x16x32_bf16 v[62:65], v[134:137], v[184:187], v[62:65]
	v_mfma_f32_16x16x32_bf16 v[58:61], v[142:145], v[184:187], v[58:61]
	v_mfma_f32_16x16x32_bf16 v[46:49], v[134:137], v[192:195], v[46:49]
	v_mfma_f32_16x16x32_bf16 v[42:45], v[142:145], v[192:195], v[42:45]
	v_mfma_f32_16x16x32_bf16 v[30:33], v[134:137], v[200:203], v[30:33]
	v_mfma_f32_16x16x32_bf16 v[26:29], v[142:145], v[200:203], v[26:29]
	v_mfma_f32_16x16x32_bf16 v[14:17], v[134:137], v[216:219], v[14:17]
	v_mfma_f32_16x16x32_bf16 v[10:13], v[142:145], v[216:219], v[10:13]
	v_mfma_f32_16x16x32_bf16 v[54:57], v[230:233], v[156:159], 0
	v_mfma_f32_16x16x32_bf16 v[50:53], v[238:241], v[156:159], 0
	v_mfma_f32_16x16x32_bf16 v[38:41], v[230:233], v[188:191], 0
	v_mfma_f32_16x16x32_bf16 v[34:37], v[238:241], v[188:191], 0
	v_mfma_f32_16x16x32_bf16 v[22:25], v[230:233], v[196:199], 0
	v_mfma_f32_16x16x32_bf16 v[18:21], v[238:241], v[196:199], 0
	v_mfma_f32_16x16x32_bf16 v[6:9], v[230:233], v[204:207], 0
	v_mfma_f32_16x16x32_bf16 v[2:5], v[238:241], v[204:207], 0
	v_mfma_f32_16x16x32_bf16 v[54:57], v[234:237], v[184:187], v[54:57]
	v_mfma_f32_16x16x32_bf16 v[50:53], v[242:245], v[184:187], v[50:53]
	v_mfma_f32_16x16x32_bf16 v[38:41], v[234:237], v[192:195], v[38:41]
	v_mfma_f32_16x16x32_bf16 v[34:37], v[242:245], v[192:195], v[34:37]
	v_mfma_f32_16x16x32_bf16 v[22:25], v[234:237], v[200:203], v[22:25]
	v_mfma_f32_16x16x32_bf16 v[18:21], v[242:245], v[200:203], v[18:21]
	v_mfma_f32_16x16x32_bf16 v[6:9], v[234:237], v[216:219], v[6:9]
	v_mfma_f32_16x16x32_bf16 v[2:5], v[242:245], v[216:219], v[2:5]
	s_setprio 0
	s_barrier
	s_add_i32 s1, 0, 0x18000
	v_add_u32_e32 v142, s1, v181
	ds_read_b128 v[130:133], v142
	ds_read_b128 v[134:137], v142 offset:1024
	ds_read_b128 v[138:141], v142 offset:2048
	ds_read_b128 v[142:145], v142 offset:3072
	s_add_u32 s30, s30, s6
	s_addc_u32 s31, s31, 0
	s_mov_b32 m0, s63
	v_lshl_add_u64 v[230:231], s[30:31], 0, v[150:151]
	ds_read_b128 v[156:159], v183 offset:32768
	ds_read_b128 v[184:187], v183 offset:33792
	ds_read_b128 v[188:191], v183 offset:34816
	ds_read_b128 v[192:195], v183 offset:35840
	ds_read_b128 v[196:199], v183 offset:36864
	ds_read_b128 v[200:203], v183 offset:37888
	ds_read_b128 v[204:207], v183 offset:38912
	ds_read_b128 v[216:219], v183 offset:39936
	global_load_lds_dwordx4 v[230:231], off
	v_lshl_add_u64 v[230:231], s[30:31], 0, v[148:149]
	s_mov_b32 m0, s64
	s_nop 0
	global_load_lds_dwordx4 v[230:231], off
	s_add_i32 s22, 0, 0x1c000
	v_add_u32_e32 v168, s22, v181
	ds_read_b128 v[230:233], v168
	ds_read_b128 v[234:237], v168 offset:1024
	ds_read_b128 v[238:241], v168 offset:2048
	ds_read_b128 v[242:245], v168 offset:3072
	s_waitcnt vmcnt(8)
	s_waitcnt lgkmcnt(0)
	v_mfma_f32_16x16x32_bf16 v[126:129], v[130:133], v[156:159], v[126:129]
	v_mfma_f32_16x16x32_bf16 v[122:125], v[138:141], v[156:159], v[122:125]
	v_mfma_f32_16x16x32_bf16 v[110:113], v[130:133], v[188:191], v[110:113]
	v_mfma_f32_16x16x32_bf16 v[106:109], v[138:141], v[188:191], v[106:109]
	s_barrier
	s_setprio 1
	v_mfma_f32_16x16x32_bf16 v[94:97], v[130:133], v[196:199], v[94:97]
	v_mfma_f32_16x16x32_bf16 v[90:93], v[138:141], v[196:199], v[90:93]
	v_mfma_f32_16x16x32_bf16 v[78:81], v[130:133], v[204:207], v[78:81]
	v_mfma_f32_16x16x32_bf16 v[74:77], v[138:141], v[204:207], v[74:77]
	v_mfma_f32_16x16x32_bf16 v[126:129], v[134:137], v[184:187], v[126:129]
	v_mfma_f32_16x16x32_bf16 v[122:125], v[142:145], v[184:187], v[122:125]
	v_mfma_f32_16x16x32_bf16 v[110:113], v[134:137], v[192:195], v[110:113]
	v_mfma_f32_16x16x32_bf16 v[106:109], v[142:145], v[192:195], v[106:109]
	v_mfma_f32_16x16x32_bf16 v[94:97], v[134:137], v[200:203], v[94:97]
	v_mfma_f32_16x16x32_bf16 v[90:93], v[142:145], v[200:203], v[90:93]
	v_mfma_f32_16x16x32_bf16 v[78:81], v[134:137], v[216:219], v[78:81]
	v_mfma_f32_16x16x32_bf16 v[74:77], v[142:145], v[216:219], v[74:77]
	v_mfma_f32_16x16x32_bf16 v[118:121], v[230:233], v[156:159], v[118:121]
	v_mfma_f32_16x16x32_bf16 v[114:117], v[238:241], v[156:159], v[114:117]
	v_mfma_f32_16x16x32_bf16 v[102:105], v[230:233], v[188:191], v[102:105]
	v_mfma_f32_16x16x32_bf16 v[98:101], v[238:241], v[188:191], v[98:101]
	v_mfma_f32_16x16x32_bf16 v[86:89], v[230:233], v[196:199], v[86:89]
	v_mfma_f32_16x16x32_bf16 v[82:85], v[238:241], v[196:199], v[82:85]
	v_mfma_f32_16x16x32_bf16 v[70:73], v[230:233], v[204:207], v[70:73]
	v_mfma_f32_16x16x32_bf16 v[66:69], v[238:241], v[204:207], v[66:69]
	v_mfma_f32_16x16x32_bf16 v[118:121], v[234:237], v[184:187], v[118:121]
	v_mfma_f32_16x16x32_bf16 v[114:117], v[242:245], v[184:187], v[114:117]
	v_mfma_f32_16x16x32_bf16 v[102:105], v[234:237], v[192:195], v[102:105]
	v_mfma_f32_16x16x32_bf16 v[98:101], v[242:245], v[192:195], v[98:101]
	v_mfma_f32_16x16x32_bf16 v[86:89], v[234:237], v[200:203], v[86:89]
	v_mfma_f32_16x16x32_bf16 v[82:85], v[242:245], v[200:203], v[82:85]
	v_mfma_f32_16x16x32_bf16 v[70:73], v[234:237], v[216:219], v[70:73]
	v_mfma_f32_16x16x32_bf16 v[66:69], v[242:245], v[216:219], v[66:69]
	s_setprio 0
	s_barrier
	ds_read_b128 v[156:159], v183 offset:49152
	ds_read_b128 v[184:187], v183 offset:50176
	ds_read_b128 v[188:191], v183 offset:51200
	ds_read_b128 v[192:195], v183 offset:52224
	ds_read_b128 v[196:199], v183 offset:53248
	ds_read_b128 v[200:203], v183 offset:54272
	ds_read_b128 v[204:207], v183 offset:55296
	ds_read_b128 v[216:219], v183 offset:56320
	s_add_i32 s1, s1, s20
	v_lshl_add_u64 v[160:161], v[160:161], 0, s[12:13]
	s_mov_b32 m0, s1
	s_nop 0
	global_load_lds_dwordx4 v[160:161], off
	v_lshl_add_u64 v[160:161], v[176:177], 0, s[12:13]
	s_add_i32 m0, s1, 0x2000
	s_nop 0
	global_load_lds_dwordx4 v[160:161], off
	s_mov_b32 m0, s65
	v_lshl_add_u64 v[160:161], v[178:179], 0, s[12:13]
	global_load_lds_dwordx4 v[160:161], off
	v_lshl_add_u64 v[160:161], v[208:209], 0, s[12:13]
	s_mov_b32 m0, s66
	s_nop 0
	global_load_lds_dwordx4 v[160:161], off
	s_add_i32 s1, s22, s20
	v_lshl_add_u64 v[160:161], v[220:221], 0, s[12:13]
	s_mov_b32 m0, s1
	s_nop 0
	global_load_lds_dwordx4 v[160:161], off
	v_lshl_add_u64 v[160:161], v[246:247], 0, s[12:13]
	s_add_i32 m0, s1, 0x2000
	s_nop 0
	global_load_lds_dwordx4 v[160:161], off
	s_waitcnt vmcnt(8)
	s_waitcnt lgkmcnt(0)
	v_mfma_f32_16x16x32_bf16 v[62:65], v[130:133], v[156:159], v[62:65]
	v_mfma_f32_16x16x32_bf16 v[58:61], v[138:141], v[156:159], v[58:61]
	v_mfma_f32_16x16x32_bf16 v[46:49], v[130:133], v[188:191], v[46:49]
	v_mfma_f32_16x16x32_bf16 v[42:45], v[138:141], v[188:191], v[42:45]
	s_barrier
	s_setprio 1
	v_mfma_f32_16x16x32_bf16 v[30:33], v[130:133], v[196:199], v[30:33]
	v_mfma_f32_16x16x32_bf16 v[26:29], v[138:141], v[196:199], v[26:29]
	v_mfma_f32_16x16x32_bf16 v[14:17], v[130:133], v[204:207], v[14:17]
	v_mfma_f32_16x16x32_bf16 v[10:13], v[138:141], v[204:207], v[10:13]
	v_mfma_f32_16x16x32_bf16 v[62:65], v[134:137], v[184:187], v[62:65]
	v_mfma_f32_16x16x32_bf16 v[58:61], v[142:145], v[184:187], v[58:61]
	v_mfma_f32_16x16x32_bf16 v[46:49], v[134:137], v[192:195], v[46:49]
	v_mfma_f32_16x16x32_bf16 v[42:45], v[142:145], v[192:195], v[42:45]
	v_mfma_f32_16x16x32_bf16 v[30:33], v[134:137], v[200:203], v[30:33]
	v_mfma_f32_16x16x32_bf16 v[26:29], v[142:145], v[200:203], v[26:29]
	v_mfma_f32_16x16x32_bf16 v[14:17], v[134:137], v[216:219], v[14:17]
	v_mfma_f32_16x16x32_bf16 v[10:13], v[142:145], v[216:219], v[10:13]
	v_mfma_f32_16x16x32_bf16 v[54:57], v[230:233], v[156:159], v[54:57]
	v_mfma_f32_16x16x32_bf16 v[50:53], v[238:241], v[156:159], v[50:53]
	v_mfma_f32_16x16x32_bf16 v[38:41], v[230:233], v[188:191], v[38:41]
	v_mfma_f32_16x16x32_bf16 v[34:37], v[238:241], v[188:191], v[34:37]
	v_mfma_f32_16x16x32_bf16 v[22:25], v[230:233], v[196:199], v[22:25]
	v_mfma_f32_16x16x32_bf16 v[18:21], v[238:241], v[196:199], v[18:21]
	v_mfma_f32_16x16x32_bf16 v[6:9], v[230:233], v[204:207], v[6:9]
	v_mfma_f32_16x16x32_bf16 v[2:5], v[238:241], v[204:207], v[2:5]
	v_mfma_f32_16x16x32_bf16 v[54:57], v[234:237], v[184:187], v[54:57]
	v_mfma_f32_16x16x32_bf16 v[50:53], v[242:245], v[184:187], v[50:53]
	v_mfma_f32_16x16x32_bf16 v[38:41], v[234:237], v[192:195], v[38:41]
	v_mfma_f32_16x16x32_bf16 v[34:37], v[242:245], v[192:195], v[34:37]
	v_mfma_f32_16x16x32_bf16 v[22:25], v[234:237], v[200:203], v[22:25]
	v_mfma_f32_16x16x32_bf16 v[18:21], v[242:245], v[200:203], v[18:21]
	v_mfma_f32_16x16x32_bf16 v[6:9], v[234:237], v[216:219], v[6:9]
	v_mfma_f32_16x16x32_bf16 v[2:5], v[242:245], v[216:219], v[2:5]
	s_setprio 0
	s_add_u32 s36, s36, 0x100
	s_addc_u32 s37, s37, 0
	s_add_u32 s48, s48, 0x100
	s_addc_u32 s49, s49, 0
	s_cmp_ge_u32 s23, s0
	s_mov_b32 s22, s23
	s_barrier
.LBB0_159:
	s_add_i32 s23, s22, 2
	s_add_u32 s1, s36, 0x80
	s_addc_u32 s30, s37, 0
	s_add_i32 s33, 0, 0x10000
	v_add_u32_e32 v142, s33, v181
	ds_read_b128 v[130:133], v142
	ds_read_b128 v[134:137], v142 offset:1024
	ds_read_b128 v[138:141], v142 offset:2048
	ds_read_b128 v[142:145], v142 offset:3072
	s_cmp_eq_u32 s68, s22
	s_cselect_b32 s31, s27, s30
	s_cselect_b32 s30, s26, s1
	s_cselect_b32 s47, s29, s49
	s_cselect_b32 s46, s28, s48
	v_lshl_add_u64 v[160:161], s[36:37], 0, v[152:153]
	s_add_i32 m0, s21, 0xc000
	ds_read_b128 v[156:159], v183
	ds_read_b128 v[184:187], v183 offset:1024
	ds_read_b128 v[188:191], v183 offset:2048
	ds_read_b128 v[192:195], v183 offset:3072
	ds_read_b128 v[196:199], v183 offset:4096
	ds_read_b128 v[200:203], v183 offset:5120
	ds_read_b128 v[204:207], v183 offset:6144
	ds_read_b128 v[216:219], v183 offset:7168
	global_load_lds_dwordx4 v[160:161], off
	v_lshl_add_u64 v[160:161], s[36:37], 0, v[154:155]
	s_add_i32 m0, s21, 0xe000
	s_nop 0
	global_load_lds_dwordx4 v[160:161], off
	s_add_i32 s1, 0, 0x14000
	v_add_u32_e32 v160, s1, v181
	ds_read_b128 v[230:233], v160
	ds_read_b128 v[234:237], v160 offset:1024
	ds_read_b128 v[238:241], v160 offset:2048
	ds_read_b128 v[242:245], v160 offset:3072
	s_waitcnt vmcnt(8)
	s_waitcnt lgkmcnt(0)
	v_mfma_f32_16x16x32_bf16 v[126:129], v[130:133], v[156:159], v[126:129]
	v_mfma_f32_16x16x32_bf16 v[122:125], v[138:141], v[156:159], v[122:125]
	v_mfma_f32_16x16x32_bf16 v[110:113], v[130:133], v[188:191], v[110:113]
	v_mfma_f32_16x16x32_bf16 v[106:109], v[138:141], v[188:191], v[106:109]
	s_barrier
	s_setprio 1
	v_mfma_f32_16x16x32_bf16 v[94:97], v[130:133], v[196:199], v[94:97]
	v_mfma_f32_16x16x32_bf16 v[90:93], v[138:141], v[196:199], v[90:93]
	v_mfma_f32_16x16x32_bf16 v[78:81], v[130:133], v[204:207], v[78:81]
	v_mfma_f32_16x16x32_bf16 v[74:77], v[138:141], v[204:207], v[74:77]
	v_mfma_f32_16x16x32_bf16 v[126:129], v[134:137], v[184:187], v[126:129]
	v_mfma_f32_16x16x32_bf16 v[122:125], v[142:145], v[184:187], v[122:125]
	v_mfma_f32_16x16x32_bf16 v[110:113], v[134:137], v[192:195], v[110:113]
	v_mfma_f32_16x16x32_bf16 v[106:109], v[142:145], v[192:195], v[106:109]
	v_mfma_f32_16x16x32_bf16 v[94:97], v[134:137], v[200:203], v[94:97]
	v_mfma_f32_16x16x32_bf16 v[90:93], v[142:145], v[200:203], v[90:93]
	v_mfma_f32_16x16x32_bf16 v[78:81], v[134:137], v[216:219], v[78:81]
	v_mfma_f32_16x16x32_bf16 v[74:77], v[142:145], v[216:219], v[74:77]
	v_mfma_f32_16x16x32_bf16 v[118:121], v[230:233], v[156:159], v[118:121]
	v_mfma_f32_16x16x32_bf16 v[114:117], v[238:241], v[156:159], v[114:117]
	v_mfma_f32_16x16x32_bf16 v[102:105], v[230:233], v[188:191], v[102:105]
	v_mfma_f32_16x16x32_bf16 v[98:101], v[238:241], v[188:191], v[98:101]
	v_mfma_f32_16x16x32_bf16 v[86:89], v[230:233], v[196:199], v[86:89]
	v_mfma_f32_16x16x32_bf16 v[82:85], v[238:241], v[196:199], v[82:85]
	v_mfma_f32_16x16x32_bf16 v[70:73], v[230:233], v[204:207], v[70:73]
	v_mfma_f32_16x16x32_bf16 v[66:69], v[238:241], v[204:207], v[66:69]
	v_mfma_f32_16x16x32_bf16 v[118:121], v[234:237], v[184:187], v[118:121]
	v_mfma_f32_16x16x32_bf16 v[114:117], v[242:245], v[184:187], v[114:117]
	v_mfma_f32_16x16x32_bf16 v[102:105], v[234:237], v[192:195], v[102:105]
	v_mfma_f32_16x16x32_bf16 v[98:101], v[242:245], v[192:195], v[98:101]
	v_mfma_f32_16x16x32_bf16 v[86:89], v[234:237], v[200:203], v[86:89]
	v_mfma_f32_16x16x32_bf16 v[82:85], v[242:245], v[200:203], v[82:85]
	v_mfma_f32_16x16x32_bf16 v[70:73], v[234:237], v[216:219], v[70:73]
	v_mfma_f32_16x16x32_bf16 v[66:69], v[242:245], v[216:219], v[66:69]
	s_setprio 0
	s_barrier
	ds_read_b128 v[156:159], v183 offset:16384
	ds_read_b128 v[184:187], v183 offset:17408
	ds_read_b128 v[188:191], v183 offset:18432
	ds_read_b128 v[192:195], v183 offset:19456
	ds_read_b128 v[196:199], v183 offset:20480
	ds_read_b128 v[200:203], v183 offset:21504
	ds_read_b128 v[204:207], v183 offset:22528
	ds_read_b128 v[216:219], v183 offset:23552
	s_add_i32 s22, s33, s20
	v_lshl_add_u64 v[160:161], s[46:47], 0, v[0:1]
	s_mov_b32 m0, s22
	v_lshl_add_u64 v[176:177], s[46:47], 0, v[146:147]
	global_load_lds_dwordx4 v[160:161], off
	s_add_i32 m0, s22, 0x2000
	s_nop 0
	global_load_lds_dwordx4 v[176:177], off
	s_mov_b32 m0, s21
	v_lshl_add_u64 v[178:179], s[30:31], 0, v[150:151]
	global_load_lds_dwordx4 v[178:179], off
	v_lshl_add_u64 v[208:209], s[30:31], 0, v[148:149]
	s_mov_b32 m0, s34
	s_nop 0
	global_load_lds_dwordx4 v[208:209], off
	s_add_u32 s46, s46, s6
	s_addc_u32 s47, s47, 0
	s_add_i32 s1, s1, s20
	v_lshl_add_u64 v[220:221], s[46:47], 0, v[0:1]
	s_mov_b32 m0, s1
	v_lshl_add_u64 v[246:247], s[46:47], 0, v[146:147]
	global_load_lds_dwordx4 v[220:221], off
	s_add_i32 m0, s1, 0x2000
	s_nop 0
	global_load_lds_dwordx4 v[246:247], off
	s_waitcnt vmcnt(8)
	s_waitcnt lgkmcnt(0)
	v_mfma_f32_16x16x32_bf16 v[62:65], v[130:133], v[156:159], v[62:65]
	v_mfma_f32_16x16x32_bf16 v[58:61], v[138:141], v[156:159], v[58:61]
	v_mfma_f32_16x16x32_bf16 v[46:49], v[130:133], v[188:191], v[46:49]
	v_mfma_f32_16x16x32_bf16 v[42:45], v[138:141], v[188:191], v[42:45]
	s_barrier
	s_setprio 1
	v_mfma_f32_16x16x32_bf16 v[30:33], v[130:133], v[196:199], v[30:33]
	v_mfma_f32_16x16x32_bf16 v[26:29], v[138:141], v[196:199], v[26:29]
	v_mfma_f32_16x16x32_bf16 v[14:17], v[130:133], v[204:207], v[14:17]
	v_mfma_f32_16x16x32_bf16 v[10:13], v[138:141], v[204:207], v[10:13]
	v_mfma_f32_16x16x32_bf16 v[62:65], v[134:137], v[184:187], v[62:65]
	v_mfma_f32_16x16x32_bf16 v[58:61], v[142:145], v[184:187], v[58:61]
	v_mfma_f32_16x16x32_bf16 v[46:49], v[134:137], v[192:195], v[46:49]
	v_mfma_f32_16x16x32_bf16 v[42:45], v[142:145], v[192:195], v[42:45]
	v_mfma_f32_16x16x32_bf16 v[30:33], v[134:137], v[200:203], v[30:33]
	v_mfma_f32_16x16x32_bf16 v[26:29], v[142:145], v[200:203], v[26:29]
	v_mfma_f32_16x16x32_bf16 v[14:17], v[134:137], v[216:219], v[14:17]
	v_mfma_f32_16x16x32_bf16 v[10:13], v[142:145], v[216:219], v[10:13]
	v_mfma_f32_16x16x32_bf16 v[54:57], v[230:233], v[156:159], v[54:57]
	v_mfma_f32_16x16x32_bf16 v[50:53], v[238:241], v[156:159], v[50:53]
	v_mfma_f32_16x16x32_bf16 v[38:41], v[230:233], v[188:191], v[38:41]
	v_mfma_f32_16x16x32_bf16 v[34:37], v[238:241], v[188:191], v[34:37]
	v_mfma_f32_16x16x32_bf16 v[22:25], v[230:233], v[196:199], v[22:25]
	v_mfma_f32_16x16x32_bf16 v[18:21], v[238:241], v[196:199], v[18:21]
	v_mfma_f32_16x16x32_bf16 v[6:9], v[230:233], v[204:207], v[6:9]
	v_mfma_f32_16x16x32_bf16 v[2:5], v[238:241], v[204:207], v[2:5]
	v_mfma_f32_16x16x32_bf16 v[54:57], v[234:237], v[184:187], v[54:57]
	v_mfma_f32_16x16x32_bf16 v[50:53], v[242:245], v[184:187], v[50:53]
	v_mfma_f32_16x16x32_bf16 v[38:41], v[234:237], v[192:195], v[38:41]
	v_mfma_f32_16x16x32_bf16 v[34:37], v[242:245], v[192:195], v[34:37]
	v_mfma_f32_16x16x32_bf16 v[22:25], v[234:237], v[200:203], v[22:25]
	v_mfma_f32_16x16x32_bf16 v[18:21], v[242:245], v[200:203], v[18:21]
	v_mfma_f32_16x16x32_bf16 v[6:9], v[234:237], v[216:219], v[6:9]
	v_mfma_f32_16x16x32_bf16 v[2:5], v[242:245], v[216:219], v[2:5]
	s_setprio 0
	s_barrier
	s_add_i32 s1, 0, 0x18000
	v_add_u32_e32 v142, s1, v181
	ds_read_b128 v[130:133], v142
	ds_read_b128 v[134:137], v142 offset:1024
	ds_read_b128 v[138:141], v142 offset:2048
	ds_read_b128 v[142:145], v142 offset:3072
	s_add_u32 s30, s30, s6
	s_addc_u32 s31, s31, 0
	s_mov_b32 m0, s63
	v_lshl_add_u64 v[230:231], s[30:31], 0, v[150:151]
	ds_read_b128 v[156:159], v183 offset:32768
	ds_read_b128 v[184:187], v183 offset:33792
	ds_read_b128 v[188:191], v183 offset:34816
	ds_read_b128 v[192:195], v183 offset:35840
	ds_read_b128 v[196:199], v183 offset:36864
	ds_read_b128 v[200:203], v183 offset:37888
	ds_read_b128 v[204:207], v183 offset:38912
	ds_read_b128 v[216:219], v183 offset:39936
	global_load_lds_dwordx4 v[230:231], off
	v_lshl_add_u64 v[230:231], s[30:31], 0, v[148:149]
	s_mov_b32 m0, s64
	s_nop 0
	global_load_lds_dwordx4 v[230:231], off
	s_add_i32 s22, 0, 0x1c000
	v_add_u32_e32 v168, s22, v181
	ds_read_b128 v[230:233], v168
	ds_read_b128 v[234:237], v168 offset:1024
	ds_read_b128 v[238:241], v168 offset:2048
	ds_read_b128 v[242:245], v168 offset:3072
	s_waitcnt vmcnt(8)
	s_waitcnt lgkmcnt(0)
	v_mfma_f32_16x16x32_bf16 v[126:129], v[130:133], v[156:159], v[126:129]
	v_mfma_f32_16x16x32_bf16 v[122:125], v[138:141], v[156:159], v[122:125]
	v_mfma_f32_16x16x32_bf16 v[110:113], v[130:133], v[188:191], v[110:113]
	v_mfma_f32_16x16x32_bf16 v[106:109], v[138:141], v[188:191], v[106:109]
	s_barrier
	s_setprio 1
	v_mfma_f32_16x16x32_bf16 v[94:97], v[130:133], v[196:199], v[94:97]
	v_mfma_f32_16x16x32_bf16 v[90:93], v[138:141], v[196:199], v[90:93]
	v_mfma_f32_16x16x32_bf16 v[78:81], v[130:133], v[204:207], v[78:81]
	v_mfma_f32_16x16x32_bf16 v[74:77], v[138:141], v[204:207], v[74:77]
	v_mfma_f32_16x16x32_bf16 v[126:129], v[134:137], v[184:187], v[126:129]
	v_mfma_f32_16x16x32_bf16 v[122:125], v[142:145], v[184:187], v[122:125]
	v_mfma_f32_16x16x32_bf16 v[110:113], v[134:137], v[192:195], v[110:113]
	v_mfma_f32_16x16x32_bf16 v[106:109], v[142:145], v[192:195], v[106:109]
	v_mfma_f32_16x16x32_bf16 v[94:97], v[134:137], v[200:203], v[94:97]
	v_mfma_f32_16x16x32_bf16 v[90:93], v[142:145], v[200:203], v[90:93]
	v_mfma_f32_16x16x32_bf16 v[78:81], v[134:137], v[216:219], v[78:81]
	v_mfma_f32_16x16x32_bf16 v[74:77], v[142:145], v[216:219], v[74:77]
	v_mfma_f32_16x16x32_bf16 v[118:121], v[230:233], v[156:159], v[118:121]
	v_mfma_f32_16x16x32_bf16 v[114:117], v[238:241], v[156:159], v[114:117]
	v_mfma_f32_16x16x32_bf16 v[102:105], v[230:233], v[188:191], v[102:105]
	v_mfma_f32_16x16x32_bf16 v[98:101], v[238:241], v[188:191], v[98:101]
	v_mfma_f32_16x16x32_bf16 v[86:89], v[230:233], v[196:199], v[86:89]
	v_mfma_f32_16x16x32_bf16 v[82:85], v[238:241], v[196:199], v[82:85]
	v_mfma_f32_16x16x32_bf16 v[70:73], v[230:233], v[204:207], v[70:73]
	v_mfma_f32_16x16x32_bf16 v[66:69], v[238:241], v[204:207], v[66:69]
	v_mfma_f32_16x16x32_bf16 v[118:121], v[234:237], v[184:187], v[118:121]
	v_mfma_f32_16x16x32_bf16 v[114:117], v[242:245], v[184:187], v[114:117]
	v_mfma_f32_16x16x32_bf16 v[102:105], v[234:237], v[192:195], v[102:105]
	v_mfma_f32_16x16x32_bf16 v[98:101], v[242:245], v[192:195], v[98:101]
	v_mfma_f32_16x16x32_bf16 v[86:89], v[234:237], v[200:203], v[86:89]
	v_mfma_f32_16x16x32_bf16 v[82:85], v[242:245], v[200:203], v[82:85]
	v_mfma_f32_16x16x32_bf16 v[70:73], v[234:237], v[216:219], v[70:73]
	v_mfma_f32_16x16x32_bf16 v[66:69], v[242:245], v[216:219], v[66:69]
	s_setprio 0
	s_barrier
	ds_read_b128 v[156:159], v183 offset:49152
	ds_read_b128 v[184:187], v183 offset:50176
	ds_read_b128 v[188:191], v183 offset:51200
	ds_read_b128 v[192:195], v183 offset:52224
	ds_read_b128 v[196:199], v183 offset:53248
	ds_read_b128 v[200:203], v183 offset:54272
	ds_read_b128 v[204:207], v183 offset:55296
	ds_read_b128 v[216:219], v183 offset:56320
	s_add_i32 s1, s1, s20
	v_lshl_add_u64 v[160:161], v[160:161], 0, s[12:13]
	s_mov_b32 m0, s1
	s_nop 0
	global_load_lds_dwordx4 v[160:161], off
	v_lshl_add_u64 v[160:161], v[176:177], 0, s[12:13]
	s_add_i32 m0, s1, 0x2000
	s_nop 0
	global_load_lds_dwordx4 v[160:161], off
	s_mov_b32 m0, s65
	v_lshl_add_u64 v[160:161], v[178:179], 0, s[12:13]
	global_load_lds_dwordx4 v[160:161], off
	v_lshl_add_u64 v[160:161], v[208:209], 0, s[12:13]
	s_mov_b32 m0, s66
	s_nop 0
	global_load_lds_dwordx4 v[160:161], off
	s_add_i32 s1, s22, s20
	v_lshl_add_u64 v[160:161], v[220:221], 0, s[12:13]
	s_mov_b32 m0, s1
	s_nop 0
	global_load_lds_dwordx4 v[160:161], off
	v_lshl_add_u64 v[160:161], v[246:247], 0, s[12:13]
	s_add_i32 m0, s1, 0x2000
	s_nop 0
	global_load_lds_dwordx4 v[160:161], off
	s_waitcnt vmcnt(8)
	s_waitcnt lgkmcnt(0)
	v_mfma_f32_16x16x32_bf16 v[62:65], v[130:133], v[156:159], v[62:65]
	v_mfma_f32_16x16x32_bf16 v[58:61], v[138:141], v[156:159], v[58:61]
	v_mfma_f32_16x16x32_bf16 v[46:49], v[130:133], v[188:191], v[46:49]
	v_mfma_f32_16x16x32_bf16 v[42:45], v[138:141], v[188:191], v[42:45]
	s_barrier
	s_setprio 1
	v_mfma_f32_16x16x32_bf16 v[30:33], v[130:133], v[196:199], v[30:33]
	v_mfma_f32_16x16x32_bf16 v[26:29], v[138:141], v[196:199], v[26:29]
	v_mfma_f32_16x16x32_bf16 v[14:17], v[130:133], v[204:207], v[14:17]
	v_mfma_f32_16x16x32_bf16 v[10:13], v[138:141], v[204:207], v[10:13]
	v_mfma_f32_16x16x32_bf16 v[62:65], v[134:137], v[184:187], v[62:65]
	v_mfma_f32_16x16x32_bf16 v[58:61], v[142:145], v[184:187], v[58:61]
	v_mfma_f32_16x16x32_bf16 v[46:49], v[134:137], v[192:195], v[46:49]
	v_mfma_f32_16x16x32_bf16 v[42:45], v[142:145], v[192:195], v[42:45]
	v_mfma_f32_16x16x32_bf16 v[30:33], v[134:137], v[200:203], v[30:33]
	v_mfma_f32_16x16x32_bf16 v[26:29], v[142:145], v[200:203], v[26:29]
	v_mfma_f32_16x16x32_bf16 v[14:17], v[134:137], v[216:219], v[14:17]
	v_mfma_f32_16x16x32_bf16 v[10:13], v[142:145], v[216:219], v[10:13]
	v_mfma_f32_16x16x32_bf16 v[54:57], v[230:233], v[156:159], v[54:57]
	v_mfma_f32_16x16x32_bf16 v[50:53], v[238:241], v[156:159], v[50:53]
	v_mfma_f32_16x16x32_bf16 v[38:41], v[230:233], v[188:191], v[38:41]
	v_mfma_f32_16x16x32_bf16 v[34:37], v[238:241], v[188:191], v[34:37]
	v_mfma_f32_16x16x32_bf16 v[22:25], v[230:233], v[196:199], v[22:25]
	v_mfma_f32_16x16x32_bf16 v[18:21], v[238:241], v[196:199], v[18:21]
	v_mfma_f32_16x16x32_bf16 v[6:9], v[230:233], v[204:207], v[6:9]
	v_mfma_f32_16x16x32_bf16 v[2:5], v[238:241], v[204:207], v[2:5]
	v_mfma_f32_16x16x32_bf16 v[54:57], v[234:237], v[184:187], v[54:57]
	v_mfma_f32_16x16x32_bf16 v[50:53], v[242:245], v[184:187], v[50:53]
	v_mfma_f32_16x16x32_bf16 v[38:41], v[234:237], v[192:195], v[38:41]
	v_mfma_f32_16x16x32_bf16 v[34:37], v[242:245], v[192:195], v[34:37]
	v_mfma_f32_16x16x32_bf16 v[22:25], v[234:237], v[200:203], v[22:25]
	v_mfma_f32_16x16x32_bf16 v[18:21], v[242:245], v[200:203], v[18:21]
	v_mfma_f32_16x16x32_bf16 v[6:9], v[234:237], v[216:219], v[6:9]
	v_mfma_f32_16x16x32_bf16 v[2:5], v[242:245], v[216:219], v[2:5]
	s_setprio 0
	s_add_u32 s36, s36, 0x100
	s_addc_u32 s37, s37, 0
	s_add_u32 s48, s48, 0x100
	s_addc_u32 s49, s49, 0
	s_cmp_ge_u32 s23, s0
	s_mov_b32 s22, s23
	s_barrier
	s_cbranch_scc0 .LBB0_159
	s_cmpk_gt_u32 s16, 0xff
	s_cbranch_scc1 .Lrs_i4_post
	s_barrier

.Lrs_proj0_pre:
	s_add_u32 s1, s42, 0xfffc0080
	s_addc_u32 s22, s43, -1
	s_add_i32 s23, 0, 0x10000
	v_add_u32_e32 v142, s23, v217
	ds_read_b128 v[130:133], v142
	ds_read_b128 v[134:137], v142 offset:1024
	ds_read_b128 v[138:141], v142 offset:2048
	ds_read_b128 v[142:145], v142 offset:3072
	s_cmp_eq_u32 s54, 12
	s_cselect_b32 s45, s27, s22
	s_cselect_b32 s44, s50, s1
	s_cselect_b32 s31, s7, s53
	s_cselect_b32 s30, s51, s52
	v_lshl_add_u64 v[176:177], s[42:43], 0, v[190:191]
	s_add_i32 m0, s16, 0xc000
	ds_read_b128 v[146:149], v219
	ds_read_b128 v[150:153], v219 offset:1024
	ds_read_b128 v[154:157], v219 offset:2048
	ds_read_b128 v[158:161], v219 offset:3072
	ds_read_b128 v[194:197], v219 offset:4096
	ds_read_b128 v[198:201], v219 offset:5120
	ds_read_b128 v[202:205], v219 offset:6144
	ds_read_b128 v[206:209], v219 offset:7168
	global_load_lds_dwordx4 v[176:177], off
	v_lshl_add_u64 v[176:177], s[42:43], 0, v[192:193]
	s_add_i32 m0, s16, 0xe000
	s_nop 0
	global_load_lds_dwordx4 v[176:177], off
	s_add_i32 s1, 0, 0x14000
	v_add_u32_e32 v168, s1, v217
	ds_read_b128 v[230:233], v168
	ds_read_b128 v[234:237], v168 offset:1024
	ds_read_b128 v[238:241], v168 offset:2048
	ds_read_b128 v[242:245], v168 offset:3072
	s_waitcnt vmcnt(8)
	s_waitcnt lgkmcnt(0)
	v_mfma_f32_16x16x32_bf16 v[126:129], v[130:133], v[146:149], 0
	v_mfma_f32_16x16x32_bf16 v[122:125], v[138:141], v[146:149], 0
	v_mfma_f32_16x16x32_bf16 v[118:121], v[130:133], v[154:157], 0
	v_mfma_f32_16x16x32_bf16 v[110:113], v[138:141], v[154:157], 0
	s_barrier
	s_setprio 1
	v_mfma_f32_16x16x32_bf16 v[102:105], v[130:133], v[194:197], 0
	v_mfma_f32_16x16x32_bf16 v[94:97], v[138:141], v[194:197], 0
	v_mfma_f32_16x16x32_bf16 v[86:89], v[130:133], v[202:205], 0
	v_mfma_f32_16x16x32_bf16 v[78:81], v[138:141], v[202:205], 0
	v_mfma_f32_16x16x32_bf16 v[126:129], v[134:137], v[150:153], v[126:129]
	v_mfma_f32_16x16x32_bf16 v[122:125], v[142:145], v[150:153], v[122:125]
	v_mfma_f32_16x16x32_bf16 v[118:121], v[134:137], v[158:161], v[118:121]
	v_mfma_f32_16x16x32_bf16 v[110:113], v[142:145], v[158:161], v[110:113]
	v_mfma_f32_16x16x32_bf16 v[102:105], v[134:137], v[198:201], v[102:105]
	v_mfma_f32_16x16x32_bf16 v[94:97], v[142:145], v[198:201], v[94:97]
	v_mfma_f32_16x16x32_bf16 v[86:89], v[134:137], v[206:209], v[86:89]
	v_mfma_f32_16x16x32_bf16 v[78:81], v[142:145], v[206:209], v[78:81]
	v_mfma_f32_16x16x32_bf16 v[114:117], v[230:233], v[146:149], 0
	v_mfma_f32_16x16x32_bf16 v[106:109], v[238:241], v[146:149], 0
	v_mfma_f32_16x16x32_bf16 v[98:101], v[230:233], v[154:157], 0
	v_mfma_f32_16x16x32_bf16 v[90:93], v[238:241], v[154:157], 0
	v_mfma_f32_16x16x32_bf16 v[82:85], v[230:233], v[194:197], 0
	v_mfma_f32_16x16x32_bf16 v[74:77], v[238:241], v[194:197], 0
	v_mfma_f32_16x16x32_bf16 v[70:73], v[230:233], v[202:205], 0
	v_mfma_f32_16x16x32_bf16 v[66:69], v[238:241], v[202:205], 0
	v_mfma_f32_16x16x32_bf16 v[114:117], v[234:237], v[150:153], v[114:117]
	v_mfma_f32_16x16x32_bf16 v[106:109], v[242:245], v[150:153], v[106:109]
	v_mfma_f32_16x16x32_bf16 v[98:101], v[234:237], v[158:161], v[98:101]
	v_mfma_f32_16x16x32_bf16 v[90:93], v[242:245], v[158:161], v[90:93]
	v_mfma_f32_16x16x32_bf16 v[82:85], v[234:237], v[198:201], v[82:85]
	v_mfma_f32_16x16x32_bf16 v[74:77], v[242:245], v[198:201], v[74:77]
	v_mfma_f32_16x16x32_bf16 v[70:73], v[234:237], v[206:209], v[70:73]
	v_mfma_f32_16x16x32_bf16 v[66:69], v[242:245], v[206:209], v[66:69]
	s_setprio 0
	s_barrier
	ds_read_b128 v[146:149], v219 offset:16384
	ds_read_b128 v[150:153], v219 offset:17408
	ds_read_b128 v[154:157], v219 offset:18432
	ds_read_b128 v[158:161], v219 offset:19456
	ds_read_b128 v[194:197], v219 offset:20480
	ds_read_b128 v[198:201], v219 offset:21504
	ds_read_b128 v[202:205], v219 offset:22528
	ds_read_b128 v[206:209], v219 offset:23552
	s_add_i32 s22, s23, s4
	v_lshl_add_u64 v[176:177], s[30:31], 0, v[0:1]
	s_mov_b32 m0, s22
	s_nop 0
	global_load_lds_dwordx4 v[176:177], off
	v_lshl_add_u64 v[220:221], s[30:31], 0, v[178:179]
	s_add_i32 m0, s22, 0x2000
	s_nop 0
	global_load_lds_dwordx4 v[220:221], off
	s_mov_b32 m0, s16
	v_lshl_add_u64 v[246:247], s[44:45], 0, v[182:183]
	global_load_lds_dwordx4 v[246:247], off
	v_lshl_add_u64 v[248:249], s[44:45], 0, v[180:181]
	s_mov_b32 m0, s17
	s_nop 0
	global_load_lds_dwordx4 v[248:249], off
	s_add_u32 s22, s30, 0x40000
	s_addc_u32 s23, s31, 0
	s_add_i32 s1, s1, s4
	s_mov_b32 m0, s1
	s_nop 0
	global_load_lds_dwordx4 v0, s[22:23]
	s_add_i32 m0, s1, 0x2000
	s_nop 0
	global_load_lds_dwordx4 v178, s[22:23]
	s_waitcnt vmcnt(8)
	s_waitcnt lgkmcnt(0)
	v_mfma_f32_16x16x32_bf16 v[62:65], v[130:133], v[146:149], 0
	v_mfma_f32_16x16x32_bf16 v[58:61], v[138:141], v[146:149], 0
	v_mfma_f32_16x16x32_bf16 v[54:57], v[130:133], v[154:157], 0
	v_mfma_f32_16x16x32_bf16 v[46:49], v[138:141], v[154:157], 0
	s_barrier
	s_setprio 1
	v_mfma_f32_16x16x32_bf16 v[38:41], v[130:133], v[194:197], 0
	v_mfma_f32_16x16x32_bf16 v[30:33], v[138:141], v[194:197], 0
	v_mfma_f32_16x16x32_bf16 v[22:25], v[130:133], v[202:205], 0
	v_mfma_f32_16x16x32_bf16 v[14:17], v[138:141], v[202:205], 0
	v_mfma_f32_16x16x32_bf16 v[62:65], v[134:137], v[150:153], v[62:65]
	v_mfma_f32_16x16x32_bf16 v[58:61], v[142:145], v[150:153], v[58:61]
	v_mfma_f32_16x16x32_bf16 v[54:57], v[134:137], v[158:161], v[54:57]
	v_mfma_f32_16x16x32_bf16 v[46:49], v[142:145], v[158:161], v[46:49]
	v_mfma_f32_16x16x32_bf16 v[38:41], v[134:137], v[198:201], v[38:41]
	v_mfma_f32_16x16x32_bf16 v[30:33], v[142:145], v[198:201], v[30:33]
	v_mfma_f32_16x16x32_bf16 v[22:25], v[134:137], v[206:209], v[22:25]
	v_mfma_f32_16x16x32_bf16 v[14:17], v[142:145], v[206:209], v[14:17]
	v_mfma_f32_16x16x32_bf16 v[50:53], v[230:233], v[146:149], 0
	v_mfma_f32_16x16x32_bf16 v[42:45], v[238:241], v[146:149], 0
	v_mfma_f32_16x16x32_bf16 v[34:37], v[230:233], v[154:157], 0
	v_mfma_f32_16x16x32_bf16 v[26:29], v[238:241], v[154:157], 0
	v_mfma_f32_16x16x32_bf16 v[18:21], v[230:233], v[194:197], 0
	v_mfma_f32_16x16x32_bf16 v[10:13], v[238:241], v[194:197], 0
	v_mfma_f32_16x16x32_bf16 v[6:9], v[230:233], v[202:205], 0
	v_mfma_f32_16x16x32_bf16 v[2:5], v[238:241], v[202:205], 0
	v_mfma_f32_16x16x32_bf16 v[50:53], v[234:237], v[150:153], v[50:53]
	v_mfma_f32_16x16x32_bf16 v[42:45], v[242:245], v[150:153], v[42:45]
	v_mfma_f32_16x16x32_bf16 v[34:37], v[234:237], v[158:161], v[34:37]
	v_mfma_f32_16x16x32_bf16 v[26:29], v[242:245], v[158:161], v[26:29]
	v_mfma_f32_16x16x32_bf16 v[18:21], v[234:237], v[198:201], v[18:21]
	v_mfma_f32_16x16x32_bf16 v[10:13], v[242:245], v[198:201], v[10:13]
	v_mfma_f32_16x16x32_bf16 v[6:9], v[234:237], v[206:209], v[6:9]
	v_mfma_f32_16x16x32_bf16 v[2:5], v[242:245], v[206:209], v[2:5]
	s_setprio 0
	s_barrier
	s_add_i32 s1, 0, 0x18000
	v_add_u32_e32 v142, s1, v217
	ds_read_b128 v[130:133], v142
	ds_read_b128 v[134:137], v142 offset:1024
	ds_read_b128 v[138:141], v142 offset:2048
	ds_read_b128 v[142:145], v142 offset:3072
	s_add_u32 s22, s44, 0x40000
	s_addc_u32 s23, s45, 0
	s_mov_b32 m0, s20
	v_lshl_add_u64 v[230:231], s[22:23], 0, v[182:183]
	ds_read_b128 v[146:149], v219 offset:32768
	ds_read_b128 v[150:153], v219 offset:33792
	ds_read_b128 v[154:157], v219 offset:34816
	ds_read_b128 v[158:161], v219 offset:35840
	ds_read_b128 v[194:197], v219 offset:36864
	ds_read_b128 v[198:201], v219 offset:37888
	ds_read_b128 v[202:205], v219 offset:38912
	ds_read_b128 v[206:209], v219 offset:39936
	global_load_lds_dwordx4 v[230:231], off
	v_lshl_add_u64 v[230:231], s[22:23], 0, v[180:181]
	s_mov_b32 m0, s21
	s_nop 0
	global_load_lds_dwordx4 v[230:231], off
	s_add_i32 s33, 0, 0x1c000
	v_add_u32_e32 v168, s33, v217
	ds_read_b128 v[230:233], v168
	ds_read_b128 v[234:237], v168 offset:1024
	ds_read_b128 v[238:241], v168 offset:2048
	ds_read_b128 v[242:245], v168 offset:3072
	s_waitcnt vmcnt(8)
	s_waitcnt lgkmcnt(0)
	v_mfma_f32_16x16x32_bf16 v[126:129], v[130:133], v[146:149], v[126:129]
	v_mfma_f32_16x16x32_bf16 v[122:125], v[138:141], v[146:149], v[122:125]
	v_mfma_f32_16x16x32_bf16 v[118:121], v[130:133], v[154:157], v[118:121]
	v_mfma_f32_16x16x32_bf16 v[110:113], v[138:141], v[154:157], v[110:113]
	s_barrier
	s_setprio 1
	v_mfma_f32_16x16x32_bf16 v[102:105], v[130:133], v[194:197], v[102:105]
	v_mfma_f32_16x16x32_bf16 v[94:97], v[138:141], v[194:197], v[94:97]
	v_mfma_f32_16x16x32_bf16 v[86:89], v[130:133], v[202:205], v[86:89]
	v_mfma_f32_16x16x32_bf16 v[78:81], v[138:141], v[202:205], v[78:81]
	v_mfma_f32_16x16x32_bf16 v[126:129], v[134:137], v[150:153], v[126:129]
	v_mfma_f32_16x16x32_bf16 v[122:125], v[142:145], v[150:153], v[122:125]
	v_mfma_f32_16x16x32_bf16 v[118:121], v[134:137], v[158:161], v[118:121]
	v_mfma_f32_16x16x32_bf16 v[110:113], v[142:145], v[158:161], v[110:113]
	v_mfma_f32_16x16x32_bf16 v[102:105], v[134:137], v[198:201], v[102:105]
	v_mfma_f32_16x16x32_bf16 v[94:97], v[142:145], v[198:201], v[94:97]
	v_mfma_f32_16x16x32_bf16 v[86:89], v[134:137], v[206:209], v[86:89]
	v_mfma_f32_16x16x32_bf16 v[78:81], v[142:145], v[206:209], v[78:81]
	v_mfma_f32_16x16x32_bf16 v[114:117], v[230:233], v[146:149], v[114:117]
	v_mfma_f32_16x16x32_bf16 v[106:109], v[238:241], v[146:149], v[106:109]
	v_mfma_f32_16x16x32_bf16 v[98:101], v[230:233], v[154:157], v[98:101]
	v_mfma_f32_16x16x32_bf16 v[90:93], v[238:241], v[154:157], v[90:93]
	v_mfma_f32_16x16x32_bf16 v[82:85], v[230:233], v[194:197], v[82:85]
	v_mfma_f32_16x16x32_bf16 v[74:77], v[238:241], v[194:197], v[74:77]
	v_mfma_f32_16x16x32_bf16 v[70:73], v[230:233], v[202:205], v[70:73]
	v_mfma_f32_16x16x32_bf16 v[66:69], v[238:241], v[202:205], v[66:69]
	v_mfma_f32_16x16x32_bf16 v[114:117], v[234:237], v[150:153], v[114:117]
	v_mfma_f32_16x16x32_bf16 v[106:109], v[242:245], v[150:153], v[106:109]
	v_mfma_f32_16x16x32_bf16 v[98:101], v[234:237], v[158:161], v[98:101]
	v_mfma_f32_16x16x32_bf16 v[90:93], v[242:245], v[158:161], v[90:93]
	v_mfma_f32_16x16x32_bf16 v[82:85], v[234:237], v[198:201], v[82:85]
	v_mfma_f32_16x16x32_bf16 v[74:77], v[242:245], v[198:201], v[74:77]
	v_mfma_f32_16x16x32_bf16 v[70:73], v[234:237], v[206:209], v[70:73]
	v_mfma_f32_16x16x32_bf16 v[66:69], v[242:245], v[206:209], v[66:69]
	s_setprio 0
	s_barrier
	ds_read_b128 v[146:149], v219 offset:49152
	ds_read_b128 v[150:153], v219 offset:50176
	ds_read_b128 v[154:157], v219 offset:51200
	ds_read_b128 v[158:161], v219 offset:52224
	ds_read_b128 v[194:197], v219 offset:53248
	ds_read_b128 v[198:201], v219 offset:54272
	ds_read_b128 v[202:205], v219 offset:55296
	ds_read_b128 v[206:209], v219 offset:56320
	s_add_i32 s1, s1, s4
	v_lshl_add_u64 v[176:177], v[176:177], 0, s[12:13]
	s_mov_b32 m0, s1
	s_nop 0
	global_load_lds_dwordx4 v[176:177], off
	v_lshl_add_u64 v[176:177], v[220:221], 0, s[12:13]
	s_add_i32 m0, s1, 0x2000
	s_nop 0
	global_load_lds_dwordx4 v[176:177], off
	s_mov_b32 m0, s34
	v_lshl_add_u64 v[176:177], v[246:247], 0, s[12:13]
	global_load_lds_dwordx4 v[176:177], off
	v_lshl_add_u64 v[176:177], v[248:249], 0, s[12:13]
	s_mov_b32 m0, s46
	s_nop 0
	global_load_lds_dwordx4 v[176:177], off
	s_add_u32 s22, s30, 0x40080
	s_addc_u32 s23, s31, 0
	s_add_i32 s1, s33, s4
	s_mov_b32 m0, s1
	s_nop 0
	global_load_lds_dwordx4 v0, s[22:23]
	s_add_i32 m0, s1, 0x2000
	s_nop 0
	global_load_lds_dwordx4 v178, s[22:23]
	s_waitcnt vmcnt(8)
	s_waitcnt lgkmcnt(0)
	v_mfma_f32_16x16x32_bf16 v[62:65], v[130:133], v[146:149], v[62:65]
	v_mfma_f32_16x16x32_bf16 v[58:61], v[138:141], v[146:149], v[58:61]
	v_mfma_f32_16x16x32_bf16 v[54:57], v[130:133], v[154:157], v[54:57]
	v_mfma_f32_16x16x32_bf16 v[46:49], v[138:141], v[154:157], v[46:49]
	s_barrier
	s_setprio 1
	v_mfma_f32_16x16x32_bf16 v[38:41], v[130:133], v[194:197], v[38:41]
	v_mfma_f32_16x16x32_bf16 v[30:33], v[138:141], v[194:197], v[30:33]
	v_mfma_f32_16x16x32_bf16 v[22:25], v[130:133], v[202:205], v[22:25]
	v_mfma_f32_16x16x32_bf16 v[14:17], v[138:141], v[202:205], v[14:17]
	v_mfma_f32_16x16x32_bf16 v[62:65], v[134:137], v[150:153], v[62:65]
	v_mfma_f32_16x16x32_bf16 v[58:61], v[142:145], v[150:153], v[58:61]
	v_mfma_f32_16x16x32_bf16 v[54:57], v[134:137], v[158:161], v[54:57]
	v_mfma_f32_16x16x32_bf16 v[46:49], v[142:145], v[158:161], v[46:49]
	v_mfma_f32_16x16x32_bf16 v[38:41], v[134:137], v[198:201], v[38:41]
	v_mfma_f32_16x16x32_bf16 v[30:33], v[142:145], v[198:201], v[30:33]
	v_mfma_f32_16x16x32_bf16 v[22:25], v[134:137], v[206:209], v[22:25]
	v_mfma_f32_16x16x32_bf16 v[14:17], v[142:145], v[206:209], v[14:17]
	v_mfma_f32_16x16x32_bf16 v[50:53], v[230:233], v[146:149], v[50:53]
	v_mfma_f32_16x16x32_bf16 v[42:45], v[238:241], v[146:149], v[42:45]
	v_mfma_f32_16x16x32_bf16 v[34:37], v[230:233], v[154:157], v[34:37]
	v_mfma_f32_16x16x32_bf16 v[26:29], v[238:241], v[154:157], v[26:29]
	v_mfma_f32_16x16x32_bf16 v[18:21], v[230:233], v[194:197], v[18:21]
	v_mfma_f32_16x16x32_bf16 v[10:13], v[238:241], v[194:197], v[10:13]
	v_mfma_f32_16x16x32_bf16 v[6:9], v[230:233], v[202:205], v[6:9]
	v_mfma_f32_16x16x32_bf16 v[2:5], v[238:241], v[202:205], v[2:5]
	v_mfma_f32_16x16x32_bf16 v[50:53], v[234:237], v[150:153], v[50:53]
	v_mfma_f32_16x16x32_bf16 v[42:45], v[242:245], v[150:153], v[42:45]
	v_mfma_f32_16x16x32_bf16 v[34:37], v[234:237], v[158:161], v[34:37]
	v_mfma_f32_16x16x32_bf16 v[26:29], v[242:245], v[158:161], v[26:29]
	v_mfma_f32_16x16x32_bf16 v[18:21], v[234:237], v[198:201], v[18:21]
	v_mfma_f32_16x16x32_bf16 v[10:13], v[242:245], v[198:201], v[10:13]
	v_mfma_f32_16x16x32_bf16 v[6:9], v[234:237], v[206:209], v[6:9]
	v_mfma_f32_16x16x32_bf16 v[2:5], v[242:245], v[206:209], v[2:5]
	s_setprio 0
	s_add_i32 s54, s54, 2
	s_add_u32 s42, s42, 0x100
	s_addc_u32 s43, s43, 0
	s_add_u32 s52, s52, 0x100
	s_addc_u32 s53, s53, 0
	s_cmp_gt_u32 s54, 13
	s_barrier
.LBB0_289:
	s_add_u32 s1, s42, 0xfffc0080
	s_addc_u32 s22, s43, -1
	s_add_i32 s23, 0, 0x10000
	v_add_u32_e32 v142, s23, v217
	ds_read_b128 v[130:133], v142
	ds_read_b128 v[134:137], v142 offset:1024
	ds_read_b128 v[138:141], v142 offset:2048
	ds_read_b128 v[142:145], v142 offset:3072
	s_cmp_eq_u32 s54, 12
	s_cselect_b32 s45, s27, s22
	s_cselect_b32 s44, s50, s1
	s_cselect_b32 s31, s7, s53
	s_cselect_b32 s30, s51, s52
	v_lshl_add_u64 v[176:177], s[42:43], 0, v[190:191]
	s_add_i32 m0, s16, 0xc000
	ds_read_b128 v[146:149], v219
	ds_read_b128 v[150:153], v219 offset:1024
	ds_read_b128 v[154:157], v219 offset:2048
	ds_read_b128 v[158:161], v219 offset:3072
	ds_read_b128 v[194:197], v219 offset:4096
	ds_read_b128 v[198:201], v219 offset:5120
	ds_read_b128 v[202:205], v219 offset:6144
	ds_read_b128 v[206:209], v219 offset:7168
	global_load_lds_dwordx4 v[176:177], off
	v_lshl_add_u64 v[176:177], s[42:43], 0, v[192:193]
	s_add_i32 m0, s16, 0xe000
	s_nop 0
	global_load_lds_dwordx4 v[176:177], off
	s_add_i32 s1, 0, 0x14000
	v_add_u32_e32 v168, s1, v217
	ds_read_b128 v[230:233], v168
	ds_read_b128 v[234:237], v168 offset:1024
	ds_read_b128 v[238:241], v168 offset:2048
	ds_read_b128 v[242:245], v168 offset:3072
	s_waitcnt vmcnt(8)
	s_waitcnt lgkmcnt(0)
	v_mfma_f32_16x16x32_bf16 v[126:129], v[130:133], v[146:149], v[126:129]
	v_mfma_f32_16x16x32_bf16 v[122:125], v[138:141], v[146:149], v[122:125]
	v_mfma_f32_16x16x32_bf16 v[118:121], v[130:133], v[154:157], v[118:121]
	v_mfma_f32_16x16x32_bf16 v[110:113], v[138:141], v[154:157], v[110:113]
	s_barrier
	s_setprio 1
	v_mfma_f32_16x16x32_bf16 v[102:105], v[130:133], v[194:197], v[102:105]
	v_mfma_f32_16x16x32_bf16 v[94:97], v[138:141], v[194:197], v[94:97]
	v_mfma_f32_16x16x32_bf16 v[86:89], v[130:133], v[202:205], v[86:89]
	v_mfma_f32_16x16x32_bf16 v[78:81], v[138:141], v[202:205], v[78:81]
	v_mfma_f32_16x16x32_bf16 v[126:129], v[134:137], v[150:153], v[126:129]
	v_mfma_f32_16x16x32_bf16 v[122:125], v[142:145], v[150:153], v[122:125]
	v_mfma_f32_16x16x32_bf16 v[118:121], v[134:137], v[158:161], v[118:121]
	v_mfma_f32_16x16x32_bf16 v[110:113], v[142:145], v[158:161], v[110:113]
	v_mfma_f32_16x16x32_bf16 v[102:105], v[134:137], v[198:201], v[102:105]
	v_mfma_f32_16x16x32_bf16 v[94:97], v[142:145], v[198:201], v[94:97]
	v_mfma_f32_16x16x32_bf16 v[86:89], v[134:137], v[206:209], v[86:89]
	v_mfma_f32_16x16x32_bf16 v[78:81], v[142:145], v[206:209], v[78:81]
	v_mfma_f32_16x16x32_bf16 v[114:117], v[230:233], v[146:149], v[114:117]
	v_mfma_f32_16x16x32_bf16 v[106:109], v[238:241], v[146:149], v[106:109]
	v_mfma_f32_16x16x32_bf16 v[98:101], v[230:233], v[154:157], v[98:101]
	v_mfma_f32_16x16x32_bf16 v[90:93], v[238:241], v[154:157], v[90:93]
	v_mfma_f32_16x16x32_bf16 v[82:85], v[230:233], v[194:197], v[82:85]
	v_mfma_f32_16x16x32_bf16 v[74:77], v[238:241], v[194:197], v[74:77]
	v_mfma_f32_16x16x32_bf16 v[70:73], v[230:233], v[202:205], v[70:73]
	v_mfma_f32_16x16x32_bf16 v[66:69], v[238:241], v[202:205], v[66:69]
	v_mfma_f32_16x16x32_bf16 v[114:117], v[234:237], v[150:153], v[114:117]
	v_mfma_f32_16x16x32_bf16 v[106:109], v[242:245], v[150:153], v[106:109]
	v_mfma_f32_16x16x32_bf16 v[98:101], v[234:237], v[158:161], v[98:101]
	v_mfma_f32_16x16x32_bf16 v[90:93], v[242:245], v[158:161], v[90:93]
	v_mfma_f32_16x16x32_bf16 v[82:85], v[234:237], v[198:201], v[82:85]
	v_mfma_f32_16x16x32_bf16 v[74:77], v[242:245], v[198:201], v[74:77]
	v_mfma_f32_16x16x32_bf16 v[70:73], v[234:237], v[206:209], v[70:73]
	v_mfma_f32_16x16x32_bf16 v[66:69], v[242:245], v[206:209], v[66:69]
	s_setprio 0
	s_barrier
	ds_read_b128 v[146:149], v219 offset:16384
	ds_read_b128 v[150:153], v219 offset:17408
	ds_read_b128 v[154:157], v219 offset:18432
	ds_read_b128 v[158:161], v219 offset:19456
	ds_read_b128 v[194:197], v219 offset:20480
	ds_read_b128 v[198:201], v219 offset:21504
	ds_read_b128 v[202:205], v219 offset:22528
	ds_read_b128 v[206:209], v219 offset:23552
	s_add_i32 s22, s23, s4
	v_lshl_add_u64 v[176:177], s[30:31], 0, v[0:1]
	s_mov_b32 m0, s22
	s_nop 0
	global_load_lds_dwordx4 v[176:177], off
	v_lshl_add_u64 v[220:221], s[30:31], 0, v[178:179]
	s_add_i32 m0, s22, 0x2000
	s_nop 0
	global_load_lds_dwordx4 v[220:221], off
	s_mov_b32 m0, s16
	v_lshl_add_u64 v[246:247], s[44:45], 0, v[182:183]
	global_load_lds_dwordx4 v[246:247], off
	v_lshl_add_u64 v[248:249], s[44:45], 0, v[180:181]
	s_mov_b32 m0, s17
	s_nop 0
	global_load_lds_dwordx4 v[248:249], off
	s_add_u32 s22, s30, 0x40000
	s_addc_u32 s23, s31, 0
	s_add_i32 s1, s1, s4
	s_mov_b32 m0, s1
	s_nop 0
	global_load_lds_dwordx4 v0, s[22:23]
	s_add_i32 m0, s1, 0x2000
	s_nop 0
	global_load_lds_dwordx4 v178, s[22:23]
	s_waitcnt vmcnt(8)
	s_waitcnt lgkmcnt(0)
	v_mfma_f32_16x16x32_bf16 v[62:65], v[130:133], v[146:149], v[62:65]
	v_mfma_f32_16x16x32_bf16 v[58:61], v[138:141], v[146:149], v[58:61]
	v_mfma_f32_16x16x32_bf16 v[54:57], v[130:133], v[154:157], v[54:57]
	v_mfma_f32_16x16x32_bf16 v[46:49], v[138:141], v[154:157], v[46:49]
	s_barrier
	s_setprio 1
	v_mfma_f32_16x16x32_bf16 v[38:41], v[130:133], v[194:197], v[38:41]
	v_mfma_f32_16x16x32_bf16 v[30:33], v[138:141], v[194:197], v[30:33]
	v_mfma_f32_16x16x32_bf16 v[22:25], v[130:133], v[202:205], v[22:25]
	v_mfma_f32_16x16x32_bf16 v[14:17], v[138:141], v[202:205], v[14:17]
	v_mfma_f32_16x16x32_bf16 v[62:65], v[134:137], v[150:153], v[62:65]
	v_mfma_f32_16x16x32_bf16 v[58:61], v[142:145], v[150:153], v[58:61]
	v_mfma_f32_16x16x32_bf16 v[54:57], v[134:137], v[158:161], v[54:57]
	v_mfma_f32_16x16x32_bf16 v[46:49], v[142:145], v[158:161], v[46:49]
	v_mfma_f32_16x16x32_bf16 v[38:41], v[134:137], v[198:201], v[38:41]
	v_mfma_f32_16x16x32_bf16 v[30:33], v[142:145], v[198:201], v[30:33]
	v_mfma_f32_16x16x32_bf16 v[22:25], v[134:137], v[206:209], v[22:25]
	v_mfma_f32_16x16x32_bf16 v[14:17], v[142:145], v[206:209], v[14:17]
	v_mfma_f32_16x16x32_bf16 v[50:53], v[230:233], v[146:149], v[50:53]
	v_mfma_f32_16x16x32_bf16 v[42:45], v[238:241], v[146:149], v[42:45]
	v_mfma_f32_16x16x32_bf16 v[34:37], v[230:233], v[154:157], v[34:37]
	v_mfma_f32_16x16x32_bf16 v[26:29], v[238:241], v[154:157], v[26:29]
	v_mfma_f32_16x16x32_bf16 v[18:21], v[230:233], v[194:197], v[18:21]
	v_mfma_f32_16x16x32_bf16 v[10:13], v[238:241], v[194:197], v[10:13]
	v_mfma_f32_16x16x32_bf16 v[6:9], v[230:233], v[202:205], v[6:9]
	v_mfma_f32_16x16x32_bf16 v[2:5], v[238:241], v[202:205], v[2:5]
	v_mfma_f32_16x16x32_bf16 v[50:53], v[234:237], v[150:153], v[50:53]
	v_mfma_f32_16x16x32_bf16 v[42:45], v[242:245], v[150:153], v[42:45]
	v_mfma_f32_16x16x32_bf16 v[34:37], v[234:237], v[158:161], v[34:37]
	v_mfma_f32_16x16x32_bf16 v[26:29], v[242:245], v[158:161], v[26:29]
	v_mfma_f32_16x16x32_bf16 v[18:21], v[234:237], v[198:201], v[18:21]
	v_mfma_f32_16x16x32_bf16 v[10:13], v[242:245], v[198:201], v[10:13]
	v_mfma_f32_16x16x32_bf16 v[6:9], v[234:237], v[206:209], v[6:9]
	v_mfma_f32_16x16x32_bf16 v[2:5], v[242:245], v[206:209], v[2:5]
	s_setprio 0
	s_barrier
	s_add_i32 s1, 0, 0x18000
	v_add_u32_e32 v142, s1, v217
	ds_read_b128 v[130:133], v142
	ds_read_b128 v[134:137], v142 offset:1024
	ds_read_b128 v[138:141], v142 offset:2048
	ds_read_b128 v[142:145], v142 offset:3072
	s_add_u32 s22, s44, 0x40000
	s_addc_u32 s23, s45, 0
	s_mov_b32 m0, s20
	v_lshl_add_u64 v[230:231], s[22:23], 0, v[182:183]
	ds_read_b128 v[146:149], v219 offset:32768
	ds_read_b128 v[150:153], v219 offset:33792
	ds_read_b128 v[154:157], v219 offset:34816
	ds_read_b128 v[158:161], v219 offset:35840
	ds_read_b128 v[194:197], v219 offset:36864
	ds_read_b128 v[198:201], v219 offset:37888
	ds_read_b128 v[202:205], v219 offset:38912
	ds_read_b128 v[206:209], v219 offset:39936
	global_load_lds_dwordx4 v[230:231], off
	v_lshl_add_u64 v[230:231], s[22:23], 0, v[180:181]
	s_mov_b32 m0, s21
	s_nop 0
	global_load_lds_dwordx4 v[230:231], off
	s_add_i32 s33, 0, 0x1c000
	v_add_u32_e32 v168, s33, v217
	ds_read_b128 v[230:233], v168
	ds_read_b128 v[234:237], v168 offset:1024
	ds_read_b128 v[238:241], v168 offset:2048
	ds_read_b128 v[242:245], v168 offset:3072
	s_waitcnt vmcnt(8)
	s_waitcnt lgkmcnt(0)
	v_mfma_f32_16x16x32_bf16 v[126:129], v[130:133], v[146:149], v[126:129]
	v_mfma_f32_16x16x32_bf16 v[122:125], v[138:141], v[146:149], v[122:125]
	v_mfma_f32_16x16x32_bf16 v[118:121], v[130:133], v[154:157], v[118:121]
	v_mfma_f32_16x16x32_bf16 v[110:113], v[138:141], v[154:157], v[110:113]
	s_barrier
	s_setprio 1
	v_mfma_f32_16x16x32_bf16 v[102:105], v[130:133], v[194:197], v[102:105]
	v_mfma_f32_16x16x32_bf16 v[94:97], v[138:141], v[194:197], v[94:97]
	v_mfma_f32_16x16x32_bf16 v[86:89], v[130:133], v[202:205], v[86:89]
	v_mfma_f32_16x16x32_bf16 v[78:81], v[138:141], v[202:205], v[78:81]
	v_mfma_f32_16x16x32_bf16 v[126:129], v[134:137], v[150:153], v[126:129]
	v_mfma_f32_16x16x32_bf16 v[122:125], v[142:145], v[150:153], v[122:125]
	v_mfma_f32_16x16x32_bf16 v[118:121], v[134:137], v[158:161], v[118:121]
	v_mfma_f32_16x16x32_bf16 v[110:113], v[142:145], v[158:161], v[110:113]
	v_mfma_f32_16x16x32_bf16 v[102:105], v[134:137], v[198:201], v[102:105]
	v_mfma_f32_16x16x32_bf16 v[94:97], v[142:145], v[198:201], v[94:97]
	v_mfma_f32_16x16x32_bf16 v[86:89], v[134:137], v[206:209], v[86:89]
	v_mfma_f32_16x16x32_bf16 v[78:81], v[142:145], v[206:209], v[78:81]
	v_mfma_f32_16x16x32_bf16 v[114:117], v[230:233], v[146:149], v[114:117]
	v_mfma_f32_16x16x32_bf16 v[106:109], v[238:241], v[146:149], v[106:109]
	v_mfma_f32_16x16x32_bf16 v[98:101], v[230:233], v[154:157], v[98:101]
	v_mfma_f32_16x16x32_bf16 v[90:93], v[238:241], v[154:157], v[90:93]
	v_mfma_f32_16x16x32_bf16 v[82:85], v[230:233], v[194:197], v[82:85]
	v_mfma_f32_16x16x32_bf16 v[74:77], v[238:241], v[194:197], v[74:77]
	v_mfma_f32_16x16x32_bf16 v[70:73], v[230:233], v[202:205], v[70:73]
	v_mfma_f32_16x16x32_bf16 v[66:69], v[238:241], v[202:205], v[66:69]
	v_mfma_f32_16x16x32_bf16 v[114:117], v[234:237], v[150:153], v[114:117]
	v_mfma_f32_16x16x32_bf16 v[106:109], v[242:245], v[150:153], v[106:109]
	v_mfma_f32_16x16x32_bf16 v[98:101], v[234:237], v[158:161], v[98:101]
	v_mfma_f32_16x16x32_bf16 v[90:93], v[242:245], v[158:161], v[90:93]
	v_mfma_f32_16x16x32_bf16 v[82:85], v[234:237], v[198:201], v[82:85]
	v_mfma_f32_16x16x32_bf16 v[74:77], v[242:245], v[198:201], v[74:77]
	v_mfma_f32_16x16x32_bf16 v[70:73], v[234:237], v[206:209], v[70:73]
	v_mfma_f32_16x16x32_bf16 v[66:69], v[242:245], v[206:209], v[66:69]
	s_setprio 0
	s_barrier
	ds_read_b128 v[146:149], v219 offset:49152
	ds_read_b128 v[150:153], v219 offset:50176
	ds_read_b128 v[154:157], v219 offset:51200
	ds_read_b128 v[158:161], v219 offset:52224
	ds_read_b128 v[194:197], v219 offset:53248
	ds_read_b128 v[198:201], v219 offset:54272
	ds_read_b128 v[202:205], v219 offset:55296
	ds_read_b128 v[206:209], v219 offset:56320
	s_add_i32 s1, s1, s4
	v_lshl_add_u64 v[176:177], v[176:177], 0, s[12:13]
	s_mov_b32 m0, s1
	s_nop 0
	global_load_lds_dwordx4 v[176:177], off
	v_lshl_add_u64 v[176:177], v[220:221], 0, s[12:13]
	s_add_i32 m0, s1, 0x2000
	s_nop 0
	global_load_lds_dwordx4 v[176:177], off
	s_mov_b32 m0, s34
	v_lshl_add_u64 v[176:177], v[246:247], 0, s[12:13]
	global_load_lds_dwordx4 v[176:177], off
	v_lshl_add_u64 v[176:177], v[248:249], 0, s[12:13]
	s_mov_b32 m0, s46
	s_nop 0
	global_load_lds_dwordx4 v[176:177], off
	s_add_u32 s22, s30, 0x40080
	s_addc_u32 s23, s31, 0
	s_add_i32 s1, s33, s4
	s_mov_b32 m0, s1
	s_nop 0
	global_load_lds_dwordx4 v0, s[22:23]
	s_add_i32 m0, s1, 0x2000
	s_nop 0
	global_load_lds_dwordx4 v178, s[22:23]
	s_waitcnt vmcnt(8)
	s_waitcnt lgkmcnt(0)
	v_mfma_f32_16x16x32_bf16 v[62:65], v[130:133], v[146:149], v[62:65]
	v_mfma_f32_16x16x32_bf16 v[58:61], v[138:141], v[146:149], v[58:61]
	v_mfma_f32_16x16x32_bf16 v[54:57], v[130:133], v[154:157], v[54:57]
	v_mfma_f32_16x16x32_bf16 v[46:49], v[138:141], v[154:157], v[46:49]
	s_barrier
	s_setprio 1
	v_mfma_f32_16x16x32_bf16 v[38:41], v[130:133], v[194:197], v[38:41]
	v_mfma_f32_16x16x32_bf16 v[30:33], v[138:141], v[194:197], v[30:33]
	v_mfma_f32_16x16x32_bf16 v[22:25], v[130:133], v[202:205], v[22:25]
	v_mfma_f32_16x16x32_bf16 v[14:17], v[138:141], v[202:205], v[14:17]
	v_mfma_f32_16x16x32_bf16 v[62:65], v[134:137], v[150:153], v[62:65]
	v_mfma_f32_16x16x32_bf16 v[58:61], v[142:145], v[150:153], v[58:61]
	v_mfma_f32_16x16x32_bf16 v[54:57], v[134:137], v[158:161], v[54:57]
	v_mfma_f32_16x16x32_bf16 v[46:49], v[142:145], v[158:161], v[46:49]
	v_mfma_f32_16x16x32_bf16 v[38:41], v[134:137], v[198:201], v[38:41]
	v_mfma_f32_16x16x32_bf16 v[30:33], v[142:145], v[198:201], v[30:33]
	v_mfma_f32_16x16x32_bf16 v[22:25], v[134:137], v[206:209], v[22:25]
	v_mfma_f32_16x16x32_bf16 v[14:17], v[142:145], v[206:209], v[14:17]
	v_mfma_f32_16x16x32_bf16 v[50:53], v[230:233], v[146:149], v[50:53]
	v_mfma_f32_16x16x32_bf16 v[42:45], v[238:241], v[146:149], v[42:45]
	v_mfma_f32_16x16x32_bf16 v[34:37], v[230:233], v[154:157], v[34:37]
	v_mfma_f32_16x16x32_bf16 v[26:29], v[238:241], v[154:157], v[26:29]
	v_mfma_f32_16x16x32_bf16 v[18:21], v[230:233], v[194:197], v[18:21]
	v_mfma_f32_16x16x32_bf16 v[10:13], v[238:241], v[194:197], v[10:13]
	v_mfma_f32_16x16x32_bf16 v[6:9], v[230:233], v[202:205], v[6:9]
	v_mfma_f32_16x16x32_bf16 v[2:5], v[238:241], v[202:205], v[2:5]
	v_mfma_f32_16x16x32_bf16 v[50:53], v[234:237], v[150:153], v[50:53]
	v_mfma_f32_16x16x32_bf16 v[42:45], v[242:245], v[150:153], v[42:45]
	v_mfma_f32_16x16x32_bf16 v[34:37], v[234:237], v[158:161], v[34:37]
	v_mfma_f32_16x16x32_bf16 v[26:29], v[242:245], v[158:161], v[26:29]
	v_mfma_f32_16x16x32_bf16 v[18:21], v[234:237], v[198:201], v[18:21]
	v_mfma_f32_16x16x32_bf16 v[10:13], v[242:245], v[198:201], v[10:13]
	v_mfma_f32_16x16x32_bf16 v[6:9], v[234:237], v[206:209], v[6:9]
	v_mfma_f32_16x16x32_bf16 v[2:5], v[242:245], v[206:209], v[2:5]
	s_setprio 0
	s_add_i32 s54, s54, 2
	s_add_u32 s42, s42, 0x100
	s_addc_u32 s43, s43, 0
	s_add_u32 s52, s52, 0x100
	s_addc_u32 s53, s53, 0
	s_cmp_gt_u32 s54, 13
	s_barrier
	s_cbranch_scc0 .LBB0_289
	s_cmpk_gt_u32 s0, 0xff
	s_cbranch_scc1 .Lrs_proj0_post
	s_barrier

.Lrs_proj1_pre:
	s_add_u32 s1, s28, 0xfffc0080
	s_addc_u32 s22, s29, -1
	s_add_i32 s23, 0, 0x10000
	v_add_u32_e32 v158, s23, v181
	ds_read_b128 v[130:133], v158
	ds_read_b128 v[134:137], v158 offset:1024
	ds_read_b128 v[154:157], v158 offset:2048
	ds_read_b128 v[186:189], v158 offset:3072
	s_cmp_eq_u32 s44, 12
	s_cselect_b32 s43, s17, s22
	s_cselect_b32 s42, s20, s1
	s_cselect_b32 s31, s9, s34
	s_cselect_b32 s30, s21, s25
	v_lshl_add_u64 v[160:161], s[28:29], 0, v[150:151]
	s_add_i32 m0, s49, 0xc000
	ds_read_b128 v[190:193], v185
	ds_read_b128 v[194:197], v185 offset:1024
	ds_read_b128 v[198:201], v185 offset:2048
	ds_read_b128 v[202:205], v185 offset:3072
	ds_read_b128 v[206:209], v185 offset:4096
	ds_read_b128 v[216:219], v185 offset:5120
	ds_read_b128 v[230:233], v185 offset:6144
	ds_read_b128 v[234:237], v185 offset:7168
	global_load_lds_dwordx4 v[160:161], off
	v_lshl_add_u64 v[160:161], s[28:29], 0, v[152:153]
	s_add_i32 m0, s49, 0xe000
	s_nop 0
	global_load_lds_dwordx4 v[160:161], off
	s_add_i32 s1, 0, 0x14000
	v_add_u32_e32 v158, s1, v181
	ds_read_b128 v[238:241], v158
	ds_read_b128 v[242:245], v158 offset:1024
	ds_read_b128 v[246:249], v158 offset:2048
	ds_read_b128 v[176:179], v158 offset:3072
	s_waitcnt vmcnt(8)
	s_waitcnt lgkmcnt(0)
	v_mfma_f32_16x16x32_bf16 v[126:129], v[130:133], v[190:193], 0
	v_mfma_f32_16x16x32_bf16 v[122:125], v[154:157], v[190:193], 0
	v_mfma_f32_16x16x32_bf16 v[110:113], v[130:133], v[198:201], 0
	v_mfma_f32_16x16x32_bf16 v[106:109], v[154:157], v[198:201], 0
	s_barrier
	s_setprio 1
	v_mfma_f32_16x16x32_bf16 v[94:97], v[130:133], v[206:209], 0
	v_mfma_f32_16x16x32_bf16 v[90:93], v[154:157], v[206:209], 0
	v_mfma_f32_16x16x32_bf16 v[78:81], v[130:133], v[230:233], 0
	v_mfma_f32_16x16x32_bf16 v[74:77], v[154:157], v[230:233], 0
	v_mfma_f32_16x16x32_bf16 v[126:129], v[134:137], v[194:197], v[126:129]
	v_mfma_f32_16x16x32_bf16 v[122:125], v[186:189], v[194:197], v[122:125]
	v_mfma_f32_16x16x32_bf16 v[110:113], v[134:137], v[202:205], v[110:113]
	v_mfma_f32_16x16x32_bf16 v[106:109], v[186:189], v[202:205], v[106:109]
	v_mfma_f32_16x16x32_bf16 v[94:97], v[134:137], v[216:219], v[94:97]
	v_mfma_f32_16x16x32_bf16 v[90:93], v[186:189], v[216:219], v[90:93]
	v_mfma_f32_16x16x32_bf16 v[78:81], v[134:137], v[234:237], v[78:81]
	v_mfma_f32_16x16x32_bf16 v[74:77], v[186:189], v[234:237], v[74:77]
	v_mfma_f32_16x16x32_bf16 v[118:121], v[238:241], v[190:193], 0
	v_mfma_f32_16x16x32_bf16 v[114:117], v[246:249], v[190:193], 0
	v_mfma_f32_16x16x32_bf16 v[102:105], v[238:241], v[198:201], 0
	v_mfma_f32_16x16x32_bf16 v[98:101], v[246:249], v[198:201], 0
	v_mfma_f32_16x16x32_bf16 v[86:89], v[238:241], v[206:209], 0
	v_mfma_f32_16x16x32_bf16 v[82:85], v[246:249], v[206:209], 0
	v_mfma_f32_16x16x32_bf16 v[70:73], v[238:241], v[230:233], 0
	v_mfma_f32_16x16x32_bf16 v[66:69], v[246:249], v[230:233], 0
	v_mfma_f32_16x16x32_bf16 v[118:121], v[242:245], v[194:197], v[118:121]
	v_mfma_f32_16x16x32_bf16 v[114:117], v[176:179], v[194:197], v[114:117]
	v_mfma_f32_16x16x32_bf16 v[102:105], v[242:245], v[202:205], v[102:105]
	v_mfma_f32_16x16x32_bf16 v[98:101], v[176:179], v[202:205], v[98:101]
	v_mfma_f32_16x16x32_bf16 v[86:89], v[242:245], v[216:219], v[86:89]
	v_mfma_f32_16x16x32_bf16 v[82:85], v[176:179], v[216:219], v[82:85]
	v_mfma_f32_16x16x32_bf16 v[70:73], v[242:245], v[234:237], v[70:73]
	v_mfma_f32_16x16x32_bf16 v[66:69], v[176:179], v[234:237], v[66:69]
	s_setprio 0
	s_barrier
	ds_read_b128 v[190:193], v185 offset:16384
	ds_read_b128 v[194:197], v185 offset:17408
	ds_read_b128 v[198:201], v185 offset:18432
	ds_read_b128 v[202:205], v185 offset:19456
	ds_read_b128 v[206:209], v185 offset:20480
	ds_read_b128 v[216:219], v185 offset:21504
	ds_read_b128 v[230:233], v185 offset:22528
	ds_read_b128 v[234:237], v185 offset:23552
	s_add_i32 s22, s23, s48
	v_lshl_add_u64 v[160:161], s[30:31], 0, v[0:1]
	s_mov_b32 m0, s22
	s_nop 0
	global_load_lds_dwordx4 v[160:161], off
	v_lshl_add_u64 v[220:221], s[30:31], 0, v[138:139]
	s_add_i32 m0, s22, 0x2000
	s_nop 0
	global_load_lds_dwordx4 v[220:221], off
	s_mov_b32 m0, s49
	v_lshl_add_u64 v[250:251], s[42:43], 0, v[142:143]
	global_load_lds_dwordx4 v[250:251], off
	v_lshl_add_u64 v[168:169], s[42:43], 0, v[140:141]
	s_mov_b32 m0, s50
	s_nop 0
	global_load_lds_dwordx4 v[168:169], off
	s_add_u32 s22, s30, 0x40000
	s_addc_u32 s23, s31, 0
	s_add_i32 s1, s1, s48
	s_mov_b32 m0, s1
	s_nop 0
	global_load_lds_dwordx4 v0, s[22:23]
	s_add_i32 m0, s1, 0x2000
	s_nop 0
	global_load_lds_dwordx4 v138, s[22:23]
	s_waitcnt vmcnt(8)
	s_waitcnt lgkmcnt(0)
	v_mfma_f32_16x16x32_bf16 v[62:65], v[130:133], v[190:193], 0
	v_mfma_f32_16x16x32_bf16 v[58:61], v[154:157], v[190:193], 0
	v_mfma_f32_16x16x32_bf16 v[46:49], v[130:133], v[198:201], 0
	v_mfma_f32_16x16x32_bf16 v[42:45], v[154:157], v[198:201], 0
	s_barrier
	s_setprio 1
	v_mfma_f32_16x16x32_bf16 v[30:33], v[130:133], v[206:209], 0
	v_mfma_f32_16x16x32_bf16 v[26:29], v[154:157], v[206:209], 0
	v_mfma_f32_16x16x32_bf16 v[14:17], v[130:133], v[230:233], 0
	v_mfma_f32_16x16x32_bf16 v[10:13], v[154:157], v[230:233], 0
	v_mfma_f32_16x16x32_bf16 v[62:65], v[134:137], v[194:197], v[62:65]
	v_mfma_f32_16x16x32_bf16 v[58:61], v[186:189], v[194:197], v[58:61]
	v_mfma_f32_16x16x32_bf16 v[46:49], v[134:137], v[202:205], v[46:49]
	v_mfma_f32_16x16x32_bf16 v[42:45], v[186:189], v[202:205], v[42:45]
	v_mfma_f32_16x16x32_bf16 v[30:33], v[134:137], v[216:219], v[30:33]
	v_mfma_f32_16x16x32_bf16 v[26:29], v[186:189], v[216:219], v[26:29]
	v_mfma_f32_16x16x32_bf16 v[14:17], v[134:137], v[234:237], v[14:17]
	v_mfma_f32_16x16x32_bf16 v[10:13], v[186:189], v[234:237], v[10:13]
	v_mfma_f32_16x16x32_bf16 v[54:57], v[238:241], v[190:193], 0
	v_mfma_f32_16x16x32_bf16 v[50:53], v[246:249], v[190:193], 0
	v_mfma_f32_16x16x32_bf16 v[38:41], v[238:241], v[198:201], 0
	v_mfma_f32_16x16x32_bf16 v[34:37], v[246:249], v[198:201], 0
	v_mfma_f32_16x16x32_bf16 v[22:25], v[238:241], v[206:209], 0
	v_mfma_f32_16x16x32_bf16 v[18:21], v[246:249], v[206:209], 0
	v_mfma_f32_16x16x32_bf16 v[6:9], v[238:241], v[230:233], 0
	v_mfma_f32_16x16x32_bf16 v[2:5], v[246:249], v[230:233], 0
	v_mfma_f32_16x16x32_bf16 v[54:57], v[242:245], v[194:197], v[54:57]
	v_mfma_f32_16x16x32_bf16 v[50:53], v[176:179], v[194:197], v[50:53]
	v_mfma_f32_16x16x32_bf16 v[38:41], v[242:245], v[202:205], v[38:41]
	v_mfma_f32_16x16x32_bf16 v[34:37], v[176:179], v[202:205], v[34:37]
	v_mfma_f32_16x16x32_bf16 v[22:25], v[242:245], v[216:219], v[22:25]
	v_mfma_f32_16x16x32_bf16 v[18:21], v[176:179], v[216:219], v[18:21]
	v_mfma_f32_16x16x32_bf16 v[6:9], v[242:245], v[234:237], v[6:9]
	v_mfma_f32_16x16x32_bf16 v[2:5], v[176:179], v[234:237], v[2:5]
	s_setprio 0
	s_barrier
	s_add_i32 s1, 0, 0x18000
	v_add_u32_e32 v158, s1, v181
	ds_read_b128 v[130:133], v158
	ds_read_b128 v[134:137], v158 offset:1024
	ds_read_b128 v[154:157], v158 offset:2048
	ds_read_b128 v[176:179], v158 offset:3072
	s_add_u32 s22, s42, 0x40000
	s_addc_u32 s23, s43, 0
	s_mov_b32 m0, s51
	v_lshl_add_u64 v[234:235], s[22:23], 0, v[142:143]
	ds_read_b128 v[186:189], v185 offset:32768
	ds_read_b128 v[190:193], v185 offset:33792
	ds_read_b128 v[194:197], v185 offset:34816
	ds_read_b128 v[198:201], v185 offset:35840
	ds_read_b128 v[202:205], v185 offset:36864
	ds_read_b128 v[206:209], v185 offset:37888
	ds_read_b128 v[216:219], v185 offset:38912
	ds_read_b128 v[230:233], v185 offset:39936
	global_load_lds_dwordx4 v[234:235], off
	v_lshl_add_u64 v[234:235], s[22:23], 0, v[140:141]
	s_mov_b32 m0, s52
	s_nop 0
	global_load_lds_dwordx4 v[234:235], off
	s_add_i32 s33, 0, 0x1c000
	v_add_u32_e32 v158, s33, v181
	ds_read_b128 v[234:237], v158
	ds_read_b128 v[238:241], v158 offset:1024
	ds_read_b128 v[242:245], v158 offset:2048
	ds_read_b128 v[246:249], v158 offset:3072
	s_waitcnt vmcnt(8)
	s_waitcnt lgkmcnt(0)
	v_mfma_f32_16x16x32_bf16 v[126:129], v[130:133], v[186:189], v[126:129]
	v_mfma_f32_16x16x32_bf16 v[122:125], v[154:157], v[186:189], v[122:125]
	v_mfma_f32_16x16x32_bf16 v[110:113], v[130:133], v[194:197], v[110:113]
	v_mfma_f32_16x16x32_bf16 v[106:109], v[154:157], v[194:197], v[106:109]
	s_barrier
	s_setprio 1
	v_mfma_f32_16x16x32_bf16 v[94:97], v[130:133], v[202:205], v[94:97]
	v_mfma_f32_16x16x32_bf16 v[90:93], v[154:157], v[202:205], v[90:93]
	v_mfma_f32_16x16x32_bf16 v[78:81], v[130:133], v[216:219], v[78:81]
	v_mfma_f32_16x16x32_bf16 v[74:77], v[154:157], v[216:219], v[74:77]
	v_mfma_f32_16x16x32_bf16 v[126:129], v[134:137], v[190:193], v[126:129]
	v_mfma_f32_16x16x32_bf16 v[122:125], v[176:179], v[190:193], v[122:125]
	v_mfma_f32_16x16x32_bf16 v[110:113], v[134:137], v[198:201], v[110:113]
	v_mfma_f32_16x16x32_bf16 v[106:109], v[176:179], v[198:201], v[106:109]
	v_mfma_f32_16x16x32_bf16 v[94:97], v[134:137], v[206:209], v[94:97]
	v_mfma_f32_16x16x32_bf16 v[90:93], v[176:179], v[206:209], v[90:93]
	v_mfma_f32_16x16x32_bf16 v[78:81], v[134:137], v[230:233], v[78:81]
	v_mfma_f32_16x16x32_bf16 v[74:77], v[176:179], v[230:233], v[74:77]
	v_mfma_f32_16x16x32_bf16 v[118:121], v[234:237], v[186:189], v[118:121]
	v_mfma_f32_16x16x32_bf16 v[114:117], v[242:245], v[186:189], v[114:117]
	v_mfma_f32_16x16x32_bf16 v[102:105], v[234:237], v[194:197], v[102:105]
	v_mfma_f32_16x16x32_bf16 v[98:101], v[242:245], v[194:197], v[98:101]
	v_mfma_f32_16x16x32_bf16 v[86:89], v[234:237], v[202:205], v[86:89]
	v_mfma_f32_16x16x32_bf16 v[82:85], v[242:245], v[202:205], v[82:85]
	v_mfma_f32_16x16x32_bf16 v[70:73], v[234:237], v[216:219], v[70:73]
	v_mfma_f32_16x16x32_bf16 v[66:69], v[242:245], v[216:219], v[66:69]
	v_mfma_f32_16x16x32_bf16 v[118:121], v[238:241], v[190:193], v[118:121]
	v_mfma_f32_16x16x32_bf16 v[114:117], v[246:249], v[190:193], v[114:117]
	v_mfma_f32_16x16x32_bf16 v[102:105], v[238:241], v[198:201], v[102:105]
	v_mfma_f32_16x16x32_bf16 v[98:101], v[246:249], v[198:201], v[98:101]
	v_mfma_f32_16x16x32_bf16 v[86:89], v[238:241], v[206:209], v[86:89]
	v_mfma_f32_16x16x32_bf16 v[82:85], v[246:249], v[206:209], v[82:85]
	v_mfma_f32_16x16x32_bf16 v[70:73], v[238:241], v[230:233], v[70:73]
	v_mfma_f32_16x16x32_bf16 v[66:69], v[246:249], v[230:233], v[66:69]
	s_setprio 0
	s_barrier
	ds_read_b128 v[186:189], v185 offset:49152
	ds_read_b128 v[190:193], v185 offset:50176
	ds_read_b128 v[194:197], v185 offset:51200
	ds_read_b128 v[198:201], v185 offset:52224
	ds_read_b128 v[202:205], v185 offset:53248
	ds_read_b128 v[206:209], v185 offset:54272
	ds_read_b128 v[216:219], v185 offset:55296
	ds_read_b128 v[230:233], v185 offset:56320
	s_add_i32 s1, s1, s48
	v_lshl_add_u64 v[160:161], v[160:161], 0, s[12:13]
	s_mov_b32 m0, s1
	s_nop 0
	global_load_lds_dwordx4 v[160:161], off
	v_lshl_add_u64 v[160:161], v[220:221], 0, s[12:13]
	s_add_i32 m0, s1, 0x2000
	s_nop 0
	global_load_lds_dwordx4 v[160:161], off
	s_mov_b32 m0, s55
	v_lshl_add_u64 v[160:161], v[250:251], 0, s[12:13]
	global_load_lds_dwordx4 v[160:161], off
	v_lshl_add_u64 v[160:161], v[168:169], 0, s[12:13]
	s_mov_b32 m0, s56
	s_nop 0
	global_load_lds_dwordx4 v[160:161], off
	s_add_u32 s22, s30, 0x40080
	s_addc_u32 s23, s31, 0
	s_add_i32 s1, s33, s48
	s_mov_b32 m0, s1
	s_nop 0
	global_load_lds_dwordx4 v0, s[22:23]
	s_add_i32 m0, s1, 0x2000
	s_nop 0
	global_load_lds_dwordx4 v138, s[22:23]
	s_waitcnt vmcnt(8)
	s_waitcnt lgkmcnt(0)
	v_mfma_f32_16x16x32_bf16 v[62:65], v[130:133], v[186:189], v[62:65]
	v_mfma_f32_16x16x32_bf16 v[58:61], v[154:157], v[186:189], v[58:61]
	v_mfma_f32_16x16x32_bf16 v[46:49], v[130:133], v[194:197], v[46:49]
	v_mfma_f32_16x16x32_bf16 v[42:45], v[154:157], v[194:197], v[42:45]
	s_barrier
	s_setprio 1
	v_mfma_f32_16x16x32_bf16 v[30:33], v[130:133], v[202:205], v[30:33]
	v_mfma_f32_16x16x32_bf16 v[26:29], v[154:157], v[202:205], v[26:29]
	v_mfma_f32_16x16x32_bf16 v[14:17], v[130:133], v[216:219], v[14:17]
	v_mfma_f32_16x16x32_bf16 v[10:13], v[154:157], v[216:219], v[10:13]
	v_mfma_f32_16x16x32_bf16 v[62:65], v[134:137], v[190:193], v[62:65]
	v_mfma_f32_16x16x32_bf16 v[58:61], v[176:179], v[190:193], v[58:61]
	v_mfma_f32_16x16x32_bf16 v[46:49], v[134:137], v[198:201], v[46:49]
	v_mfma_f32_16x16x32_bf16 v[42:45], v[176:179], v[198:201], v[42:45]
	v_mfma_f32_16x16x32_bf16 v[30:33], v[134:137], v[206:209], v[30:33]
	v_mfma_f32_16x16x32_bf16 v[26:29], v[176:179], v[206:209], v[26:29]
	v_mfma_f32_16x16x32_bf16 v[14:17], v[134:137], v[230:233], v[14:17]
	v_mfma_f32_16x16x32_bf16 v[10:13], v[176:179], v[230:233], v[10:13]
	v_mfma_f32_16x16x32_bf16 v[54:57], v[234:237], v[186:189], v[54:57]
	v_mfma_f32_16x16x32_bf16 v[50:53], v[242:245], v[186:189], v[50:53]
	v_mfma_f32_16x16x32_bf16 v[38:41], v[234:237], v[194:197], v[38:41]
	v_mfma_f32_16x16x32_bf16 v[34:37], v[242:245], v[194:197], v[34:37]
	v_mfma_f32_16x16x32_bf16 v[22:25], v[234:237], v[202:205], v[22:25]
	v_mfma_f32_16x16x32_bf16 v[18:21], v[242:245], v[202:205], v[18:21]
	v_mfma_f32_16x16x32_bf16 v[6:9], v[234:237], v[216:219], v[6:9]
	v_mfma_f32_16x16x32_bf16 v[2:5], v[242:245], v[216:219], v[2:5]
	v_mfma_f32_16x16x32_bf16 v[54:57], v[238:241], v[190:193], v[54:57]
	v_mfma_f32_16x16x32_bf16 v[50:53], v[246:249], v[190:193], v[50:53]
	v_mfma_f32_16x16x32_bf16 v[38:41], v[238:241], v[198:201], v[38:41]
	v_mfma_f32_16x16x32_bf16 v[34:37], v[246:249], v[198:201], v[34:37]
	v_mfma_f32_16x16x32_bf16 v[22:25], v[238:241], v[206:209], v[22:25]
	v_mfma_f32_16x16x32_bf16 v[18:21], v[246:249], v[206:209], v[18:21]
	v_mfma_f32_16x16x32_bf16 v[6:9], v[238:241], v[230:233], v[6:9]
	v_mfma_f32_16x16x32_bf16 v[2:5], v[246:249], v[230:233], v[2:5]
	s_setprio 0
	s_add_i32 s44, s44, 2
	s_add_u32 s28, s28, 0x100
	s_addc_u32 s29, s29, 0
	s_add_u32 s25, s25, 0x100
	s_addc_u32 s34, s34, 0
	s_cmp_gt_u32 s44, 13
	s_barrier
.LBB0_362:
	s_add_u32 s1, s28, 0xfffc0080
	s_addc_u32 s22, s29, -1
	s_add_i32 s23, 0, 0x10000
	v_add_u32_e32 v158, s23, v181
	ds_read_b128 v[130:133], v158
	ds_read_b128 v[134:137], v158 offset:1024
	ds_read_b128 v[154:157], v158 offset:2048
	ds_read_b128 v[186:189], v158 offset:3072
	s_cmp_eq_u32 s44, 12
	s_cselect_b32 s43, s17, s22
	s_cselect_b32 s42, s20, s1
	s_cselect_b32 s31, s9, s34
	s_cselect_b32 s30, s21, s25
	v_lshl_add_u64 v[160:161], s[28:29], 0, v[150:151]
	s_add_i32 m0, s49, 0xc000
	ds_read_b128 v[190:193], v185
	ds_read_b128 v[194:197], v185 offset:1024
	ds_read_b128 v[198:201], v185 offset:2048
	ds_read_b128 v[202:205], v185 offset:3072
	ds_read_b128 v[206:209], v185 offset:4096
	ds_read_b128 v[216:219], v185 offset:5120
	ds_read_b128 v[230:233], v185 offset:6144
	ds_read_b128 v[234:237], v185 offset:7168
	global_load_lds_dwordx4 v[160:161], off
	v_lshl_add_u64 v[160:161], s[28:29], 0, v[152:153]
	s_add_i32 m0, s49, 0xe000
	s_nop 0
	global_load_lds_dwordx4 v[160:161], off
	s_add_i32 s1, 0, 0x14000
	v_add_u32_e32 v158, s1, v181
	ds_read_b128 v[238:241], v158
	ds_read_b128 v[242:245], v158 offset:1024
	ds_read_b128 v[246:249], v158 offset:2048
	ds_read_b128 v[176:179], v158 offset:3072
	s_waitcnt vmcnt(8)
	s_waitcnt lgkmcnt(0)
	v_mfma_f32_16x16x32_bf16 v[126:129], v[130:133], v[190:193], v[126:129]
	v_mfma_f32_16x16x32_bf16 v[122:125], v[154:157], v[190:193], v[122:125]
	v_mfma_f32_16x16x32_bf16 v[110:113], v[130:133], v[198:201], v[110:113]
	v_mfma_f32_16x16x32_bf16 v[106:109], v[154:157], v[198:201], v[106:109]
	s_barrier
	s_setprio 1
	v_mfma_f32_16x16x32_bf16 v[94:97], v[130:133], v[206:209], v[94:97]
	v_mfma_f32_16x16x32_bf16 v[90:93], v[154:157], v[206:209], v[90:93]
	v_mfma_f32_16x16x32_bf16 v[78:81], v[130:133], v[230:233], v[78:81]
	v_mfma_f32_16x16x32_bf16 v[74:77], v[154:157], v[230:233], v[74:77]
	v_mfma_f32_16x16x32_bf16 v[126:129], v[134:137], v[194:197], v[126:129]
	v_mfma_f32_16x16x32_bf16 v[122:125], v[186:189], v[194:197], v[122:125]
	v_mfma_f32_16x16x32_bf16 v[110:113], v[134:137], v[202:205], v[110:113]
	v_mfma_f32_16x16x32_bf16 v[106:109], v[186:189], v[202:205], v[106:109]
	v_mfma_f32_16x16x32_bf16 v[94:97], v[134:137], v[216:219], v[94:97]
	v_mfma_f32_16x16x32_bf16 v[90:93], v[186:189], v[216:219], v[90:93]
	v_mfma_f32_16x16x32_bf16 v[78:81], v[134:137], v[234:237], v[78:81]
	v_mfma_f32_16x16x32_bf16 v[74:77], v[186:189], v[234:237], v[74:77]
	v_mfma_f32_16x16x32_bf16 v[118:121], v[238:241], v[190:193], v[118:121]
	v_mfma_f32_16x16x32_bf16 v[114:117], v[246:249], v[190:193], v[114:117]
	v_mfma_f32_16x16x32_bf16 v[102:105], v[238:241], v[198:201], v[102:105]
	v_mfma_f32_16x16x32_bf16 v[98:101], v[246:249], v[198:201], v[98:101]
	v_mfma_f32_16x16x32_bf16 v[86:89], v[238:241], v[206:209], v[86:89]
	v_mfma_f32_16x16x32_bf16 v[82:85], v[246:249], v[206:209], v[82:85]
	v_mfma_f32_16x16x32_bf16 v[70:73], v[238:241], v[230:233], v[70:73]
	v_mfma_f32_16x16x32_bf16 v[66:69], v[246:249], v[230:233], v[66:69]
	v_mfma_f32_16x16x32_bf16 v[118:121], v[242:245], v[194:197], v[118:121]
	v_mfma_f32_16x16x32_bf16 v[114:117], v[176:179], v[194:197], v[114:117]
	v_mfma_f32_16x16x32_bf16 v[102:105], v[242:245], v[202:205], v[102:105]
	v_mfma_f32_16x16x32_bf16 v[98:101], v[176:179], v[202:205], v[98:101]
	v_mfma_f32_16x16x32_bf16 v[86:89], v[242:245], v[216:219], v[86:89]
	v_mfma_f32_16x16x32_bf16 v[82:85], v[176:179], v[216:219], v[82:85]
	v_mfma_f32_16x16x32_bf16 v[70:73], v[242:245], v[234:237], v[70:73]
	v_mfma_f32_16x16x32_bf16 v[66:69], v[176:179], v[234:237], v[66:69]
	s_setprio 0
	s_barrier
	ds_read_b128 v[190:193], v185 offset:16384
	ds_read_b128 v[194:197], v185 offset:17408
	ds_read_b128 v[198:201], v185 offset:18432
	ds_read_b128 v[202:205], v185 offset:19456
	ds_read_b128 v[206:209], v185 offset:20480
	ds_read_b128 v[216:219], v185 offset:21504
	ds_read_b128 v[230:233], v185 offset:22528
	ds_read_b128 v[234:237], v185 offset:23552
	s_add_i32 s22, s23, s48
	v_lshl_add_u64 v[160:161], s[30:31], 0, v[0:1]
	s_mov_b32 m0, s22
	s_nop 0
	global_load_lds_dwordx4 v[160:161], off
	v_lshl_add_u64 v[220:221], s[30:31], 0, v[138:139]
	s_add_i32 m0, s22, 0x2000
	s_nop 0
	global_load_lds_dwordx4 v[220:221], off
	s_mov_b32 m0, s49
	v_lshl_add_u64 v[250:251], s[42:43], 0, v[142:143]
	global_load_lds_dwordx4 v[250:251], off
	v_lshl_add_u64 v[168:169], s[42:43], 0, v[140:141]
	s_mov_b32 m0, s50
	s_nop 0
	global_load_lds_dwordx4 v[168:169], off
	s_add_u32 s22, s30, 0x40000
	s_addc_u32 s23, s31, 0
	s_add_i32 s1, s1, s48
	s_mov_b32 m0, s1
	s_nop 0
	global_load_lds_dwordx4 v0, s[22:23]
	s_add_i32 m0, s1, 0x2000
	s_nop 0
	global_load_lds_dwordx4 v138, s[22:23]
	s_waitcnt vmcnt(8)
	s_waitcnt lgkmcnt(0)
	v_mfma_f32_16x16x32_bf16 v[62:65], v[130:133], v[190:193], v[62:65]
	v_mfma_f32_16x16x32_bf16 v[58:61], v[154:157], v[190:193], v[58:61]
	v_mfma_f32_16x16x32_bf16 v[46:49], v[130:133], v[198:201], v[46:49]
	v_mfma_f32_16x16x32_bf16 v[42:45], v[154:157], v[198:201], v[42:45]
	s_barrier
	s_setprio 1
	v_mfma_f32_16x16x32_bf16 v[30:33], v[130:133], v[206:209], v[30:33]
	v_mfma_f32_16x16x32_bf16 v[26:29], v[154:157], v[206:209], v[26:29]
	v_mfma_f32_16x16x32_bf16 v[14:17], v[130:133], v[230:233], v[14:17]
	v_mfma_f32_16x16x32_bf16 v[10:13], v[154:157], v[230:233], v[10:13]
	v_mfma_f32_16x16x32_bf16 v[62:65], v[134:137], v[194:197], v[62:65]
	v_mfma_f32_16x16x32_bf16 v[58:61], v[186:189], v[194:197], v[58:61]
	v_mfma_f32_16x16x32_bf16 v[46:49], v[134:137], v[202:205], v[46:49]
	v_mfma_f32_16x16x32_bf16 v[42:45], v[186:189], v[202:205], v[42:45]
	v_mfma_f32_16x16x32_bf16 v[30:33], v[134:137], v[216:219], v[30:33]
	v_mfma_f32_16x16x32_bf16 v[26:29], v[186:189], v[216:219], v[26:29]
	v_mfma_f32_16x16x32_bf16 v[14:17], v[134:137], v[234:237], v[14:17]
	v_mfma_f32_16x16x32_bf16 v[10:13], v[186:189], v[234:237], v[10:13]
	v_mfma_f32_16x16x32_bf16 v[54:57], v[238:241], v[190:193], v[54:57]
	v_mfma_f32_16x16x32_bf16 v[50:53], v[246:249], v[190:193], v[50:53]
	v_mfma_f32_16x16x32_bf16 v[38:41], v[238:241], v[198:201], v[38:41]
	v_mfma_f32_16x16x32_bf16 v[34:37], v[246:249], v[198:201], v[34:37]
	v_mfma_f32_16x16x32_bf16 v[22:25], v[238:241], v[206:209], v[22:25]
	v_mfma_f32_16x16x32_bf16 v[18:21], v[246:249], v[206:209], v[18:21]
	v_mfma_f32_16x16x32_bf16 v[6:9], v[238:241], v[230:233], v[6:9]
	v_mfma_f32_16x16x32_bf16 v[2:5], v[246:249], v[230:233], v[2:5]
	v_mfma_f32_16x16x32_bf16 v[54:57], v[242:245], v[194:197], v[54:57]
	v_mfma_f32_16x16x32_bf16 v[50:53], v[176:179], v[194:197], v[50:53]
	v_mfma_f32_16x16x32_bf16 v[38:41], v[242:245], v[202:205], v[38:41]
	v_mfma_f32_16x16x32_bf16 v[34:37], v[176:179], v[202:205], v[34:37]
	v_mfma_f32_16x16x32_bf16 v[22:25], v[242:245], v[216:219], v[22:25]
	v_mfma_f32_16x16x32_bf16 v[18:21], v[176:179], v[216:219], v[18:21]
	v_mfma_f32_16x16x32_bf16 v[6:9], v[242:245], v[234:237], v[6:9]
	v_mfma_f32_16x16x32_bf16 v[2:5], v[176:179], v[234:237], v[2:5]
	s_setprio 0
	s_barrier
	s_add_i32 s1, 0, 0x18000
	v_add_u32_e32 v158, s1, v181
	ds_read_b128 v[130:133], v158
	ds_read_b128 v[134:137], v158 offset:1024
	ds_read_b128 v[154:157], v158 offset:2048
	ds_read_b128 v[176:179], v158 offset:3072
	s_add_u32 s22, s42, 0x40000
	s_addc_u32 s23, s43, 0
	s_mov_b32 m0, s51
	v_lshl_add_u64 v[234:235], s[22:23], 0, v[142:143]
	ds_read_b128 v[186:189], v185 offset:32768
	ds_read_b128 v[190:193], v185 offset:33792
	ds_read_b128 v[194:197], v185 offset:34816
	ds_read_b128 v[198:201], v185 offset:35840
	ds_read_b128 v[202:205], v185 offset:36864
	ds_read_b128 v[206:209], v185 offset:37888
	ds_read_b128 v[216:219], v185 offset:38912
	ds_read_b128 v[230:233], v185 offset:39936
	global_load_lds_dwordx4 v[234:235], off
	v_lshl_add_u64 v[234:235], s[22:23], 0, v[140:141]
	s_mov_b32 m0, s52
	s_nop 0
	global_load_lds_dwordx4 v[234:235], off
	s_add_i32 s33, 0, 0x1c000
	v_add_u32_e32 v158, s33, v181
	ds_read_b128 v[234:237], v158
	ds_read_b128 v[238:241], v158 offset:1024
	ds_read_b128 v[242:245], v158 offset:2048
	ds_read_b128 v[246:249], v158 offset:3072
	s_waitcnt vmcnt(8)
	s_waitcnt lgkmcnt(0)
	v_mfma_f32_16x16x32_bf16 v[126:129], v[130:133], v[186:189], v[126:129]
	v_mfma_f32_16x16x32_bf16 v[122:125], v[154:157], v[186:189], v[122:125]
	v_mfma_f32_16x16x32_bf16 v[110:113], v[130:133], v[194:197], v[110:113]
	v_mfma_f32_16x16x32_bf16 v[106:109], v[154:157], v[194:197], v[106:109]
	s_barrier
	s_setprio 1
	v_mfma_f32_16x16x32_bf16 v[94:97], v[130:133], v[202:205], v[94:97]
	v_mfma_f32_16x16x32_bf16 v[90:93], v[154:157], v[202:205], v[90:93]
	v_mfma_f32_16x16x32_bf16 v[78:81], v[130:133], v[216:219], v[78:81]
	v_mfma_f32_16x16x32_bf16 v[74:77], v[154:157], v[216:219], v[74:77]
	v_mfma_f32_16x16x32_bf16 v[126:129], v[134:137], v[190:193], v[126:129]
	v_mfma_f32_16x16x32_bf16 v[122:125], v[176:179], v[190:193], v[122:125]
	v_mfma_f32_16x16x32_bf16 v[110:113], v[134:137], v[198:201], v[110:113]
	v_mfma_f32_16x16x32_bf16 v[106:109], v[176:179], v[198:201], v[106:109]
	v_mfma_f32_16x16x32_bf16 v[94:97], v[134:137], v[206:209], v[94:97]
	v_mfma_f32_16x16x32_bf16 v[90:93], v[176:179], v[206:209], v[90:93]
	v_mfma_f32_16x16x32_bf16 v[78:81], v[134:137], v[230:233], v[78:81]
	v_mfma_f32_16x16x32_bf16 v[74:77], v[176:179], v[230:233], v[74:77]
	v_mfma_f32_16x16x32_bf16 v[118:121], v[234:237], v[186:189], v[118:121]
	v_mfma_f32_16x16x32_bf16 v[114:117], v[242:245], v[186:189], v[114:117]
	v_mfma_f32_16x16x32_bf16 v[102:105], v[234:237], v[194:197], v[102:105]
	v_mfma_f32_16x16x32_bf16 v[98:101], v[242:245], v[194:197], v[98:101]
	v_mfma_f32_16x16x32_bf16 v[86:89], v[234:237], v[202:205], v[86:89]
	v_mfma_f32_16x16x32_bf16 v[82:85], v[242:245], v[202:205], v[82:85]
	v_mfma_f32_16x16x32_bf16 v[70:73], v[234:237], v[216:219], v[70:73]
	v_mfma_f32_16x16x32_bf16 v[66:69], v[242:245], v[216:219], v[66:69]
	v_mfma_f32_16x16x32_bf16 v[118:121], v[238:241], v[190:193], v[118:121]
	v_mfma_f32_16x16x32_bf16 v[114:117], v[246:249], v[190:193], v[114:117]
	v_mfma_f32_16x16x32_bf16 v[102:105], v[238:241], v[198:201], v[102:105]
	v_mfma_f32_16x16x32_bf16 v[98:101], v[246:249], v[198:201], v[98:101]
	v_mfma_f32_16x16x32_bf16 v[86:89], v[238:241], v[206:209], v[86:89]
	v_mfma_f32_16x16x32_bf16 v[82:85], v[246:249], v[206:209], v[82:85]
	v_mfma_f32_16x16x32_bf16 v[70:73], v[238:241], v[230:233], v[70:73]
	v_mfma_f32_16x16x32_bf16 v[66:69], v[246:249], v[230:233], v[66:69]
	s_setprio 0
	s_barrier
	ds_read_b128 v[186:189], v185 offset:49152
	ds_read_b128 v[190:193], v185 offset:50176
	ds_read_b128 v[194:197], v185 offset:51200
	ds_read_b128 v[198:201], v185 offset:52224
	ds_read_b128 v[202:205], v185 offset:53248
	ds_read_b128 v[206:209], v185 offset:54272
	ds_read_b128 v[216:219], v185 offset:55296
	ds_read_b128 v[230:233], v185 offset:56320
	s_add_i32 s1, s1, s48
	v_lshl_add_u64 v[160:161], v[160:161], 0, s[12:13]
	s_mov_b32 m0, s1
	s_nop 0
	global_load_lds_dwordx4 v[160:161], off
	v_lshl_add_u64 v[160:161], v[220:221], 0, s[12:13]
	s_add_i32 m0, s1, 0x2000
	s_nop 0
	global_load_lds_dwordx4 v[160:161], off
	s_mov_b32 m0, s55
	v_lshl_add_u64 v[160:161], v[250:251], 0, s[12:13]
	global_load_lds_dwordx4 v[160:161], off
	v_lshl_add_u64 v[160:161], v[168:169], 0, s[12:13]
	s_mov_b32 m0, s56
	s_nop 0
	global_load_lds_dwordx4 v[160:161], off
	s_add_u32 s22, s30, 0x40080
	s_addc_u32 s23, s31, 0
	s_add_i32 s1, s33, s48
	s_mov_b32 m0, s1
	s_nop 0
	global_load_lds_dwordx4 v0, s[22:23]
	s_add_i32 m0, s1, 0x2000
	s_nop 0
	global_load_lds_dwordx4 v138, s[22:23]
	s_waitcnt vmcnt(8)
	s_waitcnt lgkmcnt(0)
	v_mfma_f32_16x16x32_bf16 v[62:65], v[130:133], v[186:189], v[62:65]
	v_mfma_f32_16x16x32_bf16 v[58:61], v[154:157], v[186:189], v[58:61]
	v_mfma_f32_16x16x32_bf16 v[46:49], v[130:133], v[194:197], v[46:49]
	v_mfma_f32_16x16x32_bf16 v[42:45], v[154:157], v[194:197], v[42:45]
	s_barrier
	s_setprio 1
	v_mfma_f32_16x16x32_bf16 v[30:33], v[130:133], v[202:205], v[30:33]
	v_mfma_f32_16x16x32_bf16 v[26:29], v[154:157], v[202:205], v[26:29]
	v_mfma_f32_16x16x32_bf16 v[14:17], v[130:133], v[216:219], v[14:17]
	v_mfma_f32_16x16x32_bf16 v[10:13], v[154:157], v[216:219], v[10:13]
	v_mfma_f32_16x16x32_bf16 v[62:65], v[134:137], v[190:193], v[62:65]
	v_mfma_f32_16x16x32_bf16 v[58:61], v[176:179], v[190:193], v[58:61]
	v_mfma_f32_16x16x32_bf16 v[46:49], v[134:137], v[198:201], v[46:49]
	v_mfma_f32_16x16x32_bf16 v[42:45], v[176:179], v[198:201], v[42:45]
	v_mfma_f32_16x16x32_bf16 v[30:33], v[134:137], v[206:209], v[30:33]
	v_mfma_f32_16x16x32_bf16 v[26:29], v[176:179], v[206:209], v[26:29]
	v_mfma_f32_16x16x32_bf16 v[14:17], v[134:137], v[230:233], v[14:17]
	v_mfma_f32_16x16x32_bf16 v[10:13], v[176:179], v[230:233], v[10:13]
	v_mfma_f32_16x16x32_bf16 v[54:57], v[234:237], v[186:189], v[54:57]
	v_mfma_f32_16x16x32_bf16 v[50:53], v[242:245], v[186:189], v[50:53]
	v_mfma_f32_16x16x32_bf16 v[38:41], v[234:237], v[194:197], v[38:41]
	v_mfma_f32_16x16x32_bf16 v[34:37], v[242:245], v[194:197], v[34:37]
	v_mfma_f32_16x16x32_bf16 v[22:25], v[234:237], v[202:205], v[22:25]
	v_mfma_f32_16x16x32_bf16 v[18:21], v[242:245], v[202:205], v[18:21]
	v_mfma_f32_16x16x32_bf16 v[6:9], v[234:237], v[216:219], v[6:9]
	v_mfma_f32_16x16x32_bf16 v[2:5], v[242:245], v[216:219], v[2:5]
	v_mfma_f32_16x16x32_bf16 v[54:57], v[238:241], v[190:193], v[54:57]
	v_mfma_f32_16x16x32_bf16 v[50:53], v[246:249], v[190:193], v[50:53]
	v_mfma_f32_16x16x32_bf16 v[38:41], v[238:241], v[198:201], v[38:41]
	v_mfma_f32_16x16x32_bf16 v[34:37], v[246:249], v[198:201], v[34:37]
	v_mfma_f32_16x16x32_bf16 v[22:25], v[238:241], v[206:209], v[22:25]
	v_mfma_f32_16x16x32_bf16 v[18:21], v[246:249], v[206:209], v[18:21]
	v_mfma_f32_16x16x32_bf16 v[6:9], v[238:241], v[230:233], v[6:9]
	v_mfma_f32_16x16x32_bf16 v[2:5], v[246:249], v[230:233], v[2:5]
	s_setprio 0
	s_add_i32 s44, s44, 2
	s_add_u32 s28, s28, 0x100
	s_addc_u32 s29, s29, 0
	s_add_u32 s25, s25, 0x100
	s_addc_u32 s34, s34, 0
	s_cmp_gt_u32 s44, 13
	s_barrier
	s_cbranch_scc0 .LBB0_362
	s_cmpk_gt_u32 s4, 0xff
	s_cbranch_scc1 .Lrs_proj1_post
	s_barrier
